# DMA issue via offset immediates; hyena conv8 pre-loop software-pipelined loads; counted vmcnt at primed GEMM tile start
# speedup vs baseline: 1.2135x; 1.0204x over previous
; template <class AL, class BL>
; DEV void gemm_mainloop_p(Acc& acc, const AL& al, const BL& bl, int m0, int n0, int m0n, int n0n, int K, char* lds,
;                          GemmPipe& gp) {
;     ...
;   if (!gp.primed) {
;     gp.ra = al.load(tid, m0, 0);
;     gp.rb = bl.load(tid, n0, 0);
;     __syncthreads();
;     al.store(tid, lds, gp.ra);
;     bl.store(tid, lds + TILE_BYTES, gp.rb);
;     gp.ra = al.load(tid, m0, BK);
;     gp.rb = bl.load(tid, n0, BK);
;     __syncthreads();
; DEV void phase_p1(const Params& p, int g, char* smem) {
;     ...
;     for (int iter = 0;; ++iter) {
;       int mt, nt, mtn, ntn;
;       if (!tile_map(iter, 128, 18, mt, nt)) break;
;       const bool more = tile_map(iter + 1, 128, 18, mtn, ntn);
;       if (!more) { mtn = mt; ntn = nt; }
;       Acc acc;
;       acc_zero(acc);
;       const int m0 = mt * 256, n0 = nt * 256;
;       RowLoader al{H, 1024}, bl{WinT + (size_t)1536 * 1024, 1024};
;       gemm_mainloop_p(acc, al, bl, m0, n0, mtn * 256, ntn * 256, 1024, smem, gp);
.LBB0_278:
	s_and_b64 vcc, exec, s[2:3]
	s_lshl_b32 s5, s7, 8
	s_lshl_b32 s4, s8, 8
	v_lshrrev_b32_e32 v149, 6, v202
	v_and_b32_e32 v148, 63, v202
	s_nop 0
	v_readfirstlane_b32 s13, v149
	v_lshrrev_b32_e32 v150, 3, v148
	v_lshl_add_u32 v150, v149, 5, v150
	v_and_b32_e32 v151, 7, v148
	v_lshrrev_b32_e32 v128, 4, v148
	v_xor_b32_e32 v151, v128, v151
	v_lshlrev_b32_e32 v151, 4, v151
	s_lshl_b32 s13, s13, 12
	v_add_u32_e32 v128, s5, v150
	v_lshlrev_b32_e32 v128, 11, v128
	v_add_u32_e32 v128, v128, v151
	v_add_u32_e32 v129, 0x3c00, v128
	v_add_u32_e32 v130, 0x7800, v128
	v_add_u32_e32 v131, 0xb400, v128
	v_xor_b32_e32 v129, 0x40, v129
	v_xor_b32_e32 v131, 0x40, v131
	v_add_u32_e32 v132, s4, v150
	v_lshlrev_b32_e32 v132, 11, v132
	v_add_u32_e32 v132, v132, v151
	v_add_u32_e32 v133, 0x3c00, v132
	v_add_u32_e32 v134, 0x7800, v132
	v_add_u32_e32 v135, 0xb400, v132
	v_xor_b32_e32 v133, 0x40, v133
	v_xor_b32_e32 v135, 0x40, v135
	v_add_u32_e32 v136, 0x40000, v128
	v_add_u32_e32 v137, 0x40000, v129
	v_add_u32_e32 v138, 0x40000, v130
	v_add_u32_e32 v139, 0x40000, v131
	v_add_u32_e32 v140, 0x40000, v132
	v_add_u32_e32 v141, 0x40000, v133
	v_add_u32_e32 v142, 0x40000, v134
	v_add_u32_e32 v143, 0x40000, v135
	v_lshrrev_b32_e32 v161, 6, v202
	v_and_b32_e32 v160, 63, v202
	v_bfe_u32 v242, v160, 1, 3
	v_lshrrev_b32_e32 v243, 4, v160
	v_xor_b32_e32 v242, v242, v243
	v_lshlrev_b32_e32 v242, 4, v242
	v_and_b32_e32 v243, 15, v160
	v_lshlrev_b32_e32 v243, 7, v243
	v_lshrrev_b32_e32 v144, 2, v161
	v_lshl_add_u32 v144, v144, 14, v243
	v_and_b32_e32 v146, 3, v161
	v_lshl_add_u32 v146, v146, 13, v243
	v_add_u32_e32 v146, 0x10000, v146
	v_xor_b32_e32 v145, 0x40, v242
	v_add_u32_e32 v145, v144, v145
	v_add_u32_e32 v144, v144, v242
	v_xor_b32_e32 v147, 0x40, v242
	v_add_u32_e32 v147, v146, v147
	v_add_u32_e32 v146, v146, v242
	s_mov_b64 s[14:15], s[64:65]
	s_mov_b64 s[16:17], s[24:25]
	s_cbranch_vccnz .Lp1a_primed
	s_cmp_lt_u32 s13, 0x4000
	s_cbranch_scc0 .Lp1a_d1
	s_add_u32 m0, s13, 0x0
	s_nop 0
	global_load_lds_dwordx4 v128, s[14:15]
	global_load_lds_dwordx4 v129, s[14:15] offset:1024
	global_load_lds_dwordx4 v130, s[14:15] offset:2048
	global_load_lds_dwordx4 v131, s[14:15] offset:3072
	s_add_u32 m0, s13, 0x10000
	s_nop 0
	global_load_lds_dwordx4 v132, s[16:17]
	global_load_lds_dwordx4 v133, s[16:17] offset:1024
	global_load_lds_dwordx4 v134, s[16:17] offset:2048
	global_load_lds_dwordx4 v135, s[16:17] offset:3072
	s_add_u32 m0, s13, 0x4000
	s_nop 0
	global_load_lds_dwordx4 v136, s[14:15]
	global_load_lds_dwordx4 v137, s[14:15] offset:1024
	global_load_lds_dwordx4 v138, s[14:15] offset:2048
	global_load_lds_dwordx4 v139, s[14:15] offset:3072
	s_add_u32 m0, s13, 0x14000
	s_nop 0
	global_load_lds_dwordx4 v140, s[16:17]
	global_load_lds_dwordx4 v141, s[16:17] offset:1024
	global_load_lds_dwordx4 v142, s[16:17] offset:2048
	global_load_lds_dwordx4 v143, s[16:17] offset:3072

; template <class AL, class BL>
; DEV void gemm_mainloop_p(Acc& acc, const AL& al, const BL& bl, int m0, int n0, int m0n, int n0n, int K, char* lds,
;                          GemmPipe& gp) {
;     ...
;   for (int kt = 0; kt < nk; ++kt) {
;     const char* cur = lds + (kt & 1) * 2 * TILE_BYTES;
;     char* nxt = lds + ((kt + 1) & 1) * 2 * TILE_BYTES;
;     const bool wrap = (kt + 2 >= nk);
;     const int kk = (wrap ? kt + 2 - nk : kt + 2) * BK;
;     const int mr = wrap ? m0n : m0, nr = wrap ? n0n : n0;
;     __builtin_amdgcn_sched_barrier(0);
;     gemm_ktile(acc, cur, cur + TILE_BYTES, wm, wn, lr, lh, al, bl, tid, mr, nr, kk, nxt, gp.ra, gp.rb);
; DEV void acc_zero(Acc& acc) {
; #pragma unroll
;   for (int i = 0; i < 4; ++i)
; #pragma unroll
;     for (int j = 0; j < 2; ++j)
; #pragma unroll
;       for (int r = 0; r < 16; ++r) acc[i][j][r] = 0.f;
; }
.Lp1a_primed:
	s_add_u32 s14, s14, 0x80
	s_addc_u32 s15, s15, 0
	s_add_u32 s16, s16, 0x80
	s_addc_u32 s17, s17, 0
	v_mov_b32_e32 v0, 0
	v_mov_b32_e32 v1, 0
	v_mov_b64_e32 v[2:3], v[0:1]
	v_mov_b64_e32 v[4:5], v[0:1]
	v_mov_b64_e32 v[6:7], v[0:1]
	v_mov_b64_e32 v[8:9], v[0:1]
	v_mov_b64_e32 v[10:11], v[0:1]
	v_mov_b64_e32 v[12:13], v[0:1]
	v_mov_b64_e32 v[14:15], v[0:1]
	v_mov_b64_e32 v[16:17], v[0:1]
	v_mov_b64_e32 v[18:19], v[0:1]
	v_mov_b64_e32 v[20:21], v[0:1]
	v_mov_b64_e32 v[22:23], v[0:1]
	v_mov_b64_e32 v[24:25], v[0:1]
	v_mov_b64_e32 v[26:27], v[0:1]
	v_mov_b64_e32 v[28:29], v[0:1]
	v_mov_b64_e32 v[30:31], v[0:1]
	v_mov_b64_e32 v[32:33], v[0:1]
	v_mov_b64_e32 v[34:35], v[0:1]
	v_mov_b64_e32 v[36:37], v[0:1]
	v_mov_b64_e32 v[38:39], v[0:1]
	v_mov_b64_e32 v[40:41], v[0:1]
	v_mov_b64_e32 v[42:43], v[0:1]
	v_mov_b64_e32 v[44:45], v[0:1]
	v_mov_b64_e32 v[46:47], v[0:1]
	v_mov_b64_e32 v[48:49], v[0:1]
	v_mov_b64_e32 v[50:51], v[0:1]
	v_mov_b64_e32 v[52:53], v[0:1]
	v_mov_b64_e32 v[54:55], v[0:1]
	v_mov_b64_e32 v[56:57], v[0:1]
	v_mov_b64_e32 v[58:59], v[0:1]
	v_mov_b64_e32 v[60:61], v[0:1]
	v_mov_b64_e32 v[62:63], v[0:1]
	v_mov_b64_e32 v[64:65], v[0:1]
	v_mov_b64_e32 v[66:67], v[0:1]
	v_mov_b64_e32 v[68:69], v[0:1]
	v_mov_b64_e32 v[70:71], v[0:1]
	v_mov_b64_e32 v[72:73], v[0:1]
	v_mov_b64_e32 v[74:75], v[0:1]
	v_mov_b64_e32 v[76:77], v[0:1]
	v_mov_b64_e32 v[78:79], v[0:1]
	v_mov_b64_e32 v[80:81], v[0:1]
	v_mov_b64_e32 v[82:83], v[0:1]
	v_mov_b64_e32 v[84:85], v[0:1]
	v_mov_b64_e32 v[86:87], v[0:1]
	v_mov_b64_e32 v[88:89], v[0:1]
	v_mov_b64_e32 v[90:91], v[0:1]
	v_mov_b64_e32 v[92:93], v[0:1]
	v_mov_b64_e32 v[94:95], v[0:1]
	v_mov_b64_e32 v[96:97], v[0:1]
	v_mov_b64_e32 v[98:99], v[0:1]
	v_mov_b64_e32 v[100:101], v[0:1]
	v_mov_b64_e32 v[102:103], v[0:1]
	v_mov_b64_e32 v[104:105], v[0:1]
	v_mov_b64_e32 v[106:107], v[0:1]
	v_mov_b64_e32 v[108:109], v[0:1]
	v_mov_b64_e32 v[110:111], v[0:1]
	v_mov_b64_e32 v[112:113], v[0:1]
	v_mov_b64_e32 v[114:115], v[0:1]
	v_mov_b64_e32 v[116:117], v[0:1]
	v_mov_b64_e32 v[118:119], v[0:1]
	v_mov_b64_e32 v[120:121], v[0:1]
	v_mov_b64_e32 v[122:123], v[0:1]
	v_mov_b64_e32 v[124:125], v[0:1]
	v_mov_b64_e32 v[126:127], v[0:1]
	s_mov_b32 s18, 0
	s_waitcnt vmcnt(16)
	s_barrier
.Lp1a_kloop:
	s_cmp_lt_u32 s13, 0x4000
	s_cbranch_scc0 .Lp1a_d2
	s_add_u32 m0, s13, 0x8000
	s_nop 0
	global_load_lds_dwordx4 v128, s[14:15]
	global_load_lds_dwordx4 v129, s[14:15] offset:1024
	global_load_lds_dwordx4 v130, s[14:15] offset:2048
	global_load_lds_dwordx4 v131, s[14:15] offset:3072
	s_add_u32 m0, s13, 0x18000
	s_nop 0
	global_load_lds_dwordx4 v132, s[16:17]
	global_load_lds_dwordx4 v133, s[16:17] offset:1024
	global_load_lds_dwordx4 v134, s[16:17] offset:2048
	global_load_lds_dwordx4 v135, s[16:17] offset:3072
	s_add_u32 m0, s13, 0xc000
	s_nop 0
	global_load_lds_dwordx4 v136, s[14:15]
	global_load_lds_dwordx4 v137, s[14:15] offset:1024
	global_load_lds_dwordx4 v138, s[14:15] offset:2048
	global_load_lds_dwordx4 v139, s[14:15] offset:3072
	s_add_u32 m0, s13, 0x1c000
	s_nop 0
	global_load_lds_dwordx4 v140, s[16:17]
	global_load_lds_dwordx4 v141, s[16:17] offset:1024
	global_load_lds_dwordx4 v142, s[16:17] offset:2048
	global_load_lds_dwordx4 v143, s[16:17] offset:3072
; template <class AL, class BL>
; DEV void gemm_ktile(Acc& acc, const char* A, const char* B, int wm, int wn, int lr, int lh, const AL& al, const BL& bl,
;                     int tid, int m0, int n0, int knext, char* nxt, R4& ra, R4& rb) {
;   bf16x8 a[2][4], b[2][2];
;   const char* pa = A + (wm + lr) * LDSROW + lh * 16;
;   const char* pb = B + (wn + lr) * LDSROW + lh * 16;
; #pragma unroll
;   for (int i = 0; i < 4; ++i) a[0][i] = *(const bf16x8*)(pa + 32 * i * LDSROW);
; #pragma unroll
;   for (int j = 0; j < 2; ++j) b[0][j] = *(const bf16x8*)(pb + 32 * j * LDSROW);
; #pragma unroll
;   for (int ks = 0; ks < 4; ++ks) {
;     const int cur = ks & 1, nx = cur ^ 1;
;     if (ks < 3) {
; #pragma unroll
;       for (int i = 0; i < 4; ++i) a[nx][i] = *(const bf16x8*)(pa + 32 * i * LDSROW + (ks + 1) * 32);
; #pragma unroll
;       for (int j = 0; j < 2; ++j) b[nx][j] = *(const bf16x8*)(pb + 32 * j * LDSROW + (ks + 1) * 32);
;     }
;     __builtin_amdgcn_sched_barrier(0);
; #pragma unroll
;     for (int i = 0; i < 4; ++i)
; #pragma unroll
;       for (int j = 0; j < 2; ++j)
;         acc[i][j] = __builtin_amdgcn_mfma_f32_32x32x16_bf16(a[cur][i], b[cur][j], acc[i][j], 0, 0, 0);
;     __builtin_amdgcn_sched_barrier(0);
;     if (ks == 1) {
;       al.store(tid, nxt, ra);
;       bl.store(tid, nxt + TILE_BYTES, rb);
;       __builtin_amdgcn_sched_barrier(0);
;       ra = al.load(tid, m0, knext);
;       rb = bl.load(tid, n0, knext);
;       __builtin_amdgcn_sched_barrier(0);
;     }
;   }
.Lp1a_d2:
	s_add_u32 s14, s14, 0x80
	s_addc_u32 s15, s15, 0
	s_add_u32 s16, s16, 0x80
	s_addc_u32 s17, s17, 0
	ds_read_b128 v[166:169], v146
	ds_read_b128 v[170:173], v146 offset:2048
	ds_read_b128 v[174:177], v146 offset:4096
	ds_read_b128 v[178:181], v146 offset:6144
	ds_read_b128 v[222:225], v144
	ds_read_b128 v[226:229], v144 offset:2048
	ds_read_b128 v[230:233], v144 offset:4096
	ds_read_b128 v[234:237], v144 offset:6144
	ds_read_b128 v[238:241], v144 offset:8192
	ds_read_b128 v[198:201], v144 offset:10240
	ds_read_b128 v[152:155], v144 offset:12288
	ds_read_b128 v[156:159], v144 offset:14336
	ds_read_b128 v[182:185], v147
	ds_read_b128 v[186:189], v147 offset:2048
	ds_read_b128 v[190:193], v147 offset:4096
	ds_read_b128 v[194:197], v147 offset:6144
	s_waitcnt lgkmcnt(8)
	v_mfma_f32_16x16x32_bf16 v[0:3], v[166:169], v[222:225], v[0:3]
	v_mfma_f32_16x16x32_bf16 v[4:7], v[170:173], v[222:225], v[4:7]
	v_mfma_f32_16x16x32_bf16 v[8:11], v[174:177], v[222:225], v[8:11]
	v_mfma_f32_16x16x32_bf16 v[12:15], v[178:181], v[222:225], v[12:15]
	v_mfma_f32_16x16x32_bf16 v[16:19], v[166:169], v[226:229], v[16:19]
	v_mfma_f32_16x16x32_bf16 v[20:23], v[170:173], v[226:229], v[20:23]
	v_mfma_f32_16x16x32_bf16 v[24:27], v[174:177], v[226:229], v[24:27]
	v_mfma_f32_16x16x32_bf16 v[28:31], v[178:181], v[226:229], v[28:31]
	v_mfma_f32_16x16x32_bf16 v[32:35], v[166:169], v[230:233], v[32:35]
	v_mfma_f32_16x16x32_bf16 v[36:39], v[170:173], v[230:233], v[36:39]
	v_mfma_f32_16x16x32_bf16 v[40:43], v[174:177], v[230:233], v[40:43]
	v_mfma_f32_16x16x32_bf16 v[44:47], v[178:181], v[230:233], v[44:47]
	v_mfma_f32_16x16x32_bf16 v[48:51], v[166:169], v[234:237], v[48:51]
	v_mfma_f32_16x16x32_bf16 v[52:55], v[170:173], v[234:237], v[52:55]
	v_mfma_f32_16x16x32_bf16 v[56:59], v[174:177], v[234:237], v[56:59]
	v_mfma_f32_16x16x32_bf16 v[60:63], v[178:181], v[234:237], v[60:63]
	ds_read_b128 v[222:225], v145
	ds_read_b128 v[226:229], v145 offset:2048
	ds_read_b128 v[230:233], v145 offset:4096
	ds_read_b128 v[234:237], v145 offset:6144
	s_waitcnt lgkmcnt(8)
	v_mfma_f32_16x16x32_bf16 v[64:67], v[166:169], v[238:241], v[64:67]
	v_mfma_f32_16x16x32_bf16 v[68:71], v[170:173], v[238:241], v[68:71]
	v_mfma_f32_16x16x32_bf16 v[72:75], v[174:177], v[238:241], v[72:75]
	v_mfma_f32_16x16x32_bf16 v[76:79], v[178:181], v[238:241], v[76:79]
	v_mfma_f32_16x16x32_bf16 v[80:83], v[166:169], v[198:201], v[80:83]
	v_mfma_f32_16x16x32_bf16 v[84:87], v[170:173], v[198:201], v[84:87]
	v_mfma_f32_16x16x32_bf16 v[88:91], v[174:177], v[198:201], v[88:91]
	v_mfma_f32_16x16x32_bf16 v[92:95], v[178:181], v[198:201], v[92:95]
	v_mfma_f32_16x16x32_bf16 v[96:99], v[166:169], v[152:155], v[96:99]
	v_mfma_f32_16x16x32_bf16 v[100:103], v[170:173], v[152:155], v[100:103]
	v_mfma_f32_16x16x32_bf16 v[104:107], v[174:177], v[152:155], v[104:107]
	v_mfma_f32_16x16x32_bf16 v[108:111], v[178:181], v[152:155], v[108:111]
	v_mfma_f32_16x16x32_bf16 v[112:115], v[166:169], v[156:159], v[112:115]
	v_mfma_f32_16x16x32_bf16 v[116:119], v[170:173], v[156:159], v[116:119]
	v_mfma_f32_16x16x32_bf16 v[120:123], v[174:177], v[156:159], v[120:123]
	v_mfma_f32_16x16x32_bf16 v[124:127], v[178:181], v[156:159], v[124:127]
	ds_read_b128 v[238:241], v145 offset:8192
	ds_read_b128 v[198:201], v145 offset:10240
	ds_read_b128 v[152:155], v145 offset:12288
	ds_read_b128 v[156:159], v145 offset:14336
	s_waitcnt lgkmcnt(4)
	v_mfma_f32_16x16x32_bf16 v[0:3], v[182:185], v[222:225], v[0:3]
	v_mfma_f32_16x16x32_bf16 v[4:7], v[186:189], v[222:225], v[4:7]
	v_mfma_f32_16x16x32_bf16 v[8:11], v[190:193], v[222:225], v[8:11]
	v_mfma_f32_16x16x32_bf16 v[12:15], v[194:197], v[222:225], v[12:15]
	v_mfma_f32_16x16x32_bf16 v[16:19], v[182:185], v[226:229], v[16:19]
	v_mfma_f32_16x16x32_bf16 v[20:23], v[186:189], v[226:229], v[20:23]
	v_mfma_f32_16x16x32_bf16 v[24:27], v[190:193], v[226:229], v[24:27]
	v_mfma_f32_16x16x32_bf16 v[28:31], v[194:197], v[226:229], v[28:31]
	v_mfma_f32_16x16x32_bf16 v[32:35], v[182:185], v[230:233], v[32:35]
	v_mfma_f32_16x16x32_bf16 v[36:39], v[186:189], v[230:233], v[36:39]
	v_mfma_f32_16x16x32_bf16 v[40:43], v[190:193], v[230:233], v[40:43]
	v_mfma_f32_16x16x32_bf16 v[44:47], v[194:197], v[230:233], v[44:47]
	v_mfma_f32_16x16x32_bf16 v[48:51], v[182:185], v[234:237], v[48:51]
	v_mfma_f32_16x16x32_bf16 v[52:55], v[186:189], v[234:237], v[52:55]
	v_mfma_f32_16x16x32_bf16 v[56:59], v[190:193], v[234:237], v[56:59]
	v_mfma_f32_16x16x32_bf16 v[60:63], v[194:197], v[234:237], v[60:63]
	s_waitcnt lgkmcnt(0)
	v_mfma_f32_16x16x32_bf16 v[64:67], v[182:185], v[238:241], v[64:67]
	v_mfma_f32_16x16x32_bf16 v[68:71], v[186:189], v[238:241], v[68:71]
	v_mfma_f32_16x16x32_bf16 v[72:75], v[190:193], v[238:241], v[72:75]
	v_mfma_f32_16x16x32_bf16 v[76:79], v[194:197], v[238:241], v[76:79]
	v_mfma_f32_16x16x32_bf16 v[80:83], v[182:185], v[198:201], v[80:83]
	v_mfma_f32_16x16x32_bf16 v[84:87], v[186:189], v[198:201], v[84:87]
	v_mfma_f32_16x16x32_bf16 v[88:91], v[190:193], v[198:201], v[88:91]
	v_mfma_f32_16x16x32_bf16 v[92:95], v[194:197], v[198:201], v[92:95]
	v_mfma_f32_16x16x32_bf16 v[96:99], v[182:185], v[152:155], v[96:99]
	v_mfma_f32_16x16x32_bf16 v[100:103], v[186:189], v[152:155], v[100:103]
	v_mfma_f32_16x16x32_bf16 v[104:107], v[190:193], v[152:155], v[104:107]
	v_mfma_f32_16x16x32_bf16 v[108:111], v[194:197], v[152:155], v[108:111]
	v_mfma_f32_16x16x32_bf16 v[112:115], v[182:185], v[156:159], v[112:115]
	v_mfma_f32_16x16x32_bf16 v[116:119], v[186:189], v[156:159], v[116:119]
	v_mfma_f32_16x16x32_bf16 v[120:123], v[190:193], v[156:159], v[120:123]
	v_mfma_f32_16x16x32_bf16 v[124:127], v[194:197], v[156:159], v[124:127]
	s_waitcnt vmcnt(0)
	s_barrier
	s_cmp_eq_u32 s18, 7
	s_cbranch_scc1 .Lp1a_last
	s_cmp_lt_u32 s13, 0x4000
	s_cbranch_scc0 .Lp1a_d3
	s_add_u32 m0, s13, 0x0
	s_nop 0
	global_load_lds_dwordx4 v128, s[14:15]
	global_load_lds_dwordx4 v129, s[14:15] offset:1024
	global_load_lds_dwordx4 v130, s[14:15] offset:2048
	global_load_lds_dwordx4 v131, s[14:15] offset:3072
	s_add_u32 m0, s13, 0x10000
	s_nop 0
	global_load_lds_dwordx4 v132, s[16:17]
	global_load_lds_dwordx4 v133, s[16:17] offset:1024
	global_load_lds_dwordx4 v134, s[16:17] offset:2048
	global_load_lds_dwordx4 v135, s[16:17] offset:3072
	s_add_u32 m0, s13, 0x4000
	s_nop 0
	global_load_lds_dwordx4 v136, s[14:15]
	global_load_lds_dwordx4 v137, s[14:15] offset:1024
	global_load_lds_dwordx4 v138, s[14:15] offset:2048
	global_load_lds_dwordx4 v139, s[14:15] offset:3072
	s_add_u32 m0, s13, 0x14000
	s_nop 0
	global_load_lds_dwordx4 v140, s[16:17]
	global_load_lds_dwordx4 v141, s[16:17] offset:1024
	global_load_lds_dwordx4 v142, s[16:17] offset:2048
	global_load_lds_dwordx4 v143, s[16:17] offset:3072

; template <class AL, class BL>
; DEV void gemm_ktile(Acc& acc, const char* A, const char* B, int wm, int wn, int lr, int lh, const AL& al, const BL& bl,
;                     int tid, int m0, int n0, int knext, char* nxt, R4& ra, R4& rb) {
;   bf16x8 a[2][4], b[2][2];
;   const char* pa = A + (wm + lr) * LDSROW + lh * 16;
;   const char* pb = B + (wn + lr) * LDSROW + lh * 16;
; #pragma unroll
;   for (int i = 0; i < 4; ++i) a[0][i] = *(const bf16x8*)(pa + 32 * i * LDSROW);
; #pragma unroll
;   for (int j = 0; j < 2; ++j) b[0][j] = *(const bf16x8*)(pb + 32 * j * LDSROW);
; #pragma unroll
;   for (int ks = 0; ks < 4; ++ks) {
;     const int cur = ks & 1, nx = cur ^ 1;
;     if (ks < 3) {
; #pragma unroll
;       for (int i = 0; i < 4; ++i) a[nx][i] = *(const bf16x8*)(pa + 32 * i * LDSROW + (ks + 1) * 32);
; #pragma unroll
;       for (int j = 0; j < 2; ++j) b[nx][j] = *(const bf16x8*)(pb + 32 * j * LDSROW + (ks + 1) * 32);
;     }
;     __builtin_amdgcn_sched_barrier(0);
; #pragma unroll
;     for (int i = 0; i < 4; ++i)
; #pragma unroll
;       for (int j = 0; j < 2; ++j)
;         acc[i][j] = __builtin_amdgcn_mfma_f32_32x32x16_bf16(a[cur][i], b[cur][j], acc[i][j], 0, 0, 0);
;     __builtin_amdgcn_sched_barrier(0);
.Lp1a_last:
	ds_read_b128 v[166:169], v146 offset:32768
	ds_read_b128 v[170:173], v146 offset:34816
	ds_read_b128 v[174:177], v146 offset:36864
	ds_read_b128 v[178:181], v146 offset:38912
	ds_read_b128 v[222:225], v144 offset:32768
	ds_read_b128 v[226:229], v144 offset:34816
	ds_read_b128 v[230:233], v144 offset:36864
	ds_read_b128 v[234:237], v144 offset:38912
	ds_read_b128 v[238:241], v144 offset:40960
	ds_read_b128 v[198:201], v144 offset:43008
	ds_read_b128 v[152:155], v144 offset:45056
	ds_read_b128 v[156:159], v144 offset:47104
	ds_read_b128 v[182:185], v147 offset:32768
	ds_read_b128 v[186:189], v147 offset:34816
	ds_read_b128 v[190:193], v147 offset:36864
	ds_read_b128 v[194:197], v147 offset:38912
	s_waitcnt lgkmcnt(8)
	v_mfma_f32_16x16x32_bf16 v[0:3], v[166:169], v[222:225], v[0:3]
	v_mfma_f32_16x16x32_bf16 v[4:7], v[170:173], v[222:225], v[4:7]
	v_mfma_f32_16x16x32_bf16 v[8:11], v[174:177], v[222:225], v[8:11]
	v_mfma_f32_16x16x32_bf16 v[12:15], v[178:181], v[222:225], v[12:15]
	v_mfma_f32_16x16x32_bf16 v[16:19], v[166:169], v[226:229], v[16:19]
	v_mfma_f32_16x16x32_bf16 v[20:23], v[170:173], v[226:229], v[20:23]
	v_mfma_f32_16x16x32_bf16 v[24:27], v[174:177], v[226:229], v[24:27]
	v_mfma_f32_16x16x32_bf16 v[28:31], v[178:181], v[226:229], v[28:31]
	v_mfma_f32_16x16x32_bf16 v[32:35], v[166:169], v[230:233], v[32:35]
	v_mfma_f32_16x16x32_bf16 v[36:39], v[170:173], v[230:233], v[36:39]
	v_mfma_f32_16x16x32_bf16 v[40:43], v[174:177], v[230:233], v[40:43]
	v_mfma_f32_16x16x32_bf16 v[44:47], v[178:181], v[230:233], v[44:47]
	v_mfma_f32_16x16x32_bf16 v[48:51], v[166:169], v[234:237], v[48:51]
	v_mfma_f32_16x16x32_bf16 v[52:55], v[170:173], v[234:237], v[52:55]
	v_mfma_f32_16x16x32_bf16 v[56:59], v[174:177], v[234:237], v[56:59]
	v_mfma_f32_16x16x32_bf16 v[60:63], v[178:181], v[234:237], v[60:63]
	ds_read_b128 v[222:225], v145 offset:32768
	ds_read_b128 v[226:229], v145 offset:34816
	ds_read_b128 v[230:233], v145 offset:36864
	ds_read_b128 v[234:237], v145 offset:38912
	s_waitcnt lgkmcnt(8)
	v_mfma_f32_16x16x32_bf16 v[64:67], v[166:169], v[238:241], v[64:67]
	v_mfma_f32_16x16x32_bf16 v[68:71], v[170:173], v[238:241], v[68:71]
	v_mfma_f32_16x16x32_bf16 v[72:75], v[174:177], v[238:241], v[72:75]
	v_mfma_f32_16x16x32_bf16 v[76:79], v[178:181], v[238:241], v[76:79]
	v_mfma_f32_16x16x32_bf16 v[80:83], v[166:169], v[198:201], v[80:83]
	v_mfma_f32_16x16x32_bf16 v[84:87], v[170:173], v[198:201], v[84:87]
	v_mfma_f32_16x16x32_bf16 v[88:91], v[174:177], v[198:201], v[88:91]
	v_mfma_f32_16x16x32_bf16 v[92:95], v[178:181], v[198:201], v[92:95]
	v_mfma_f32_16x16x32_bf16 v[96:99], v[166:169], v[152:155], v[96:99]
	v_mfma_f32_16x16x32_bf16 v[100:103], v[170:173], v[152:155], v[100:103]
	v_mfma_f32_16x16x32_bf16 v[104:107], v[174:177], v[152:155], v[104:107]
	v_mfma_f32_16x16x32_bf16 v[108:111], v[178:181], v[152:155], v[108:111]
	v_mfma_f32_16x16x32_bf16 v[112:115], v[166:169], v[156:159], v[112:115]
	v_mfma_f32_16x16x32_bf16 v[116:119], v[170:173], v[156:159], v[116:119]
	v_mfma_f32_16x16x32_bf16 v[120:123], v[174:177], v[156:159], v[120:123]
	v_mfma_f32_16x16x32_bf16 v[124:127], v[178:181], v[156:159], v[124:127]
	ds_read_b128 v[238:241], v145 offset:40960
	ds_read_b128 v[198:201], v145 offset:43008
	ds_read_b128 v[152:155], v145 offset:45056
	ds_read_b128 v[156:159], v145 offset:47104
	s_waitcnt lgkmcnt(4)
	v_mfma_f32_16x16x32_bf16 v[0:3], v[182:185], v[222:225], v[0:3]
	v_mfma_f32_16x16x32_bf16 v[4:7], v[186:189], v[222:225], v[4:7]
	v_mfma_f32_16x16x32_bf16 v[8:11], v[190:193], v[222:225], v[8:11]
	v_mfma_f32_16x16x32_bf16 v[12:15], v[194:197], v[222:225], v[12:15]
	v_mfma_f32_16x16x32_bf16 v[16:19], v[182:185], v[226:229], v[16:19]
	v_mfma_f32_16x16x32_bf16 v[20:23], v[186:189], v[226:229], v[20:23]
	v_mfma_f32_16x16x32_bf16 v[24:27], v[190:193], v[226:229], v[24:27]
	v_mfma_f32_16x16x32_bf16 v[28:31], v[194:197], v[226:229], v[28:31]
	v_mfma_f32_16x16x32_bf16 v[32:35], v[182:185], v[230:233], v[32:35]
	v_mfma_f32_16x16x32_bf16 v[36:39], v[186:189], v[230:233], v[36:39]
	v_mfma_f32_16x16x32_bf16 v[40:43], v[190:193], v[230:233], v[40:43]
	v_mfma_f32_16x16x32_bf16 v[44:47], v[194:197], v[230:233], v[44:47]
	v_mfma_f32_16x16x32_bf16 v[48:51], v[182:185], v[234:237], v[48:51]
	v_mfma_f32_16x16x32_bf16 v[52:55], v[186:189], v[234:237], v[52:55]
	v_mfma_f32_16x16x32_bf16 v[56:59], v[190:193], v[234:237], v[56:59]
	v_mfma_f32_16x16x32_bf16 v[60:63], v[194:197], v[234:237], v[60:63]
	s_waitcnt lgkmcnt(0)
	v_mfma_f32_16x16x32_bf16 v[64:67], v[182:185], v[238:241], v[64:67]
	v_mfma_f32_16x16x32_bf16 v[68:71], v[186:189], v[238:241], v[68:71]
	v_mfma_f32_16x16x32_bf16 v[72:75], v[190:193], v[238:241], v[72:75]
	v_mfma_f32_16x16x32_bf16 v[76:79], v[194:197], v[238:241], v[76:79]
	v_mfma_f32_16x16x32_bf16 v[80:83], v[182:185], v[198:201], v[80:83]
	v_mfma_f32_16x16x32_bf16 v[84:87], v[186:189], v[198:201], v[84:87]
	v_mfma_f32_16x16x32_bf16 v[88:91], v[190:193], v[198:201], v[88:91]
	v_mfma_f32_16x16x32_bf16 v[92:95], v[194:197], v[198:201], v[92:95]
	v_mfma_f32_16x16x32_bf16 v[96:99], v[182:185], v[152:155], v[96:99]
	v_mfma_f32_16x16x32_bf16 v[100:103], v[186:189], v[152:155], v[100:103]
	v_mfma_f32_16x16x32_bf16 v[104:107], v[190:193], v[152:155], v[104:107]
	v_mfma_f32_16x16x32_bf16 v[108:111], v[194:197], v[152:155], v[108:111]
	v_mfma_f32_16x16x32_bf16 v[112:115], v[182:185], v[156:159], v[112:115]
	v_mfma_f32_16x16x32_bf16 v[116:119], v[186:189], v[156:159], v[116:119]
	v_mfma_f32_16x16x32_bf16 v[120:123], v[190:193], v[156:159], v[120:123]
	v_mfma_f32_16x16x32_bf16 v[124:127], v[194:197], v[156:159], v[124:127]
	s_barrier
; template <class AL, class BL>
; DEV void gemm_mainloop_p(Acc& acc, const AL& al, const BL& bl, int m0, int n0, int m0n, int n0n, int K, char* lds,
;                          GemmPipe& gp) {
;     ...
;     const bool wrap = (kt + 2 >= nk);
;     const int kk = (wrap ? kt + 2 - nk : kt + 2) * BK;
;     const int mr = wrap ? m0n : m0, nr = wrap ? n0n : n0;
;     __builtin_amdgcn_sched_barrier(0);
;     gemm_ktile(acc, cur, cur + TILE_BYTES, wm, wn, lr, lh, al, bl, tid, mr, nr, kk, nxt, gp.ra, gp.rb);
; DEV void phase_p1(const Params& p, int g, char* smem) {
;     ...
;       const bool more = tile_map(iter + 1, 128, 18, mtn, ntn);
;       if (!more) { mtn = mt; ntn = nt; }
;       Acc acc;
;       acc_zero(acc);
;       const int m0 = mt * 256, n0 = nt * 256;
;       RowLoader al{H, 1024}, bl{WinT + (size_t)1536 * 1024, 1024};
;       gemm_mainloop_p(acc, al, bl, m0, n0, mtn * 256, ntn * 256, 1024, smem, gp);
;       gp.primed = more;
	s_and_b64 vcc, exec, s[0:1]
	s_cbranch_vccz .Lp1a_nomore
	s_lshl_b32 s9, s11, 8
	s_lshl_b32 s10, s12, 8
	v_add_u32_e32 v128, s9, v150
	v_lshlrev_b32_e32 v128, 11, v128
	v_add_u32_e32 v128, v128, v151
	v_add_u32_e32 v129, 0x3c00, v128
	v_add_u32_e32 v130, 0x7800, v128
	v_add_u32_e32 v131, 0xb400, v128
	v_xor_b32_e32 v129, 0x40, v129
	v_xor_b32_e32 v131, 0x40, v131
	v_add_u32_e32 v132, s10, v150
	v_lshlrev_b32_e32 v132, 11, v132
	v_add_u32_e32 v132, v132, v151
	v_add_u32_e32 v133, 0x3c00, v132
	v_add_u32_e32 v134, 0x7800, v132
	v_add_u32_e32 v135, 0xb400, v132
	v_xor_b32_e32 v133, 0x40, v133
	v_xor_b32_e32 v135, 0x40, v135
	v_add_u32_e32 v136, 0x40000, v128
	v_add_u32_e32 v137, 0x40000, v129
	v_add_u32_e32 v138, 0x40000, v130
	v_add_u32_e32 v139, 0x40000, v131
	v_add_u32_e32 v140, 0x40000, v132
	v_add_u32_e32 v141, 0x40000, v133
	v_add_u32_e32 v142, 0x40000, v134
	v_add_u32_e32 v143, 0x40000, v135
	s_mov_b64 s[14:15], s[64:65]
	s_mov_b64 s[16:17], s[24:25]
	s_cmp_lt_u32 s13, 0x4000
	s_cbranch_scc0 .Lp1a_d4
	s_add_u32 m0, s13, 0x0
	s_nop 0
	global_load_lds_dwordx4 v128, s[14:15]
	global_load_lds_dwordx4 v129, s[14:15] offset:1024
	global_load_lds_dwordx4 v130, s[14:15] offset:2048
	global_load_lds_dwordx4 v131, s[14:15] offset:3072
	s_add_u32 m0, s13, 0x10000
	s_nop 0
	global_load_lds_dwordx4 v132, s[16:17]
	global_load_lds_dwordx4 v133, s[16:17] offset:1024
	global_load_lds_dwordx4 v134, s[16:17] offset:2048
	global_load_lds_dwordx4 v135, s[16:17] offset:3072
	s_add_u32 m0, s13, 0x4000
	s_nop 0
	global_load_lds_dwordx4 v136, s[14:15]
	global_load_lds_dwordx4 v137, s[14:15] offset:1024
	global_load_lds_dwordx4 v138, s[14:15] offset:2048
	global_load_lds_dwordx4 v139, s[14:15] offset:3072
	s_add_u32 m0, s13, 0x14000
	s_nop 0
	global_load_lds_dwordx4 v140, s[16:17]
	global_load_lds_dwordx4 v141, s[16:17] offset:1024
	global_load_lds_dwordx4 v142, s[16:17] offset:2048
	global_load_lds_dwordx4 v143, s[16:17] offset:3072

; template <class AL, class BL>
; DEV void gemm_mainloop_p(Acc& acc, const AL& al, const BL& bl, int m0, int n0, int m0n, int n0n, int K, char* lds,
;                          GemmPipe& gp) {
;     ...
;   if (!gp.primed) {
;     gp.ra = al.load(tid, m0, 0);
;     gp.rb = bl.load(tid, n0, 0);
;     __syncthreads();
;     al.store(tid, lds, gp.ra);
;     bl.store(tid, lds + TILE_BYTES, gp.rb);
;     gp.ra = al.load(tid, m0, BK);
;     gp.rb = bl.load(tid, n0, BK);
;     __syncthreads();
; DEV void phase_p1(const Params& p, int g, char* smem) {
;     ...
;     for (int iter = 0;; ++iter) {
;       int cm, tn, cmn, tnn;
;       if (!tile_map(iter, 6, 128, cm, tn)) break;
;       const bool more = tile_map(iter + 1, 6, 128, cmn, tnn);
;       if (!more) { cmn = cm; tnn = tn; }
;       Acc acc;
;       acc_zero(acc);
;       const int m0 = cm * 256, n0 = tn * 256;
;       RowLoader al{WinT, 1024}, bl{H, 1024};
;       gemm_mainloop_p(acc, al, bl, m0, n0, cmn * 256, tnn * 256, 1024, smem, gp);
.LBB0_560:
	s_and_b64 vcc, exec, s[2:3]
	s_lshl_b32 s11, s7, 8
	s_lshl_b32 s2, s8, 8
	v_lshrrev_b32_e32 v149, 6, v202
	v_and_b32_e32 v148, 63, v202
	s_nop 0
	v_readfirstlane_b32 s9, v149
	v_lshrrev_b32_e32 v150, 3, v148
	v_lshl_add_u32 v150, v149, 5, v150
	v_and_b32_e32 v151, 7, v148
	v_lshrrev_b32_e32 v128, 4, v148
	v_xor_b32_e32 v151, v128, v151
	v_lshlrev_b32_e32 v151, 4, v151
	s_lshl_b32 s9, s9, 12
	v_add_u32_e32 v128, s11, v150
	v_lshlrev_b32_e32 v128, 11, v128
	v_add_u32_e32 v128, v128, v151
	v_add_u32_e32 v129, 0x3c00, v128
	v_add_u32_e32 v130, 0x7800, v128
	v_add_u32_e32 v131, 0xb400, v128
	v_xor_b32_e32 v129, 0x40, v129
	v_xor_b32_e32 v131, 0x40, v131
	v_add_u32_e32 v132, s2, v150
	v_lshlrev_b32_e32 v132, 11, v132
	v_add_u32_e32 v132, v132, v151
	v_add_u32_e32 v133, 0x3c00, v132
	v_add_u32_e32 v134, 0x7800, v132
	v_add_u32_e32 v135, 0xb400, v132
	v_xor_b32_e32 v133, 0x40, v133
	v_xor_b32_e32 v135, 0x40, v135
	v_add_u32_e32 v136, 0x40000, v128
	v_add_u32_e32 v137, 0x40000, v129
	v_add_u32_e32 v138, 0x40000, v130
	v_add_u32_e32 v139, 0x40000, v131
	v_add_u32_e32 v140, 0x40000, v132
	v_add_u32_e32 v141, 0x40000, v133
	v_add_u32_e32 v142, 0x40000, v134
	v_add_u32_e32 v143, 0x40000, v135
	v_lshrrev_b32_e32 v161, 6, v202
	v_and_b32_e32 v160, 63, v202
	v_bfe_u32 v242, v160, 1, 3
	v_lshrrev_b32_e32 v243, 4, v160
	v_xor_b32_e32 v242, v242, v243
	v_lshlrev_b32_e32 v242, 4, v242
	v_and_b32_e32 v243, 15, v160
	v_lshlrev_b32_e32 v243, 7, v243
	v_lshrrev_b32_e32 v144, 2, v161
	v_lshl_add_u32 v144, v144, 14, v243
	v_and_b32_e32 v146, 3, v161
	v_lshl_add_u32 v146, v146, 13, v243
	v_add_u32_e32 v146, 0x10000, v146
	v_xor_b32_e32 v145, 0x40, v242
	v_add_u32_e32 v145, v144, v145
	v_add_u32_e32 v144, v144, v242
	v_xor_b32_e32 v147, 0x40, v242
	v_add_u32_e32 v147, v146, v147
	v_add_u32_e32 v146, v146, v242
	s_mov_b64 s[14:15], s[88:89]
	s_mov_b64 s[16:17], s[64:65]
	s_cbranch_vccnz .Lp1b_primed
	s_cmp_lt_u32 s9, 0x4000
	s_cbranch_scc0 .Lp1b_d1
	s_add_u32 m0, s9, 0x0
	s_nop 0
	global_load_lds_dwordx4 v128, s[14:15]
	global_load_lds_dwordx4 v129, s[14:15] offset:1024
	global_load_lds_dwordx4 v130, s[14:15] offset:2048
	global_load_lds_dwordx4 v131, s[14:15] offset:3072
	s_add_u32 m0, s9, 0x10000
	s_nop 0
	global_load_lds_dwordx4 v132, s[16:17]
	global_load_lds_dwordx4 v133, s[16:17] offset:1024
	global_load_lds_dwordx4 v134, s[16:17] offset:2048
	global_load_lds_dwordx4 v135, s[16:17] offset:3072
	s_add_u32 m0, s9, 0x4000
	s_nop 0
	global_load_lds_dwordx4 v136, s[14:15]
	global_load_lds_dwordx4 v137, s[14:15] offset:1024
	global_load_lds_dwordx4 v138, s[14:15] offset:2048
	global_load_lds_dwordx4 v139, s[14:15] offset:3072
	s_add_u32 m0, s9, 0x14000
	s_nop 0
	global_load_lds_dwordx4 v140, s[16:17]
	global_load_lds_dwordx4 v141, s[16:17] offset:1024
	global_load_lds_dwordx4 v142, s[16:17] offset:2048
	global_load_lds_dwordx4 v143, s[16:17] offset:3072

; template <class AL, class BL>
; DEV void gemm_mainloop_p(Acc& acc, const AL& al, const BL& bl, int m0, int n0, int m0n, int n0n, int K, char* lds,
;                          GemmPipe& gp) {
;     ...
;   for (int kt = 0; kt < nk; ++kt) {
;     const char* cur = lds + (kt & 1) * 2 * TILE_BYTES;
;     char* nxt = lds + ((kt + 1) & 1) * 2 * TILE_BYTES;
;     const bool wrap = (kt + 2 >= nk);
;     const int kk = (wrap ? kt + 2 - nk : kt + 2) * BK;
;     const int mr = wrap ? m0n : m0, nr = wrap ? n0n : n0;
;     __builtin_amdgcn_sched_barrier(0);
;     gemm_ktile(acc, cur, cur + TILE_BYTES, wm, wn, lr, lh, al, bl, tid, mr, nr, kk, nxt, gp.ra, gp.rb);
; DEV void acc_zero(Acc& acc) {
; #pragma unroll
;   for (int i = 0; i < 4; ++i)
; #pragma unroll
;     for (int j = 0; j < 2; ++j)
; #pragma unroll
;       for (int r = 0; r < 16; ++r) acc[i][j][r] = 0.f;
; }
.Lp1b_primed:
	s_add_u32 s14, s14, 0x80
	s_addc_u32 s15, s15, 0
	s_add_u32 s16, s16, 0x80
	s_addc_u32 s17, s17, 0
	v_mov_b32_e32 v0, 0
	v_mov_b32_e32 v1, 0
	v_mov_b64_e32 v[2:3], v[0:1]
	v_mov_b64_e32 v[4:5], v[0:1]
	v_mov_b64_e32 v[6:7], v[0:1]
	v_mov_b64_e32 v[8:9], v[0:1]
	v_mov_b64_e32 v[10:11], v[0:1]
	v_mov_b64_e32 v[12:13], v[0:1]
	v_mov_b64_e32 v[14:15], v[0:1]
	v_mov_b64_e32 v[16:17], v[0:1]
	v_mov_b64_e32 v[18:19], v[0:1]
	v_mov_b64_e32 v[20:21], v[0:1]
	v_mov_b64_e32 v[22:23], v[0:1]
	v_mov_b64_e32 v[24:25], v[0:1]
	v_mov_b64_e32 v[26:27], v[0:1]
	v_mov_b64_e32 v[28:29], v[0:1]
	v_mov_b64_e32 v[30:31], v[0:1]
	v_mov_b64_e32 v[32:33], v[0:1]
	v_mov_b64_e32 v[34:35], v[0:1]
	v_mov_b64_e32 v[36:37], v[0:1]
	v_mov_b64_e32 v[38:39], v[0:1]
	v_mov_b64_e32 v[40:41], v[0:1]
	v_mov_b64_e32 v[42:43], v[0:1]
	v_mov_b64_e32 v[44:45], v[0:1]
	v_mov_b64_e32 v[46:47], v[0:1]
	v_mov_b64_e32 v[48:49], v[0:1]
	v_mov_b64_e32 v[50:51], v[0:1]
	v_mov_b64_e32 v[52:53], v[0:1]
	v_mov_b64_e32 v[54:55], v[0:1]
	v_mov_b64_e32 v[56:57], v[0:1]
	v_mov_b64_e32 v[58:59], v[0:1]
	v_mov_b64_e32 v[60:61], v[0:1]
	v_mov_b64_e32 v[62:63], v[0:1]
	v_mov_b64_e32 v[64:65], v[0:1]
	v_mov_b64_e32 v[66:67], v[0:1]
	v_mov_b64_e32 v[68:69], v[0:1]
	v_mov_b64_e32 v[70:71], v[0:1]
	v_mov_b64_e32 v[72:73], v[0:1]
	v_mov_b64_e32 v[74:75], v[0:1]
	v_mov_b64_e32 v[76:77], v[0:1]
	v_mov_b64_e32 v[78:79], v[0:1]
	v_mov_b64_e32 v[80:81], v[0:1]
	v_mov_b64_e32 v[82:83], v[0:1]
	v_mov_b64_e32 v[84:85], v[0:1]
	v_mov_b64_e32 v[86:87], v[0:1]
	v_mov_b64_e32 v[88:89], v[0:1]
	v_mov_b64_e32 v[90:91], v[0:1]
	v_mov_b64_e32 v[92:93], v[0:1]
	v_mov_b64_e32 v[94:95], v[0:1]
	v_mov_b64_e32 v[96:97], v[0:1]
	v_mov_b64_e32 v[98:99], v[0:1]
	v_mov_b64_e32 v[100:101], v[0:1]
	v_mov_b64_e32 v[102:103], v[0:1]
	v_mov_b64_e32 v[104:105], v[0:1]
	v_mov_b64_e32 v[106:107], v[0:1]
	v_mov_b64_e32 v[108:109], v[0:1]
	v_mov_b64_e32 v[110:111], v[0:1]
	v_mov_b64_e32 v[112:113], v[0:1]
	v_mov_b64_e32 v[114:115], v[0:1]
	v_mov_b64_e32 v[116:117], v[0:1]
	v_mov_b64_e32 v[118:119], v[0:1]
	v_mov_b64_e32 v[120:121], v[0:1]
	v_mov_b64_e32 v[122:123], v[0:1]
	v_mov_b64_e32 v[124:125], v[0:1]
	v_mov_b64_e32 v[126:127], v[0:1]
	s_mov_b32 s10, 0
	s_waitcnt vmcnt(16)
	s_barrier
.Lp1b_kloop:
	s_cmp_lt_u32 s9, 0x4000
	s_cbranch_scc0 .Lp1b_d2
	s_add_u32 m0, s9, 0x8000
	s_nop 0
	global_load_lds_dwordx4 v128, s[14:15]
	global_load_lds_dwordx4 v129, s[14:15] offset:1024
	global_load_lds_dwordx4 v130, s[14:15] offset:2048
	global_load_lds_dwordx4 v131, s[14:15] offset:3072
	s_add_u32 m0, s9, 0x18000
	s_nop 0
	global_load_lds_dwordx4 v132, s[16:17]
	global_load_lds_dwordx4 v133, s[16:17] offset:1024
	global_load_lds_dwordx4 v134, s[16:17] offset:2048
	global_load_lds_dwordx4 v135, s[16:17] offset:3072
	s_add_u32 m0, s9, 0xc000
	s_nop 0
	global_load_lds_dwordx4 v136, s[14:15]
	global_load_lds_dwordx4 v137, s[14:15] offset:1024
	global_load_lds_dwordx4 v138, s[14:15] offset:2048
	global_load_lds_dwordx4 v139, s[14:15] offset:3072
	s_add_u32 m0, s9, 0x1c000
	s_nop 0
	global_load_lds_dwordx4 v140, s[16:17]
	global_load_lds_dwordx4 v141, s[16:17] offset:1024
	global_load_lds_dwordx4 v142, s[16:17] offset:2048
	global_load_lds_dwordx4 v143, s[16:17] offset:3072
; template <class AL, class BL>
; DEV void gemm_ktile(Acc& acc, const char* A, const char* B, int wm, int wn, int lr, int lh, const AL& al, const BL& bl,
;                     int tid, int m0, int n0, int knext, char* nxt, R4& ra, R4& rb) {
;   bf16x8 a[2][4], b[2][2];
;   const char* pa = A + (wm + lr) * LDSROW + lh * 16;
;   const char* pb = B + (wn + lr) * LDSROW + lh * 16;
; #pragma unroll
;   for (int i = 0; i < 4; ++i) a[0][i] = *(const bf16x8*)(pa + 32 * i * LDSROW);
; #pragma unroll
;   for (int j = 0; j < 2; ++j) b[0][j] = *(const bf16x8*)(pb + 32 * j * LDSROW);
; #pragma unroll
;   for (int ks = 0; ks < 4; ++ks) {
;     const int cur = ks & 1, nx = cur ^ 1;
;     if (ks < 3) {
; #pragma unroll
;       for (int i = 0; i < 4; ++i) a[nx][i] = *(const bf16x8*)(pa + 32 * i * LDSROW + (ks + 1) * 32);
; #pragma unroll
;       for (int j = 0; j < 2; ++j) b[nx][j] = *(const bf16x8*)(pb + 32 * j * LDSROW + (ks + 1) * 32);
;     }
;     __builtin_amdgcn_sched_barrier(0);
; #pragma unroll
;     for (int i = 0; i < 4; ++i)
; #pragma unroll
;       for (int j = 0; j < 2; ++j)
;         acc[i][j] = __builtin_amdgcn_mfma_f32_32x32x16_bf16(a[cur][i], b[cur][j], acc[i][j], 0, 0, 0);
;     __builtin_amdgcn_sched_barrier(0);
;     if (ks == 1) {
;       al.store(tid, nxt, ra);
;       bl.store(tid, nxt + TILE_BYTES, rb);
;       __builtin_amdgcn_sched_barrier(0);
;       ra = al.load(tid, m0, knext);
;       rb = bl.load(tid, n0, knext);
;       __builtin_amdgcn_sched_barrier(0);
;     }
;   }
.Lp1b_d2:
	s_add_u32 s14, s14, 0x80
	s_addc_u32 s15, s15, 0
	s_add_u32 s16, s16, 0x80
	s_addc_u32 s17, s17, 0
	ds_read_b128 v[166:169], v146
	ds_read_b128 v[170:173], v146 offset:2048
	ds_read_b128 v[174:177], v146 offset:4096
	ds_read_b128 v[178:181], v146 offset:6144
	ds_read_b128 v[222:225], v144
	ds_read_b128 v[226:229], v144 offset:2048
	ds_read_b128 v[230:233], v144 offset:4096
	ds_read_b128 v[234:237], v144 offset:6144
	ds_read_b128 v[238:241], v144 offset:8192
	ds_read_b128 v[198:201], v144 offset:10240
	ds_read_b128 v[152:155], v144 offset:12288
	ds_read_b128 v[156:159], v144 offset:14336
	ds_read_b128 v[182:185], v147
	ds_read_b128 v[186:189], v147 offset:2048
	ds_read_b128 v[190:193], v147 offset:4096
	ds_read_b128 v[194:197], v147 offset:6144
	s_waitcnt lgkmcnt(8)
	v_mfma_f32_16x16x32_bf16 v[0:3], v[166:169], v[222:225], v[0:3]
	v_mfma_f32_16x16x32_bf16 v[4:7], v[170:173], v[222:225], v[4:7]
	v_mfma_f32_16x16x32_bf16 v[8:11], v[174:177], v[222:225], v[8:11]
	v_mfma_f32_16x16x32_bf16 v[12:15], v[178:181], v[222:225], v[12:15]
	v_mfma_f32_16x16x32_bf16 v[16:19], v[166:169], v[226:229], v[16:19]
	v_mfma_f32_16x16x32_bf16 v[20:23], v[170:173], v[226:229], v[20:23]
	v_mfma_f32_16x16x32_bf16 v[24:27], v[174:177], v[226:229], v[24:27]
	v_mfma_f32_16x16x32_bf16 v[28:31], v[178:181], v[226:229], v[28:31]
	v_mfma_f32_16x16x32_bf16 v[32:35], v[166:169], v[230:233], v[32:35]
	v_mfma_f32_16x16x32_bf16 v[36:39], v[170:173], v[230:233], v[36:39]
	v_mfma_f32_16x16x32_bf16 v[40:43], v[174:177], v[230:233], v[40:43]
	v_mfma_f32_16x16x32_bf16 v[44:47], v[178:181], v[230:233], v[44:47]
	v_mfma_f32_16x16x32_bf16 v[48:51], v[166:169], v[234:237], v[48:51]
	v_mfma_f32_16x16x32_bf16 v[52:55], v[170:173], v[234:237], v[52:55]
	v_mfma_f32_16x16x32_bf16 v[56:59], v[174:177], v[234:237], v[56:59]
	v_mfma_f32_16x16x32_bf16 v[60:63], v[178:181], v[234:237], v[60:63]
	ds_read_b128 v[222:225], v145
	ds_read_b128 v[226:229], v145 offset:2048
	ds_read_b128 v[230:233], v145 offset:4096
	ds_read_b128 v[234:237], v145 offset:6144
	s_waitcnt lgkmcnt(8)
	v_mfma_f32_16x16x32_bf16 v[64:67], v[166:169], v[238:241], v[64:67]
	v_mfma_f32_16x16x32_bf16 v[68:71], v[170:173], v[238:241], v[68:71]
	v_mfma_f32_16x16x32_bf16 v[72:75], v[174:177], v[238:241], v[72:75]
	v_mfma_f32_16x16x32_bf16 v[76:79], v[178:181], v[238:241], v[76:79]
	v_mfma_f32_16x16x32_bf16 v[80:83], v[166:169], v[198:201], v[80:83]
	v_mfma_f32_16x16x32_bf16 v[84:87], v[170:173], v[198:201], v[84:87]
	v_mfma_f32_16x16x32_bf16 v[88:91], v[174:177], v[198:201], v[88:91]
	v_mfma_f32_16x16x32_bf16 v[92:95], v[178:181], v[198:201], v[92:95]
	v_mfma_f32_16x16x32_bf16 v[96:99], v[166:169], v[152:155], v[96:99]
	v_mfma_f32_16x16x32_bf16 v[100:103], v[170:173], v[152:155], v[100:103]
	v_mfma_f32_16x16x32_bf16 v[104:107], v[174:177], v[152:155], v[104:107]
	v_mfma_f32_16x16x32_bf16 v[108:111], v[178:181], v[152:155], v[108:111]
	v_mfma_f32_16x16x32_bf16 v[112:115], v[166:169], v[156:159], v[112:115]
	v_mfma_f32_16x16x32_bf16 v[116:119], v[170:173], v[156:159], v[116:119]
	v_mfma_f32_16x16x32_bf16 v[120:123], v[174:177], v[156:159], v[120:123]
	v_mfma_f32_16x16x32_bf16 v[124:127], v[178:181], v[156:159], v[124:127]
	ds_read_b128 v[238:241], v145 offset:8192
	ds_read_b128 v[198:201], v145 offset:10240
	ds_read_b128 v[152:155], v145 offset:12288
	ds_read_b128 v[156:159], v145 offset:14336
	s_waitcnt lgkmcnt(4)
	v_mfma_f32_16x16x32_bf16 v[0:3], v[182:185], v[222:225], v[0:3]
	v_mfma_f32_16x16x32_bf16 v[4:7], v[186:189], v[222:225], v[4:7]
	v_mfma_f32_16x16x32_bf16 v[8:11], v[190:193], v[222:225], v[8:11]
	v_mfma_f32_16x16x32_bf16 v[12:15], v[194:197], v[222:225], v[12:15]
	v_mfma_f32_16x16x32_bf16 v[16:19], v[182:185], v[226:229], v[16:19]
	v_mfma_f32_16x16x32_bf16 v[20:23], v[186:189], v[226:229], v[20:23]
	v_mfma_f32_16x16x32_bf16 v[24:27], v[190:193], v[226:229], v[24:27]
	v_mfma_f32_16x16x32_bf16 v[28:31], v[194:197], v[226:229], v[28:31]
	v_mfma_f32_16x16x32_bf16 v[32:35], v[182:185], v[230:233], v[32:35]
	v_mfma_f32_16x16x32_bf16 v[36:39], v[186:189], v[230:233], v[36:39]
	v_mfma_f32_16x16x32_bf16 v[40:43], v[190:193], v[230:233], v[40:43]
	v_mfma_f32_16x16x32_bf16 v[44:47], v[194:197], v[230:233], v[44:47]
	v_mfma_f32_16x16x32_bf16 v[48:51], v[182:185], v[234:237], v[48:51]
	v_mfma_f32_16x16x32_bf16 v[52:55], v[186:189], v[234:237], v[52:55]
	v_mfma_f32_16x16x32_bf16 v[56:59], v[190:193], v[234:237], v[56:59]
	v_mfma_f32_16x16x32_bf16 v[60:63], v[194:197], v[234:237], v[60:63]
	s_waitcnt lgkmcnt(0)
	v_mfma_f32_16x16x32_bf16 v[64:67], v[182:185], v[238:241], v[64:67]
	v_mfma_f32_16x16x32_bf16 v[68:71], v[186:189], v[238:241], v[68:71]
	v_mfma_f32_16x16x32_bf16 v[72:75], v[190:193], v[238:241], v[72:75]
	v_mfma_f32_16x16x32_bf16 v[76:79], v[194:197], v[238:241], v[76:79]
	v_mfma_f32_16x16x32_bf16 v[80:83], v[182:185], v[198:201], v[80:83]
	v_mfma_f32_16x16x32_bf16 v[84:87], v[186:189], v[198:201], v[84:87]
	v_mfma_f32_16x16x32_bf16 v[88:91], v[190:193], v[198:201], v[88:91]
	v_mfma_f32_16x16x32_bf16 v[92:95], v[194:197], v[198:201], v[92:95]
	v_mfma_f32_16x16x32_bf16 v[96:99], v[182:185], v[152:155], v[96:99]
	v_mfma_f32_16x16x32_bf16 v[100:103], v[186:189], v[152:155], v[100:103]
	v_mfma_f32_16x16x32_bf16 v[104:107], v[190:193], v[152:155], v[104:107]
	v_mfma_f32_16x16x32_bf16 v[108:111], v[194:197], v[152:155], v[108:111]
	v_mfma_f32_16x16x32_bf16 v[112:115], v[182:185], v[156:159], v[112:115]
	v_mfma_f32_16x16x32_bf16 v[116:119], v[186:189], v[156:159], v[116:119]
	v_mfma_f32_16x16x32_bf16 v[120:123], v[190:193], v[156:159], v[120:123]
	v_mfma_f32_16x16x32_bf16 v[124:127], v[194:197], v[156:159], v[124:127]
	s_waitcnt vmcnt(0)
	s_barrier
	s_cmp_eq_u32 s10, 7
	s_cbranch_scc1 .Lp1b_last
	s_cmp_lt_u32 s9, 0x4000
	s_cbranch_scc0 .Lp1b_d3
	s_add_u32 m0, s9, 0x0
	s_nop 0
	global_load_lds_dwordx4 v128, s[14:15]
	global_load_lds_dwordx4 v129, s[14:15] offset:1024
	global_load_lds_dwordx4 v130, s[14:15] offset:2048
	global_load_lds_dwordx4 v131, s[14:15] offset:3072
	s_add_u32 m0, s9, 0x10000
	s_nop 0
	global_load_lds_dwordx4 v132, s[16:17]
	global_load_lds_dwordx4 v133, s[16:17] offset:1024
	global_load_lds_dwordx4 v134, s[16:17] offset:2048
	global_load_lds_dwordx4 v135, s[16:17] offset:3072
	s_add_u32 m0, s9, 0x4000
	s_nop 0
	global_load_lds_dwordx4 v136, s[14:15]
	global_load_lds_dwordx4 v137, s[14:15] offset:1024
	global_load_lds_dwordx4 v138, s[14:15] offset:2048
	global_load_lds_dwordx4 v139, s[14:15] offset:3072
	s_add_u32 m0, s9, 0x14000
	s_nop 0
	global_load_lds_dwordx4 v140, s[16:17]
	global_load_lds_dwordx4 v141, s[16:17] offset:1024
	global_load_lds_dwordx4 v142, s[16:17] offset:2048
	global_load_lds_dwordx4 v143, s[16:17] offset:3072

; template <class AL, class BL>
; DEV void gemm_ktile(Acc& acc, const char* A, const char* B, int wm, int wn, int lr, int lh, const AL& al, const BL& bl,
;                     int tid, int m0, int n0, int knext, char* nxt, R4& ra, R4& rb) {
;   bf16x8 a[2][4], b[2][2];
;   const char* pa = A + (wm + lr) * LDSROW + lh * 16;
;   const char* pb = B + (wn + lr) * LDSROW + lh * 16;
; #pragma unroll
;   for (int i = 0; i < 4; ++i) a[0][i] = *(const bf16x8*)(pa + 32 * i * LDSROW);
; #pragma unroll
;   for (int j = 0; j < 2; ++j) b[0][j] = *(const bf16x8*)(pb + 32 * j * LDSROW);
; #pragma unroll
;   for (int ks = 0; ks < 4; ++ks) {
;     const int cur = ks & 1, nx = cur ^ 1;
;     if (ks < 3) {
; #pragma unroll
;       for (int i = 0; i < 4; ++i) a[nx][i] = *(const bf16x8*)(pa + 32 * i * LDSROW + (ks + 1) * 32);
; #pragma unroll
;       for (int j = 0; j < 2; ++j) b[nx][j] = *(const bf16x8*)(pb + 32 * j * LDSROW + (ks + 1) * 32);
;     }
;     __builtin_amdgcn_sched_barrier(0);
; #pragma unroll
;     for (int i = 0; i < 4; ++i)
; #pragma unroll
;       for (int j = 0; j < 2; ++j)
;         acc[i][j] = __builtin_amdgcn_mfma_f32_32x32x16_bf16(a[cur][i], b[cur][j], acc[i][j], 0, 0, 0);
;     __builtin_amdgcn_sched_barrier(0);
.Lp1b_last:
	ds_read_b128 v[166:169], v146 offset:32768
	ds_read_b128 v[170:173], v146 offset:34816
	ds_read_b128 v[174:177], v146 offset:36864
	ds_read_b128 v[178:181], v146 offset:38912
	ds_read_b128 v[222:225], v144 offset:32768
	ds_read_b128 v[226:229], v144 offset:34816
	ds_read_b128 v[230:233], v144 offset:36864
	ds_read_b128 v[234:237], v144 offset:38912
	ds_read_b128 v[238:241], v144 offset:40960
	ds_read_b128 v[198:201], v144 offset:43008
	ds_read_b128 v[152:155], v144 offset:45056
	ds_read_b128 v[156:159], v144 offset:47104
	ds_read_b128 v[182:185], v147 offset:32768
	ds_read_b128 v[186:189], v147 offset:34816
	ds_read_b128 v[190:193], v147 offset:36864
	ds_read_b128 v[194:197], v147 offset:38912
	s_waitcnt lgkmcnt(8)
	v_mfma_f32_16x16x32_bf16 v[0:3], v[166:169], v[222:225], v[0:3]
	v_mfma_f32_16x16x32_bf16 v[4:7], v[170:173], v[222:225], v[4:7]
	v_mfma_f32_16x16x32_bf16 v[8:11], v[174:177], v[222:225], v[8:11]
	v_mfma_f32_16x16x32_bf16 v[12:15], v[178:181], v[222:225], v[12:15]
	v_mfma_f32_16x16x32_bf16 v[16:19], v[166:169], v[226:229], v[16:19]
	v_mfma_f32_16x16x32_bf16 v[20:23], v[170:173], v[226:229], v[20:23]
	v_mfma_f32_16x16x32_bf16 v[24:27], v[174:177], v[226:229], v[24:27]
	v_mfma_f32_16x16x32_bf16 v[28:31], v[178:181], v[226:229], v[28:31]
	v_mfma_f32_16x16x32_bf16 v[32:35], v[166:169], v[230:233], v[32:35]
	v_mfma_f32_16x16x32_bf16 v[36:39], v[170:173], v[230:233], v[36:39]
	v_mfma_f32_16x16x32_bf16 v[40:43], v[174:177], v[230:233], v[40:43]
	v_mfma_f32_16x16x32_bf16 v[44:47], v[178:181], v[230:233], v[44:47]
	v_mfma_f32_16x16x32_bf16 v[48:51], v[166:169], v[234:237], v[48:51]
	v_mfma_f32_16x16x32_bf16 v[52:55], v[170:173], v[234:237], v[52:55]
	v_mfma_f32_16x16x32_bf16 v[56:59], v[174:177], v[234:237], v[56:59]
	v_mfma_f32_16x16x32_bf16 v[60:63], v[178:181], v[234:237], v[60:63]
	ds_read_b128 v[222:225], v145 offset:32768
	ds_read_b128 v[226:229], v145 offset:34816
	ds_read_b128 v[230:233], v145 offset:36864
	ds_read_b128 v[234:237], v145 offset:38912
	s_waitcnt lgkmcnt(8)
	v_mfma_f32_16x16x32_bf16 v[64:67], v[166:169], v[238:241], v[64:67]
	v_mfma_f32_16x16x32_bf16 v[68:71], v[170:173], v[238:241], v[68:71]
	v_mfma_f32_16x16x32_bf16 v[72:75], v[174:177], v[238:241], v[72:75]
	v_mfma_f32_16x16x32_bf16 v[76:79], v[178:181], v[238:241], v[76:79]
	v_mfma_f32_16x16x32_bf16 v[80:83], v[166:169], v[198:201], v[80:83]
	v_mfma_f32_16x16x32_bf16 v[84:87], v[170:173], v[198:201], v[84:87]
	v_mfma_f32_16x16x32_bf16 v[88:91], v[174:177], v[198:201], v[88:91]
	v_mfma_f32_16x16x32_bf16 v[92:95], v[178:181], v[198:201], v[92:95]
	v_mfma_f32_16x16x32_bf16 v[96:99], v[166:169], v[152:155], v[96:99]
	v_mfma_f32_16x16x32_bf16 v[100:103], v[170:173], v[152:155], v[100:103]
	v_mfma_f32_16x16x32_bf16 v[104:107], v[174:177], v[152:155], v[104:107]
	v_mfma_f32_16x16x32_bf16 v[108:111], v[178:181], v[152:155], v[108:111]
	v_mfma_f32_16x16x32_bf16 v[112:115], v[166:169], v[156:159], v[112:115]
	v_mfma_f32_16x16x32_bf16 v[116:119], v[170:173], v[156:159], v[116:119]
	v_mfma_f32_16x16x32_bf16 v[120:123], v[174:177], v[156:159], v[120:123]
	v_mfma_f32_16x16x32_bf16 v[124:127], v[178:181], v[156:159], v[124:127]
	ds_read_b128 v[238:241], v145 offset:40960
	ds_read_b128 v[198:201], v145 offset:43008
	ds_read_b128 v[152:155], v145 offset:45056
	ds_read_b128 v[156:159], v145 offset:47104
	s_waitcnt lgkmcnt(4)
	v_mfma_f32_16x16x32_bf16 v[0:3], v[182:185], v[222:225], v[0:3]
	v_mfma_f32_16x16x32_bf16 v[4:7], v[186:189], v[222:225], v[4:7]
	v_mfma_f32_16x16x32_bf16 v[8:11], v[190:193], v[222:225], v[8:11]
	v_mfma_f32_16x16x32_bf16 v[12:15], v[194:197], v[222:225], v[12:15]
	v_mfma_f32_16x16x32_bf16 v[16:19], v[182:185], v[226:229], v[16:19]
	v_mfma_f32_16x16x32_bf16 v[20:23], v[186:189], v[226:229], v[20:23]
	v_mfma_f32_16x16x32_bf16 v[24:27], v[190:193], v[226:229], v[24:27]
	v_mfma_f32_16x16x32_bf16 v[28:31], v[194:197], v[226:229], v[28:31]
	v_mfma_f32_16x16x32_bf16 v[32:35], v[182:185], v[230:233], v[32:35]
	v_mfma_f32_16x16x32_bf16 v[36:39], v[186:189], v[230:233], v[36:39]
	v_mfma_f32_16x16x32_bf16 v[40:43], v[190:193], v[230:233], v[40:43]
	v_mfma_f32_16x16x32_bf16 v[44:47], v[194:197], v[230:233], v[44:47]
	v_mfma_f32_16x16x32_bf16 v[48:51], v[182:185], v[234:237], v[48:51]
	v_mfma_f32_16x16x32_bf16 v[52:55], v[186:189], v[234:237], v[52:55]
	v_mfma_f32_16x16x32_bf16 v[56:59], v[190:193], v[234:237], v[56:59]
	v_mfma_f32_16x16x32_bf16 v[60:63], v[194:197], v[234:237], v[60:63]
	s_waitcnt lgkmcnt(0)
	v_mfma_f32_16x16x32_bf16 v[64:67], v[182:185], v[238:241], v[64:67]
	v_mfma_f32_16x16x32_bf16 v[68:71], v[186:189], v[238:241], v[68:71]
	v_mfma_f32_16x16x32_bf16 v[72:75], v[190:193], v[238:241], v[72:75]
	v_mfma_f32_16x16x32_bf16 v[76:79], v[194:197], v[238:241], v[76:79]
	v_mfma_f32_16x16x32_bf16 v[80:83], v[182:185], v[198:201], v[80:83]
	v_mfma_f32_16x16x32_bf16 v[84:87], v[186:189], v[198:201], v[84:87]
	v_mfma_f32_16x16x32_bf16 v[88:91], v[190:193], v[198:201], v[88:91]
	v_mfma_f32_16x16x32_bf16 v[92:95], v[194:197], v[198:201], v[92:95]
	v_mfma_f32_16x16x32_bf16 v[96:99], v[182:185], v[152:155], v[96:99]
	v_mfma_f32_16x16x32_bf16 v[100:103], v[186:189], v[152:155], v[100:103]
	v_mfma_f32_16x16x32_bf16 v[104:107], v[190:193], v[152:155], v[104:107]
	v_mfma_f32_16x16x32_bf16 v[108:111], v[194:197], v[152:155], v[108:111]
	v_mfma_f32_16x16x32_bf16 v[112:115], v[182:185], v[156:159], v[112:115]
	v_mfma_f32_16x16x32_bf16 v[116:119], v[186:189], v[156:159], v[116:119]
	v_mfma_f32_16x16x32_bf16 v[120:123], v[190:193], v[156:159], v[120:123]
	v_mfma_f32_16x16x32_bf16 v[124:127], v[194:197], v[156:159], v[124:127]
	s_barrier
; template <class AL, class BL>
; DEV void gemm_mainloop_p(Acc& acc, const AL& al, const BL& bl, int m0, int n0, int m0n, int n0n, int K, char* lds,
;                          GemmPipe& gp) {
;     ...
;     const bool wrap = (kt + 2 >= nk);
;     const int kk = (wrap ? kt + 2 - nk : kt + 2) * BK;
;     const int mr = wrap ? m0n : m0, nr = wrap ? n0n : n0;
;     __builtin_amdgcn_sched_barrier(0);
;     gemm_ktile(acc, cur, cur + TILE_BYTES, wm, wn, lr, lh, al, bl, tid, mr, nr, kk, nxt, gp.ra, gp.rb);
; DEV void phase_p1(const Params& p, int g, char* smem) {
;     ...
;       const bool more = tile_map(iter + 1, 6, 128, cmn, tnn);
;       if (!more) { cmn = cm; tnn = tn; }
;       Acc acc;
;       acc_zero(acc);
;       const int m0 = cm * 256, n0 = tn * 256;
;       RowLoader al{WinT, 1024}, bl{H, 1024};
;       gemm_mainloop_p(acc, al, bl, m0, n0, cmn * 256, tnn * 256, 1024, smem, gp);
;       gp.primed = more;
	s_and_b64 vcc, exec, s[0:1]
	s_cbranch_vccz .Lp1b_nomore
	s_lshl_b32 s4, s12, 8
	s_lshl_b32 s5, s13, 8
	v_add_u32_e32 v128, s4, v150
	v_lshlrev_b32_e32 v128, 11, v128
	v_add_u32_e32 v128, v128, v151
	v_add_u32_e32 v129, 0x3c00, v128
	v_add_u32_e32 v130, 0x7800, v128
	v_add_u32_e32 v131, 0xb400, v128
	v_xor_b32_e32 v129, 0x40, v129
	v_xor_b32_e32 v131, 0x40, v131
	v_add_u32_e32 v132, s5, v150
	v_lshlrev_b32_e32 v132, 11, v132
	v_add_u32_e32 v132, v132, v151
	v_add_u32_e32 v133, 0x3c00, v132
	v_add_u32_e32 v134, 0x7800, v132
	v_add_u32_e32 v135, 0xb400, v132
	v_xor_b32_e32 v133, 0x40, v133
	v_xor_b32_e32 v135, 0x40, v135
	v_add_u32_e32 v136, 0x40000, v128
	v_add_u32_e32 v137, 0x40000, v129
	v_add_u32_e32 v138, 0x40000, v130
	v_add_u32_e32 v139, 0x40000, v131
	v_add_u32_e32 v140, 0x40000, v132
	v_add_u32_e32 v141, 0x40000, v133
	v_add_u32_e32 v142, 0x40000, v134
	v_add_u32_e32 v143, 0x40000, v135
	s_mov_b64 s[14:15], s[88:89]
	s_mov_b64 s[16:17], s[64:65]
	s_cmp_lt_u32 s9, 0x4000
	s_cbranch_scc0 .Lp1b_d4
	s_add_u32 m0, s9, 0x0
	s_nop 0
	global_load_lds_dwordx4 v128, s[14:15]
	global_load_lds_dwordx4 v129, s[14:15] offset:1024
	global_load_lds_dwordx4 v130, s[14:15] offset:2048
	global_load_lds_dwordx4 v131, s[14:15] offset:3072
	s_add_u32 m0, s9, 0x10000
	s_nop 0
	global_load_lds_dwordx4 v132, s[16:17]
	global_load_lds_dwordx4 v133, s[16:17] offset:1024
	global_load_lds_dwordx4 v134, s[16:17] offset:2048
	global_load_lds_dwordx4 v135, s[16:17] offset:3072
	s_add_u32 m0, s9, 0x4000
	s_nop 0
	global_load_lds_dwordx4 v136, s[14:15]
	global_load_lds_dwordx4 v137, s[14:15] offset:1024
	global_load_lds_dwordx4 v138, s[14:15] offset:2048
	global_load_lds_dwordx4 v139, s[14:15] offset:3072
	s_add_u32 m0, s9, 0x14000
	s_nop 0
	global_load_lds_dwordx4 v140, s[16:17]
	global_load_lds_dwordx4 v141, s[16:17] offset:1024
	global_load_lds_dwordx4 v142, s[16:17] offset:2048
	global_load_lds_dwordx4 v143, s[16:17] offset:3072

; DEV float bf2f(u16 h) { return __uint_as_float(((unsigned)h) << 16); }
; DEV float bflo(unsigned w) { return __uint_as_float(w << 16); }
; DEV float bfhi(unsigned w) { return __uint_as_float(w & 0xffff0000u); }
; DEV F8 conv8(const u16* __restrict__ row, int t, int L, float w0, float w1, float w2, float bb) {
;   const uint4 u = *(const uint4*)(row + t);
;   const float um = (t > 0) ? bf2f(row[t - 1]) : 0.f;
;   const float up = (t + 8 < L) ? bf2f(row[t + 8]) : 0.f;
;   float x[10];
;   x[0] = um;
;   x[1] = bflo(u.x); x[2] = bfhi(u.x); x[3] = bflo(u.y); x[4] = bfhi(u.y);
;   x[5] = bflo(u.z); x[6] = bfhi(u.z); x[7] = bflo(u.w); x[8] = bfhi(u.w);
;   x[9] = up;
; template <int BG>
; DEV void hyena_item_mfma(const Params& p, int g, int item, char* smem, int half) {
;     ...
;   {
;     const float wx1_0 = cw[0 * 1536 + 512 + c], wx1_1 = cw[1 * 1536 + 512 + c], wx1_2 = cw[2 * 1536 + 512 + c], bx1 = cb[512 + c];
;     const float wv_0 = cw[0 * 1536 + 1024 + c], wv_1 = cw[1 * 1536 + 1024 + c], wv_2 = cw[2 * 1536 + 1024 + c], bv = cb[1024 + c];
; #pragma unroll 4
;     for (int e = tid; e < BG * L / 8; e += 256) {
;       const int bl = e / (L / 8), t = (e % (L / 8)) * 8;
;       const int b = bgi * BG + bl;
;       const F8 a = conv8(UHY + ((size_t)b * 1536 + 1024 + c) * L, t, L, wv_0, wv_1, wv_2, bv);
;       const F8 x = conv8(UHY + ((size_t)b * 1536 + 512 + c) * L, t, L, wx1_0, wx1_1, wx1_2, bx1);
.LBB0_738:
	v_readlane_b32 s36, v249, 32
	v_readlane_b32 s37, v249, 33
	s_lshl_b64 s[24:25], s[18:19], 2
	v_readlane_b32 s38, v249, 34
	v_readlane_b32 s39, v249, 35
	s_mov_b64 s[8:9], s[36:37]
	s_add_u32 s20, s8, s24
	s_mov_b64 s[10:11], s[38:39]
	s_addc_u32 s21, s9, s25
	s_add_u32 s22, s10, s24
	s_addc_u32 s23, s11, s25
	global_load_dword v10, v208, s[20:21]
	global_load_dword v11, v209, s[20:21] offset:2048
	global_load_dword v12, v210, s[20:21]
	global_load_dword v13, v210, s[22:23]
	global_load_dword v14, v208, s[20:21] offset:2048
	global_load_dword v15, v165, s[20:21] offset:2048
	global_load_dword v16, v165, s[22:23] offset:2048
	global_load_dword v17, v211, s[20:21]
	s_lshl_b32 s0, s35, 1
	s_and_b32 s36, s0, 2
	s_add_u32 s4, s18, 0x400
	s_addc_u32 s5, s19, 0
	s_add_u32 s8, s18, 0x200
	s_waitcnt vmcnt(9)
	v_lshlrev_b32_e32 v148, 3, v146
	s_addc_u32 s9, s19, 0
	v_lshrrev_b32_e32 v18, 2, v146
	s_mov_b64 s[10:11], 0
	v_mov_b32_e32 v19, v148
	v_mov_b32_e32 v20, v145
	v_mov_b32_e32 v21, v146
	v_readlane_b32 s40, v249, 36
	v_readlane_b32 s41, v249, 37
	v_readlane_b32 s42, v249, 38
	v_readlane_b32 s43, v249, 39
	v_readlane_b32 s44, v249, 40
	v_readlane_b32 s45, v249, 41
	v_readlane_b32 s46, v249, 42
	v_readlane_b32 s47, v249, 43
	v_readlane_b32 s48, v249, 44
	v_readlane_b32 s49, v249, 45
	v_readlane_b32 s50, v249, 46
	v_readlane_b32 s51, v249, 47
	s_mov_b32 s100, 0
	v_lshrrev_b32_e32 v52, 10, v21
	v_add_u32_e32 v52, s36, v52
	v_mul_u32_u24_e32 v52, 0x600, v52
	v_mov_b32_e32 v53, 0
	v_lshl_add_u64 v[54:55], s[4:5], 0, v[52:53]
	v_lshlrev_b64 v[54:55], 14, v[54:55]
	v_lshl_add_u64 v[54:55], s[74:75], 0, v[54:55]
	v_and_b32_e32 v56, 0x1ff8, v19
	v_lshlrev_b32_e32 v58, 1, v56
	v_mov_b32_e32 v59, 0
	v_lshl_add_u64 v[54:55], v[54:55], 0, v[58:59]
	global_load_dwordx4 v[40:43], v[54:55], off
	v_cmp_ne_u32_e32 vcc, 0, v56
	s_movk_i32 s0, 0x1ff8
	v_cmp_ne_u32_e64 s[0:1], s0, v56
	v_mov_b32_e32 v48, 0
	v_mov_b32_e32 v49, 0
	v_mov_b32_e32 v50, 0
	v_mov_b32_e32 v51, 0
	s_and_saveexec_b64 s[12:13], vcc
	global_load_ushort v48, v[54:55], off offset:-2
	s_mov_b64 exec, s[12:13]
	s_and_saveexec_b64 s[12:13], s[0:1]
	global_load_ushort v49, v[54:55], off offset:16
	s_mov_b64 exec, s[12:13]
	v_lshl_add_u64 v[54:55], s[8:9], 0, v[52:53]
	v_lshlrev_b64 v[54:55], 14, v[54:55]
	v_lshl_add_u64 v[54:55], s[74:75], 0, v[54:55]
	v_lshl_add_u64 v[54:55], v[54:55], 0, v[58:59]
	global_load_dwordx4 v[44:47], v[54:55], off
	s_and_saveexec_b64 s[12:13], vcc
	global_load_ushort v50, v[54:55], off offset:-2
	s_mov_b64 exec, s[12:13]
	s_and_saveexec_b64 s[12:13], s[0:1]
	global_load_ushort v51, v[54:55], off offset:16
	s_mov_b64 exec, s[12:13]
.LhyA_top:
	s_waitcnt vmcnt(0)
	v_mov_b32_e32 v4, v40
	v_mov_b32_e32 v5, v41
	v_mov_b32_e32 v6, v42
	v_mov_b32_e32 v7, v43
	v_mov_b32_e32 v0, v44
	v_mov_b32_e32 v1, v45
	v_mov_b32_e32 v2, v46
	v_mov_b32_e32 v3, v47
	v_lshlrev_b32_e32 v26, 16, v48
	v_lshlrev_b32_e32 v24, 16, v49
	v_lshlrev_b32_e32 v25, 16, v50
	v_lshlrev_b32_e32 v23, 16, v51
	v_lshrrev_b32_e32 v22, 10, v21
	s_cmp_lt_u32 s100, 7
	s_cbranch_scc0 .LhyA_nonext
	v_add_u32_e32 v60, 0x100, v21
	v_add_u32_e32 v61, 0x800, v19
	v_lshrrev_b32_e32 v52, 10, v60
	v_add_u32_e32 v52, s36, v52
	v_mul_u32_u24_e32 v52, 0x600, v52
	v_mov_b32_e32 v53, 0
	v_lshl_add_u64 v[54:55], s[4:5], 0, v[52:53]
	v_lshlrev_b64 v[54:55], 14, v[54:55]
	v_lshl_add_u64 v[54:55], s[74:75], 0, v[54:55]
	v_and_b32_e32 v56, 0x1ff8, v61
	v_lshlrev_b32_e32 v58, 1, v56
	v_mov_b32_e32 v59, 0
	v_lshl_add_u64 v[54:55], v[54:55], 0, v[58:59]
	global_load_dwordx4 v[40:43], v[54:55], off
	v_cmp_ne_u32_e32 vcc, 0, v56
	s_movk_i32 s0, 0x1ff8
	v_cmp_ne_u32_e64 s[0:1], s0, v56
	v_mov_b32_e32 v48, 0
	v_mov_b32_e32 v49, 0
	v_mov_b32_e32 v50, 0
	v_mov_b32_e32 v51, 0
	s_and_saveexec_b64 s[12:13], vcc
	global_load_ushort v48, v[54:55], off offset:-2
	s_mov_b64 exec, s[12:13]
	s_and_saveexec_b64 s[12:13], s[0:1]
	global_load_ushort v49, v[54:55], off offset:16
	s_mov_b64 exec, s[12:13]
	v_lshl_add_u64 v[54:55], s[8:9], 0, v[52:53]
	v_lshlrev_b64 v[54:55], 14, v[54:55]
	v_lshl_add_u64 v[54:55], s[74:75], 0, v[54:55]
	v_lshl_add_u64 v[54:55], v[54:55], 0, v[58:59]
	global_load_dwordx4 v[44:47], v[54:55], off
	s_and_saveexec_b64 s[12:13], vcc
	global_load_ushort v50, v[54:55], off offset:-2
	s_mov_b64 exec, s[12:13]
	s_and_saveexec_b64 s[12:13], s[0:1]
	global_load_ushort v51, v[54:55], off offset:16
	s_mov_b64 exec, s[12:13]
; DEV float bf2f(u16 h) { return __uint_as_float(((unsigned)h) << 16); }
; DEV float bflo(unsigned w) { return __uint_as_float(w << 16); }
; DEV float bfhi(unsigned w) { return __uint_as_float(w & 0xffff0000u); }
; DEV F8 conv8(const u16* __restrict__ row, int t, int L, float w0, float w1, float w2, float bb) {
;   const uint4 u = *(const uint4*)(row + t);
;   const float um = (t > 0) ? bf2f(row[t - 1]) : 0.f;
;   const float up = (t + 8 < L) ? bf2f(row[t + 8]) : 0.f;
;   float x[10];
;   x[0] = um;
;   x[1] = bflo(u.x); x[2] = bfhi(u.x); x[3] = bflo(u.y); x[4] = bfhi(u.y);
;   x[5] = bflo(u.z); x[6] = bfhi(u.z); x[7] = bflo(u.w); x[8] = bfhi(u.w);
;   x[9] = up;
;   F8 o;
; #pragma unroll
;   for (int j = 0; j < 8; ++j) o.v[j] = x[j] * w0 + x[j + 1] * w1 + x[j + 2] * w2 + bb;
;   return o;
; template <int BG>
; DEV void hyena_item_mfma(const Params& p, int g, int item, char* smem, int half) {
;     ...
;     for (int e = tid; e < BG * L / 8; e += 256) {
;       const int bl = e / (L / 8), t = (e % (L / 8)) * 8;
;       const int b = bgi * BG + bl;
;       const F8 a = conv8(UHY + ((size_t)b * 1536 + 1024 + c) * L, t, L, wv_0, wv_1, wv_2, bv);
;       const F8 x = conv8(UHY + ((size_t)b * 1536 + 512 + c) * L, t, L, wx1_0, wx1_1, wx1_2, bx1);
;       *(uint4*)(Vl + ((t >> 6) * BG + bl) * VROW + (t & 63) * 2) =
;           make_uint4(pack2(a.v[0] * x.v[0], a.v[1] * x.v[1]), pack2(a.v[2] * x.v[2], a.v[3] * x.v[3]),
;                      pack2(a.v[4] * x.v[4], a.v[5] * x.v[5]), pack2(a.v[6] * x.v[6], a.v[7] * x.v[7]));
.LhyA_nonext:
	s_add_u32 s100, s100, 1
	v_lshlrev_b32_e32 v8, 16, v4
	v_and_b32_e32 v4, 0xffff0000, v4
	v_mul_f32_e32 v29, v14, v4
	v_lshlrev_b32_e32 v9, 16, v5
	v_fmac_f32_e32 v29, v12, v8
	v_mul_f32_e32 v26, v12, v26
	v_fmac_f32_e32 v29, v17, v9
	v_fmac_f32_e32 v26, v14, v8
	v_add_f32_e32 v8, v13, v29
	v_mul_f32_e32 v29, v14, v9
	v_and_b32_e32 v5, 0xffff0000, v5
	v_fmac_f32_e32 v29, v12, v4
	v_fmac_f32_e32 v29, v17, v5
	v_fmac_f32_e32 v26, v17, v4
	v_add_f32_e32 v4, v13, v29
	v_mul_f32_e32 v29, v14, v5
	v_lshlrev_b32_e32 v27, 16, v6
	v_fmac_f32_e32 v29, v12, v9
	v_fmac_f32_e32 v29, v17, v27
	v_add_f32_e32 v9, v13, v29
	v_mul_f32_e32 v29, v14, v27
	v_and_b32_e32 v6, 0xffff0000, v6
	v_fmac_f32_e32 v29, v12, v5
	v_fmac_f32_e32 v29, v17, v6
	v_add_f32_e32 v5, v13, v29
	v_mul_f32_e32 v29, v14, v6
	v_lshlrev_b32_e32 v28, 16, v7
	v_fmac_f32_e32 v29, v12, v27
	v_fmac_f32_e32 v29, v17, v28
	v_add_f32_e32 v27, v13, v29
	v_mul_f32_e32 v29, v14, v28
	v_and_b32_e32 v7, 0xffff0000, v7
	v_fmac_f32_e32 v29, v12, v6
	v_fmac_f32_e32 v29, v17, v7
	v_mul_f32_e32 v7, v14, v7
	v_fmac_f32_e32 v7, v12, v28
	v_fmac_f32_e32 v7, v17, v24
	v_lshlrev_b32_e32 v24, 16, v0
	v_and_b32_e32 v0, 0xffff0000, v0
	v_mul_f32_e32 v31, v10, v0
	v_lshlrev_b32_e32 v28, 16, v1
	v_fmac_f32_e32 v31, v15, v24
	v_mul_f32_e32 v25, v15, v25
	v_fmac_f32_e32 v31, v11, v28
	v_and_b32_e32 v1, 0xffff0000, v1
	v_fmac_f32_e32 v25, v10, v24
	v_add_f32_e32 v24, v16, v31
	v_mul_f32_e32 v31, v10, v28
	v_fmac_f32_e32 v25, v11, v0
	v_fmac_f32_e32 v31, v15, v0
	v_mul_f32_e32 v0, v10, v1
	v_add_f32_e32 v6, v13, v29
	v_lshlrev_b32_e32 v29, 16, v2
	v_fmac_f32_e32 v0, v15, v28
	v_fmac_f32_e32 v0, v11, v29
	v_add_f32_e32 v28, v16, v0
	v_mul_f32_e32 v0, v10, v29
	v_and_b32_e32 v2, 0xffff0000, v2
	v_fmac_f32_e32 v0, v15, v1
	v_fmac_f32_e32 v0, v11, v2
	v_add_f32_e32 v32, v16, v0
	v_mul_f32_e32 v0, v10, v2
	v_lshlrev_b32_e32 v30, 16, v3
	v_fmac_f32_e32 v0, v15, v29
	v_fmac_f32_e32 v0, v11, v30
	v_add_f32_e32 v29, v16, v0
	v_mul_f32_e32 v0, v10, v30
	v_and_b32_e32 v3, 0xffff0000, v3
	v_fmac_f32_e32 v0, v15, v2
	v_fmac_f32_e32 v0, v11, v3
	v_add_f32_e32 v33, v16, v0
	v_mul_f32_e32 v0, v10, v3
	v_fmac_f32_e32 v0, v15, v30
	v_add_f32_e32 v26, v13, v26
	v_add_f32_e32 v25, v16, v25
	v_fmac_f32_e32 v31, v11, v1
	v_fmac_f32_e32 v0, v11, v23
	v_add_f32_e32 v31, v16, v31
	v_add_f32_e32 v3, v16, v0
	v_mul_f32_e32 v0, v26, v25
	v_mul_f32_e32 v1, v8, v24
	s_nop 0
	v_cvt_pk_bf16_f32 v0, v0, v1
	v_mul_f32_e32 v1, v4, v31
	v_mul_f32_e32 v2, v9, v28
	v_add_f32_e32 v7, v13, v7
	s_nop 0
	v_cvt_pk_bf16_f32 v1, v1, v2
	v_mul_f32_e32 v2, v5, v32
	v_mul_f32_e32 v4, v27, v29
	s_nop 0
	v_cvt_pk_bf16_f32 v2, v2, v4
	v_mul_f32_e32 v4, v6, v33
	v_mul_f32_e32 v3, v7, v3
	s_nop 0
	v_cvt_pk_bf16_f32 v3, v4, v3
	v_and_b32_e32 v4, 0xfe, v18
	v_add_u32_e32 v4, v4, v22
	v_mul_u32_u24_e32 v4, 0x90, v4
	v_and_b32_e32 v5, 0x70, v20
	v_add3_u32 v4, s27, v4, v5
	s_movk_i32 s0, 0x6ff
	ds_write_b128 v4, v[0:3]
	v_add_u32_e32 v0, 0x100, v21
	v_cmp_lt_u32_e32 vcc, s0, v21
	v_add_u32_e32 v20, 0x1000, v20
	v_add_u32_e32 v18, 64, v18
	v_add_u32_e32 v19, 0x800, v19
	s_or_b64 s[10:11], vcc, s[10:11]
	v_mov_b32_e32 v21, v0
	s_andn2_b64 exec, exec, s[10:11]
	s_cbranch_execz .LBB0_748
	s_branch .LhyA_top

; DEV float bf2f(u16 h) { return __uint_as_float(((unsigned)h) << 16); }
; DEV float bflo(unsigned w) { return __uint_as_float(w << 16); }
; DEV float bfhi(unsigned w) { return __uint_as_float(w & 0xffff0000u); }
; DEV F8 conv8(const u16* __restrict__ row, int t, int L, float w0, float w1, float w2, float bb) {
;   const uint4 u = *(const uint4*)(row + t);
;   const float um = (t > 0) ? bf2f(row[t - 1]) : 0.f;
;   const float up = (t + 8 < L) ? bf2f(row[t + 8]) : 0.f;
;   float x[10];
;   x[0] = um;
;   x[1] = bflo(u.x); x[2] = bfhi(u.x); x[3] = bflo(u.y); x[4] = bfhi(u.y);
;   x[5] = bflo(u.z); x[6] = bfhi(u.z); x[7] = bflo(u.w); x[8] = bfhi(u.w);
;   x[9] = up;
; template <int BG>
; DEV void hyena_item_mfma(const Params& p, int g, int item, char* smem, int half) {
;     ...
;   {
;     const float wx1_0 = cw[0 * 1536 + 512 + c], wx1_1 = cw[1 * 1536 + 512 + c], wx1_2 = cw[2 * 1536 + 512 + c], bx1 = cb[512 + c];
;     const float wv_0 = cw[0 * 1536 + 1024 + c], wv_1 = cw[1 * 1536 + 1024 + c], wv_2 = cw[2 * 1536 + 1024 + c], bv = cb[1024 + c];
; #pragma unroll 4
;     for (int e = tid; e < BG * L / 8; e += 256) {
;       const int bl = e / (L / 8), t = (e % (L / 8)) * 8;
;       const int b = bgi * BG + bl;
;       const F8 a = conv8(UHY + ((size_t)b * 1536 + 1024 + c) * L, t, L, wv_0, wv_1, wv_2, bv);
;       const F8 x = conv8(UHY + ((size_t)b * 1536 + 512 + c) * L, t, L, wx1_0, wx1_1, wx1_2, bx1);
.LBB0_778:
	v_readlane_b32 s36, v249, 32
	v_readlane_b32 s37, v249, 33
	s_lshl_b64 s[24:25], s[18:19], 2
	v_readlane_b32 s38, v249, 34
	v_readlane_b32 s39, v249, 35
	s_mov_b64 s[8:9], s[36:37]
	s_add_u32 s20, s8, s24
	s_mov_b64 s[10:11], s[38:39]
	s_addc_u32 s21, s9, s25
	s_add_u32 s22, s10, s24
	s_addc_u32 s23, s11, s25
	global_load_dword v10, v208, s[20:21]
	global_load_dword v11, v209, s[20:21] offset:2048
	global_load_dword v12, v210, s[20:21]
	global_load_dword v13, v210, s[22:23]
	global_load_dword v14, v208, s[20:21] offset:2048
	global_load_dword v15, v165, s[20:21] offset:2048
	global_load_dword v16, v165, s[22:23] offset:2048
	global_load_dword v17, v211, s[20:21]
	s_lshl_b32 s0, s35, 2
	s_and_b32 s35, s0, 4
	s_add_u32 s4, s18, 0x400
	s_addc_u32 s5, s19, 0
	s_add_u32 s8, s18, 0x200
	s_addc_u32 s9, s19, 0
	v_lshrrev_b32_e32 v18, 1, v148
	s_mov_b64 s[10:11], 0
	v_mov_b32_e32 v19, v146
	v_mov_b32_e32 v20, v144
	v_mov_b32_e32 v21, v148
	v_readlane_b32 s40, v249, 36
	v_readlane_b32 s41, v249, 37
	v_readlane_b32 s42, v249, 38
	v_readlane_b32 s43, v249, 39
	v_readlane_b32 s44, v249, 40
	v_readlane_b32 s45, v249, 41
	v_readlane_b32 s46, v249, 42
	v_readlane_b32 s47, v249, 43
	v_readlane_b32 s48, v249, 44
	v_readlane_b32 s49, v249, 45
	v_readlane_b32 s50, v249, 46
	v_readlane_b32 s51, v249, 47
	s_mov_b32 s100, 0
	v_lshrrev_b32_e32 v52, 9, v21
	v_add_u32_e32 v52, s35, v52
	v_mul_u32_u24_e32 v52, 0x600, v52
	v_mov_b32_e32 v53, 0
	v_lshl_add_u64 v[54:55], s[4:5], 0, v[52:53]
	v_lshlrev_b64 v[54:55], 13, v[54:55]
	v_lshl_add_u64 v[54:55], s[74:75], 0, v[54:55]
	v_and_b32_e32 v56, 0xff8, v19
	v_lshlrev_b32_e32 v58, 1, v56
	v_mov_b32_e32 v59, 0
	v_lshl_add_u64 v[54:55], v[54:55], 0, v[58:59]
	global_load_dwordx4 v[40:43], v[54:55], off
	v_cmp_ne_u32_e32 vcc, 0, v56
	s_movk_i32 s0, 0xff8
	v_cmp_ne_u32_e64 s[0:1], s0, v56
	v_mov_b32_e32 v48, 0
	v_mov_b32_e32 v49, 0
	v_mov_b32_e32 v50, 0
	v_mov_b32_e32 v51, 0
	s_and_saveexec_b64 s[12:13], vcc
	global_load_ushort v48, v[54:55], off offset:-2
	s_mov_b64 exec, s[12:13]
	s_and_saveexec_b64 s[12:13], s[0:1]
	global_load_ushort v49, v[54:55], off offset:16
	s_mov_b64 exec, s[12:13]
	v_lshl_add_u64 v[54:55], s[8:9], 0, v[52:53]
	v_lshlrev_b64 v[54:55], 13, v[54:55]
	v_lshl_add_u64 v[54:55], s[74:75], 0, v[54:55]
	v_lshl_add_u64 v[54:55], v[54:55], 0, v[58:59]
	global_load_dwordx4 v[44:47], v[54:55], off
	s_and_saveexec_b64 s[12:13], vcc
	global_load_ushort v50, v[54:55], off offset:-2
	s_mov_b64 exec, s[12:13]
	s_and_saveexec_b64 s[12:13], s[0:1]
	global_load_ushort v51, v[54:55], off offset:16
	s_mov_b64 exec, s[12:13]
.LhyB_top:
	s_waitcnt vmcnt(0)
	v_mov_b32_e32 v4, v40
	v_mov_b32_e32 v5, v41
	v_mov_b32_e32 v6, v42
	v_mov_b32_e32 v7, v43
	v_mov_b32_e32 v0, v44
	v_mov_b32_e32 v1, v45
	v_mov_b32_e32 v2, v46
	v_mov_b32_e32 v3, v47
	v_lshlrev_b32_e32 v26, 16, v48
	v_lshlrev_b32_e32 v24, 16, v49
	v_lshlrev_b32_e32 v25, 16, v50
	v_lshlrev_b32_e32 v23, 16, v51
	v_lshrrev_b32_e32 v22, 9, v21
	s_cmp_lt_u32 s100, 7
	s_cbranch_scc0 .LhyB_nonext
	v_add_u32_e32 v60, 0x100, v21
	v_add_u32_e32 v61, 0x800, v19
	v_lshrrev_b32_e32 v52, 9, v60
	v_add_u32_e32 v52, s35, v52
	v_mul_u32_u24_e32 v52, 0x600, v52
	v_mov_b32_e32 v53, 0
	v_lshl_add_u64 v[54:55], s[4:5], 0, v[52:53]
	v_lshlrev_b64 v[54:55], 13, v[54:55]
	v_lshl_add_u64 v[54:55], s[74:75], 0, v[54:55]
	v_and_b32_e32 v56, 0xff8, v61
	v_lshlrev_b32_e32 v58, 1, v56
	v_mov_b32_e32 v59, 0
	v_lshl_add_u64 v[54:55], v[54:55], 0, v[58:59]
	global_load_dwordx4 v[40:43], v[54:55], off
	v_cmp_ne_u32_e32 vcc, 0, v56
	s_movk_i32 s0, 0xff8
	v_cmp_ne_u32_e64 s[0:1], s0, v56
	v_mov_b32_e32 v48, 0
	v_mov_b32_e32 v49, 0
	v_mov_b32_e32 v50, 0
	v_mov_b32_e32 v51, 0
	s_and_saveexec_b64 s[12:13], vcc
	global_load_ushort v48, v[54:55], off offset:-2
	s_mov_b64 exec, s[12:13]
	s_and_saveexec_b64 s[12:13], s[0:1]
	global_load_ushort v49, v[54:55], off offset:16
	s_mov_b64 exec, s[12:13]
	v_lshl_add_u64 v[54:55], s[8:9], 0, v[52:53]
	v_lshlrev_b64 v[54:55], 13, v[54:55]
	v_lshl_add_u64 v[54:55], s[74:75], 0, v[54:55]
	v_lshl_add_u64 v[54:55], v[54:55], 0, v[58:59]
	global_load_dwordx4 v[44:47], v[54:55], off
	s_and_saveexec_b64 s[12:13], vcc
	global_load_ushort v50, v[54:55], off offset:-2
	s_mov_b64 exec, s[12:13]
	s_and_saveexec_b64 s[12:13], s[0:1]
	global_load_ushort v51, v[54:55], off offset:16
	s_mov_b64 exec, s[12:13]
; DEV float bf2f(u16 h) { return __uint_as_float(((unsigned)h) << 16); }
; DEV float bflo(unsigned w) { return __uint_as_float(w << 16); }
; DEV float bfhi(unsigned w) { return __uint_as_float(w & 0xffff0000u); }
; DEV F8 conv8(const u16* __restrict__ row, int t, int L, float w0, float w1, float w2, float bb) {
;   const uint4 u = *(const uint4*)(row + t);
;   const float um = (t > 0) ? bf2f(row[t - 1]) : 0.f;
;   const float up = (t + 8 < L) ? bf2f(row[t + 8]) : 0.f;
;   float x[10];
;   x[0] = um;
;   x[1] = bflo(u.x); x[2] = bfhi(u.x); x[3] = bflo(u.y); x[4] = bfhi(u.y);
;   x[5] = bflo(u.z); x[6] = bfhi(u.z); x[7] = bflo(u.w); x[8] = bfhi(u.w);
;   x[9] = up;
;   F8 o;
; #pragma unroll
;   for (int j = 0; j < 8; ++j) o.v[j] = x[j] * w0 + x[j + 1] * w1 + x[j + 2] * w2 + bb;
;   return o;
; template <int BG>
; DEV void hyena_item_mfma(const Params& p, int g, int item, char* smem, int half) {
;     ...
;     for (int e = tid; e < BG * L / 8; e += 256) {
;       const int bl = e / (L / 8), t = (e % (L / 8)) * 8;
;       const int b = bgi * BG + bl;
;       const F8 a = conv8(UHY + ((size_t)b * 1536 + 1024 + c) * L, t, L, wv_0, wv_1, wv_2, bv);
;       const F8 x = conv8(UHY + ((size_t)b * 1536 + 512 + c) * L, t, L, wx1_0, wx1_1, wx1_2, bx1);
;       *(uint4*)(Vl + ((t >> 6) * BG + bl) * VROW + (t & 63) * 2) =
;           make_uint4(pack2(a.v[0] * x.v[0], a.v[1] * x.v[1]), pack2(a.v[2] * x.v[2], a.v[3] * x.v[3]),
;                      pack2(a.v[4] * x.v[4], a.v[5] * x.v[5]), pack2(a.v[6] * x.v[6], a.v[7] * x.v[7]));
.LhyB_nonext:
	s_add_u32 s100, s100, 1
	v_lshlrev_b32_e32 v8, 16, v4
	v_and_b32_e32 v4, 0xffff0000, v4
	v_mul_f32_e32 v29, v14, v4
	v_lshlrev_b32_e32 v9, 16, v5
	v_fmac_f32_e32 v29, v12, v8
	v_mul_f32_e32 v26, v12, v26
	v_fmac_f32_e32 v29, v17, v9
	v_fmac_f32_e32 v26, v14, v8
	v_add_f32_e32 v8, v13, v29
	v_mul_f32_e32 v29, v14, v9
	v_and_b32_e32 v5, 0xffff0000, v5
	v_fmac_f32_e32 v29, v12, v4
	v_fmac_f32_e32 v29, v17, v5
	v_fmac_f32_e32 v26, v17, v4
	v_add_f32_e32 v4, v13, v29
	v_mul_f32_e32 v29, v14, v5
	v_lshlrev_b32_e32 v27, 16, v6
	v_fmac_f32_e32 v29, v12, v9
	v_fmac_f32_e32 v29, v17, v27
	v_add_f32_e32 v9, v13, v29
	v_mul_f32_e32 v29, v14, v27
	v_and_b32_e32 v6, 0xffff0000, v6
	v_fmac_f32_e32 v29, v12, v5
	v_fmac_f32_e32 v29, v17, v6
	v_add_f32_e32 v5, v13, v29
	v_mul_f32_e32 v29, v14, v6
	v_lshlrev_b32_e32 v28, 16, v7
	v_fmac_f32_e32 v29, v12, v27
	v_fmac_f32_e32 v29, v17, v28
	v_add_f32_e32 v27, v13, v29
	v_mul_f32_e32 v29, v14, v28
	v_and_b32_e32 v7, 0xffff0000, v7
	v_fmac_f32_e32 v29, v12, v6
	v_fmac_f32_e32 v29, v17, v7
	v_mul_f32_e32 v7, v14, v7
	v_fmac_f32_e32 v7, v12, v28
	v_fmac_f32_e32 v7, v17, v24
	v_lshlrev_b32_e32 v24, 16, v0
	v_and_b32_e32 v0, 0xffff0000, v0
	v_mul_f32_e32 v31, v10, v0
	v_lshlrev_b32_e32 v28, 16, v1
	v_fmac_f32_e32 v31, v15, v24
	v_mul_f32_e32 v25, v15, v25
	v_fmac_f32_e32 v31, v11, v28
	v_and_b32_e32 v1, 0xffff0000, v1
	v_fmac_f32_e32 v25, v10, v24
	v_add_f32_e32 v24, v16, v31
	v_mul_f32_e32 v31, v10, v28
	v_fmac_f32_e32 v25, v11, v0
	v_fmac_f32_e32 v31, v15, v0
	v_mul_f32_e32 v0, v10, v1
	v_add_f32_e32 v6, v13, v29
	v_lshlrev_b32_e32 v29, 16, v2
	v_fmac_f32_e32 v0, v15, v28
	v_fmac_f32_e32 v0, v11, v29
	v_add_f32_e32 v28, v16, v0
	v_mul_f32_e32 v0, v10, v29
	v_and_b32_e32 v2, 0xffff0000, v2
	v_fmac_f32_e32 v0, v15, v1
	v_fmac_f32_e32 v0, v11, v2
	v_add_f32_e32 v32, v16, v0
	v_mul_f32_e32 v0, v10, v2
	v_lshlrev_b32_e32 v30, 16, v3
	v_fmac_f32_e32 v0, v15, v29
	v_fmac_f32_e32 v0, v11, v30
	v_add_f32_e32 v29, v16, v0
	v_mul_f32_e32 v0, v10, v30
	v_and_b32_e32 v3, 0xffff0000, v3
	v_fmac_f32_e32 v0, v15, v2
	v_fmac_f32_e32 v0, v11, v3
	v_add_f32_e32 v33, v16, v0
	v_mul_f32_e32 v0, v10, v3
	v_fmac_f32_e32 v0, v15, v30
	v_add_f32_e32 v26, v13, v26
	v_add_f32_e32 v25, v16, v25
	v_fmac_f32_e32 v31, v11, v1
	v_fmac_f32_e32 v0, v11, v23
	v_add_f32_e32 v31, v16, v31
	v_add_f32_e32 v3, v16, v0
	v_mul_f32_e32 v0, v26, v25
	v_mul_f32_e32 v1, v8, v24
	s_nop 0
	v_cvt_pk_bf16_f32 v0, v0, v1
	v_mul_f32_e32 v1, v4, v31
	v_mul_f32_e32 v2, v9, v28
	v_add_f32_e32 v7, v13, v7
	s_nop 0
	v_cvt_pk_bf16_f32 v1, v1, v2
	v_mul_f32_e32 v2, v5, v32
	v_mul_f32_e32 v4, v27, v29
	s_nop 0
	v_cvt_pk_bf16_f32 v2, v2, v4
	v_mul_f32_e32 v4, v6, v33
	v_mul_f32_e32 v3, v7, v3
	s_nop 0
	v_cvt_pk_bf16_f32 v3, v4, v3
	v_and_b32_e32 v4, 0xfc, v18
	v_add_u32_e32 v4, v4, v22
	v_mul_u32_u24_e32 v4, 0x90, v4
	v_and_b32_e32 v5, 0x70, v20
	v_add3_u32 v4, s15, v4, v5
	s_movk_i32 s0, 0x6ff
	ds_write_b128 v4, v[0:3] offset:32896
	v_add_u32_e32 v0, 0x100, v21
	v_cmp_lt_u32_e32 vcc, s0, v21
	v_add_u32_e32 v20, 0x1000, v20
	v_add_u32_e32 v18, 0x80, v18
	v_add_u32_e32 v19, 0x800, v19
	s_or_b64 s[10:11], vcc, s[10:11]
	v_mov_b32_e32 v21, v0
	s_andn2_b64 exec, exec, s[10:11]
	s_cbranch_execz .LBB0_788
	s_branch .LhyB_top

; DEV void phase_p3a(const Params& p, int g, char* smem) {
;     ...
;   for (int iter = 0;; ++iter) {
;     int mt, nt;
;     if (!tile_map(iter, 128, 4, mt, nt)) break;
;     const int m0 = mt * 256, n0 = nt * 256;
;     Acc acc;
;     acc_zero(acc);
;     {
;       TransLoader al{UHY, L};
;       RowLoader bl{WbrT, 1024};
;       gemm_mainloop(acc, al, bl, m0, n0, 0, 512, smem);
.LBB0_937:
	s_lshl_b32 s3, s5, 8
	s_lshl_b32 s2, s6, 8
	v_readlane_b32 s11, v252, 18
	v_readlane_b32 s6, v251, 16
	v_readlane_b32 s7, v251, 17
	v_readlane_b32 s12, v249, 48
	v_readlane_b32 s13, v249, 49
	s_lshr_b32 s0, s3, s11
	s_lshl_b32 s1, s0, s11
	s_sub_u32 s1, s3, s1
	s_mulk_i32 s0, 0x600
	s_addk_i32 s0, 0x400
	s_add_u32 s11, s11, 1
	s_lshl_b32 s0, s0, s11
	s_lshl_b32 s1, s1, 1
	s_add_u32 s0, s0, s1
	s_add_u32 s0, s74, s0
	s_addc_u32 s1, s75, 0
	s_lshl_b32 s10, 64, s11
	v_lshrrev_b32_e32 v149, 6, v202
	v_and_b32_e32 v148, 63, v202
	s_nop 0
	v_readfirstlane_b32 s5, v149
	v_lshrrev_b32_e32 v150, 3, v148
	v_lshl_add_u32 v150, v149, 5, v150
	v_and_b32_e32 v151, 7, v148
	v_lshrrev_b32_e32 v128, 4, v148
	v_xor_b32_e32 v151, v128, v151
	v_lshlrev_b32_e32 v151, 4, v151
	s_mul_i32 s9, s5, 0x2300
	s_lshl_b32 s5, s5, 12
	v_add_u32_e32 v132, s2, v150
	v_lshlrev_b32_e32 v132, 11, v132
	v_add_u32_e32 v132, v132, v151
	v_add_u32_e32 v133, 0x3c00, v132
	v_add_u32_e32 v134, 0x7800, v132
	v_add_u32_e32 v135, 0xb400, v132
	v_xor_b32_e32 v133, 0x40, v133
	v_xor_b32_e32 v135, 0x40, v135
	v_add_u32_e32 v140, 0x40000, v132
	v_add_u32_e32 v141, 0x40000, v133
	v_add_u32_e32 v142, 0x40000, v134
	v_add_u32_e32 v143, 0x40000, v135
	v_lshrrev_b32_e32 v164, 5, v148
	v_bfe_u32 v242, v148, 1, 4
	v_xor_b32_e32 v242, v242, v164
	v_lshlrev_b32_e32 v242, 1, v242
	v_and_b32_e32 v128, 1, v148
	v_or_b32_e32 v242, v242, v128
	v_lshlrev_b32_e32 v242, 4, v242
	v_lshl_add_u32 v164, v149, 4, v164
	v_lshlrev_b32_e32 v164, s11, v164
	v_add_u32_e32 v128, v164, v242
	s_lshl_b32 s8, 2, s11
	v_add_u32_e32 v129, s8, v128
	v_add_u32_e32 v130, s8, v129
	v_add_u32_e32 v131, s8, v130
	v_add_u32_e32 v136, s8, v131
	v_add_u32_e32 v137, s8, v136
	v_add_u32_e32 v138, s8, v137
	v_add_u32_e32 v139, s8, v138
	v_add_u32_e32 v129, 0xfffffbc0, v129
	v_add_u32_e32 v130, 0xfffff780, v130
	v_add_u32_e32 v131, 0xfffff340, v131
	v_add_u32_e32 v137, 0xfffffbc0, v137
	v_add_u32_e32 v138, 0xfffff780, v138
	v_add_u32_e32 v139, 0xfffff340, v139
	v_lshrrev_b32_e32 v242, 6, v202
	v_and_b32_e32 v164, 63, v202
	v_bfe_u32 v243, v164, 1, 3
	v_lshrrev_b32_e32 v244, 4, v164
	v_xor_b32_e32 v243, v243, v244
	v_lshlrev_b32_e32 v243, 4, v243
	v_and_b32_e32 v244, 15, v164
	v_lshlrev_b32_e32 v244, 7, v244
	v_lshrrev_b32_e32 v144, 2, v242
	v_lshl_add_u32 v144, v144, 14, v244
	v_and_b32_e32 v146, 3, v242
	v_lshl_add_u32 v146, v146, 13, v244
	v_add_u32_e32 v146, 0x10000, v146
	v_xor_b32_e32 v145, 0x40, v243
	v_add_u32_e32 v145, v144, v145
	v_add_u32_e32 v144, v144, v243
	v_xor_b32_e32 v147, 0x40, v243
	v_add_u32_e32 v147, v146, v147
	v_add_u32_e32 v146, v146, v243
	v_lshrrev_b32_e32 v164, 4, v148
	v_bfe_u32 v242, v148, 2, 2
	v_lshrrev_b32_e32 v243, 1, v242
	v_mul_u32_u24_e32 v244, 0x1180, v164
	v_mul_u32_u24_e32 v243, 0x440, v243
	v_add_u32_e32 v244, v244, v243
	v_and_b32_e32 v243, 1, v242
	v_lshl_add_u32 v244, v243, 9, v244
	v_and_b32_e32 v164, 3, v148
	v_lshl_add_u32 v244, v164, 3, v244
	v_lshrrev_b32_e32 v164, 2, v149
	v_lshl_add_u32 v244, v164, 8, v244
	v_lshl_add_u32 v160, v243, 5, v244
	v_xor_b32_e32 v243, 1, v243
	v_lshl_add_u32 v161, v243, 5, v244
	s_cmp_lt_u32 s5, 0x4000
	s_cbranch_scc0 .Lp3a_t1
	s_add_u32 m0, s9, 0x0
	s_nop 0
	global_load_lds_dwordx4 v128, s[0:1]
	global_load_lds_dwordx4 v129, s[0:1] offset:1088
	global_load_lds_dwordx4 v130, s[0:1] offset:2176
	global_load_lds_dwordx4 v131, s[0:1] offset:3264
	s_add_u32 m0, s9, 0x1180
	s_nop 0
	global_load_lds_dwordx4 v136, s[0:1]
	global_load_lds_dwordx4 v137, s[0:1] offset:1088
	global_load_lds_dwordx4 v138, s[0:1] offset:2176
	global_load_lds_dwordx4 v139, s[0:1] offset:3264
	s_add_u32 m0, s5, 0x11800
	s_nop 0
	global_load_lds_dwordx4 v132, s[6:7]
	global_load_lds_dwordx4 v133, s[6:7] offset:1024
	global_load_lds_dwordx4 v134, s[6:7] offset:2048
	global_load_lds_dwordx4 v135, s[6:7] offset:3072
	s_add_u32 m0, s5, 0x15800
	s_nop 0
	global_load_lds_dwordx4 v140, s[6:7]
	global_load_lds_dwordx4 v141, s[6:7] offset:1024
	global_load_lds_dwordx4 v142, s[6:7] offset:2048
	global_load_lds_dwordx4 v143, s[6:7] offset:3072

; template <class AL, class BL>
; DEV void gemm_ktile(Acc& acc, const char* A, const char* B, int wm, int wn, int lr, int lh, const AL& al, const BL& bl,
;                     int tid, int m0, int n0, int knext, char* nxt, R4& ra, R4& rb) {
;   bf16x8 a[2][4], b[2][2];
;   const char* pa = A + (wm + lr) * LDSROW + lh * 16;
;   const char* pb = B + (wn + lr) * LDSROW + lh * 16;
; #pragma unroll
;   for (int i = 0; i < 4; ++i) a[0][i] = *(const bf16x8*)(pa + 32 * i * LDSROW);
; #pragma unroll
;   for (int j = 0; j < 2; ++j) b[0][j] = *(const bf16x8*)(pb + 32 * j * LDSROW);
; #pragma unroll
;   for (int ks = 0; ks < 4; ++ks) {
;     const int cur = ks & 1, nx = cur ^ 1;
;     if (ks < 3) {
; #pragma unroll
;       for (int i = 0; i < 4; ++i) a[nx][i] = *(const bf16x8*)(pa + 32 * i * LDSROW + (ks + 1) * 32);
; #pragma unroll
;       for (int j = 0; j < 2; ++j) b[nx][j] = *(const bf16x8*)(pb + 32 * j * LDSROW + (ks + 1) * 32);
;     }
;     __builtin_amdgcn_sched_barrier(0);
; #pragma unroll
;     for (int i = 0; i < 4; ++i)
; #pragma unroll
;       for (int j = 0; j < 2; ++j)
;         acc[i][j] = __builtin_amdgcn_mfma_f32_32x32x16_bf16(a[cur][i], b[cur][j], acc[i][j], 0, 0, 0);
; DEV void phase_p3a(const Params& p, int g, char* smem) {
;     ...
;       TransLoader al{UHY, L};
;       RowLoader bl{WbrT, 1024};
;       gemm_mainloop(acc, al, bl, m0, n0, 0, 512, smem);
.Lp3a_k1loop:
	s_cmp_lt_u32 s5, 0x4000
	s_cbranch_scc0 .Lp3a_t2
	s_add_u32 m0, s9, 0x8c00
	s_nop 0
	global_load_lds_dwordx4 v128, s[0:1]
	global_load_lds_dwordx4 v129, s[0:1] offset:1088
	global_load_lds_dwordx4 v130, s[0:1] offset:2176
	global_load_lds_dwordx4 v131, s[0:1] offset:3264
	s_add_u32 m0, s9, 0x9d80
	s_nop 0
	global_load_lds_dwordx4 v136, s[0:1]
	global_load_lds_dwordx4 v137, s[0:1] offset:1088
	global_load_lds_dwordx4 v138, s[0:1] offset:2176
	global_load_lds_dwordx4 v139, s[0:1] offset:3264
	s_add_u32 m0, s5, 0x19800
	s_nop 0
	global_load_lds_dwordx4 v132, s[6:7]
	global_load_lds_dwordx4 v133, s[6:7] offset:1024
	global_load_lds_dwordx4 v134, s[6:7] offset:2048
	global_load_lds_dwordx4 v135, s[6:7] offset:3072
	s_add_u32 m0, s5, 0x1d800
	s_nop 0
	global_load_lds_dwordx4 v140, s[6:7]
	global_load_lds_dwordx4 v141, s[6:7] offset:1024
	global_load_lds_dwordx4 v142, s[6:7] offset:2048
	global_load_lds_dwordx4 v143, s[6:7] offset:3072
.Lp3a_t2:
	s_add_u32 s0, s0, s10
	s_addc_u32 s1, s1, 0
	s_add_u32 s6, s6, 0x80
	s_addc_u32 s7, s7, 0
	ds_read_b128 v[166:169], v146 offset:6144
	ds_read_b128 v[170:173], v146 offset:8192
	ds_read_b128 v[174:177], v146 offset:10240
	ds_read_b128 v[178:181], v146 offset:12288
	ds_read_b64_tr_b16 v[222:223], v160 offset:0
	ds_read_b64_tr_b16 v[224:225], v160 offset:2176
	ds_read_b64_tr_b16 v[226:227], v161 offset:0
	ds_read_b64_tr_b16 v[228:229], v161 offset:2176
	ds_read_b64_tr_b16 v[230:231], v160 offset:64
	ds_read_b64_tr_b16 v[232:233], v160 offset:2240
	ds_read_b64_tr_b16 v[234:235], v161 offset:64
	ds_read_b64_tr_b16 v[236:237], v161 offset:2240
	ds_read_b64_tr_b16 v[238:239], v160 offset:128
	ds_read_b64_tr_b16 v[240:241], v160 offset:2304
	ds_read_b64_tr_b16 v[198:199], v161 offset:128
	ds_read_b64_tr_b16 v[200:201], v161 offset:2304
	ds_read_b64_tr_b16 v[152:153], v160 offset:192
	ds_read_b64_tr_b16 v[154:155], v160 offset:2368
	ds_read_b64_tr_b16 v[156:157], v161 offset:192
	ds_read_b64_tr_b16 v[158:159], v161 offset:2368
	ds_read_b128 v[182:185], v147 offset:6144
	ds_read_b128 v[186:189], v147 offset:8192
	ds_read_b128 v[190:193], v147 offset:10240
	ds_read_b128 v[194:197], v147 offset:12288
	s_waitcnt lgkmcnt(12)
	v_mfma_f32_16x16x32_bf16 v[0:3], v[166:169], v[222:225], v[0:3]
	v_mfma_f32_16x16x32_bf16 v[4:7], v[170:173], v[222:225], v[4:7]
	v_mfma_f32_16x16x32_bf16 v[8:11], v[174:177], v[222:225], v[8:11]
	v_mfma_f32_16x16x32_bf16 v[12:15], v[178:181], v[222:225], v[12:15]
	v_mfma_f32_16x16x32_bf16 v[16:19], v[166:169], v[226:229], v[16:19]
	v_mfma_f32_16x16x32_bf16 v[20:23], v[170:173], v[226:229], v[20:23]
	v_mfma_f32_16x16x32_bf16 v[24:27], v[174:177], v[226:229], v[24:27]
	v_mfma_f32_16x16x32_bf16 v[28:31], v[178:181], v[226:229], v[28:31]
	v_mfma_f32_16x16x32_bf16 v[32:35], v[166:169], v[230:233], v[32:35]
	v_mfma_f32_16x16x32_bf16 v[36:39], v[170:173], v[230:233], v[36:39]
	v_mfma_f32_16x16x32_bf16 v[40:43], v[174:177], v[230:233], v[40:43]
	v_mfma_f32_16x16x32_bf16 v[44:47], v[178:181], v[230:233], v[44:47]
	v_mfma_f32_16x16x32_bf16 v[48:51], v[166:169], v[234:237], v[48:51]
	v_mfma_f32_16x16x32_bf16 v[52:55], v[170:173], v[234:237], v[52:55]
	v_mfma_f32_16x16x32_bf16 v[56:59], v[174:177], v[234:237], v[56:59]
	v_mfma_f32_16x16x32_bf16 v[60:63], v[178:181], v[234:237], v[60:63]
	ds_read_b64_tr_b16 v[222:223], v160 offset:17920
	ds_read_b64_tr_b16 v[224:225], v160 offset:20096
	ds_read_b64_tr_b16 v[226:227], v161 offset:17920
	ds_read_b64_tr_b16 v[228:229], v161 offset:20096
	ds_read_b64_tr_b16 v[230:231], v160 offset:17984
	ds_read_b64_tr_b16 v[232:233], v160 offset:20160
	ds_read_b64_tr_b16 v[234:235], v161 offset:17984
	ds_read_b64_tr_b16 v[236:237], v161 offset:20160
	s_waitcnt lgkmcnt(12)
; template <class AL, class BL>
; DEV void gemm_ktile(Acc& acc, const char* A, const char* B, int wm, int wn, int lr, int lh, const AL& al, const BL& bl,
;                     int tid, int m0, int n0, int knext, char* nxt, R4& ra, R4& rb) {
;   bf16x8 a[2][4], b[2][2];
;   const char* pa = A + (wm + lr) * LDSROW + lh * 16;
;   const char* pb = B + (wn + lr) * LDSROW + lh * 16;
; #pragma unroll
;   for (int i = 0; i < 4; ++i) a[0][i] = *(const bf16x8*)(pa + 32 * i * LDSROW);
; #pragma unroll
;   for (int j = 0; j < 2; ++j) b[0][j] = *(const bf16x8*)(pb + 32 * j * LDSROW);
; #pragma unroll
;   for (int ks = 0; ks < 4; ++ks) {
;     const int cur = ks & 1, nx = cur ^ 1;
;     if (ks < 3) {
; #pragma unroll
;       for (int i = 0; i < 4; ++i) a[nx][i] = *(const bf16x8*)(pa + 32 * i * LDSROW + (ks + 1) * 32);
; #pragma unroll
;       for (int j = 0; j < 2; ++j) b[nx][j] = *(const bf16x8*)(pb + 32 * j * LDSROW + (ks + 1) * 32);
;     }
;     __builtin_amdgcn_sched_barrier(0);
; #pragma unroll
;     for (int i = 0; i < 4; ++i)
; #pragma unroll
;       for (int j = 0; j < 2; ++j)
;         acc[i][j] = __builtin_amdgcn_mfma_f32_32x32x16_bf16(a[cur][i], b[cur][j], acc[i][j], 0, 0, 0);
;     __builtin_amdgcn_sched_barrier(0);
;     if (ks == 1) {
;       al.store(tid, nxt, ra);
;       bl.store(tid, nxt + TILE_BYTES, rb);
;       __builtin_amdgcn_sched_barrier(0);
;       ra = al.load(tid, m0, knext);
;       rb = bl.load(tid, n0, knext);
;       __builtin_amdgcn_sched_barrier(0);
;     }
	v_mfma_f32_16x16x32_bf16 v[64:67], v[166:169], v[238:241], v[64:67]
	v_mfma_f32_16x16x32_bf16 v[68:71], v[170:173], v[238:241], v[68:71]
	v_mfma_f32_16x16x32_bf16 v[72:75], v[174:177], v[238:241], v[72:75]
	v_mfma_f32_16x16x32_bf16 v[76:79], v[178:181], v[238:241], v[76:79]
	v_mfma_f32_16x16x32_bf16 v[80:83], v[166:169], v[198:201], v[80:83]
	v_mfma_f32_16x16x32_bf16 v[84:87], v[170:173], v[198:201], v[84:87]
	v_mfma_f32_16x16x32_bf16 v[88:91], v[174:177], v[198:201], v[88:91]
	v_mfma_f32_16x16x32_bf16 v[92:95], v[178:181], v[198:201], v[92:95]
	v_mfma_f32_16x16x32_bf16 v[96:99], v[166:169], v[152:155], v[96:99]
	v_mfma_f32_16x16x32_bf16 v[100:103], v[170:173], v[152:155], v[100:103]
	v_mfma_f32_16x16x32_bf16 v[104:107], v[174:177], v[152:155], v[104:107]
	v_mfma_f32_16x16x32_bf16 v[108:111], v[178:181], v[152:155], v[108:111]
	v_mfma_f32_16x16x32_bf16 v[112:115], v[166:169], v[156:159], v[112:115]
	v_mfma_f32_16x16x32_bf16 v[116:119], v[170:173], v[156:159], v[116:119]
	v_mfma_f32_16x16x32_bf16 v[120:123], v[174:177], v[156:159], v[120:123]
	v_mfma_f32_16x16x32_bf16 v[124:127], v[178:181], v[156:159], v[124:127]
	ds_read_b64_tr_b16 v[238:239], v160 offset:18048
	ds_read_b64_tr_b16 v[240:241], v160 offset:20224
	ds_read_b64_tr_b16 v[198:199], v161 offset:18048
	ds_read_b64_tr_b16 v[200:201], v161 offset:20224
	ds_read_b64_tr_b16 v[152:153], v160 offset:18112
	ds_read_b64_tr_b16 v[154:155], v160 offset:20288
	ds_read_b64_tr_b16 v[156:157], v161 offset:18112
	ds_read_b64_tr_b16 v[158:159], v161 offset:20288
	s_waitcnt lgkmcnt(8)
	v_mfma_f32_16x16x32_bf16 v[0:3], v[182:185], v[222:225], v[0:3]
	v_mfma_f32_16x16x32_bf16 v[4:7], v[186:189], v[222:225], v[4:7]
	v_mfma_f32_16x16x32_bf16 v[8:11], v[190:193], v[222:225], v[8:11]
	v_mfma_f32_16x16x32_bf16 v[12:15], v[194:197], v[222:225], v[12:15]
	v_mfma_f32_16x16x32_bf16 v[16:19], v[182:185], v[226:229], v[16:19]
	v_mfma_f32_16x16x32_bf16 v[20:23], v[186:189], v[226:229], v[20:23]
	v_mfma_f32_16x16x32_bf16 v[24:27], v[190:193], v[226:229], v[24:27]
	v_mfma_f32_16x16x32_bf16 v[28:31], v[194:197], v[226:229], v[28:31]
	v_mfma_f32_16x16x32_bf16 v[32:35], v[182:185], v[230:233], v[32:35]
	v_mfma_f32_16x16x32_bf16 v[36:39], v[186:189], v[230:233], v[36:39]
	v_mfma_f32_16x16x32_bf16 v[40:43], v[190:193], v[230:233], v[40:43]
	v_mfma_f32_16x16x32_bf16 v[44:47], v[194:197], v[230:233], v[44:47]
	v_mfma_f32_16x16x32_bf16 v[48:51], v[182:185], v[234:237], v[48:51]
	v_mfma_f32_16x16x32_bf16 v[52:55], v[186:189], v[234:237], v[52:55]
	v_mfma_f32_16x16x32_bf16 v[56:59], v[190:193], v[234:237], v[56:59]
	v_mfma_f32_16x16x32_bf16 v[60:63], v[194:197], v[234:237], v[60:63]
	s_waitcnt lgkmcnt(0)
	v_mfma_f32_16x16x32_bf16 v[64:67], v[182:185], v[238:241], v[64:67]
	v_mfma_f32_16x16x32_bf16 v[68:71], v[186:189], v[238:241], v[68:71]
	v_mfma_f32_16x16x32_bf16 v[72:75], v[190:193], v[238:241], v[72:75]
	v_mfma_f32_16x16x32_bf16 v[76:79], v[194:197], v[238:241], v[76:79]
	v_mfma_f32_16x16x32_bf16 v[80:83], v[182:185], v[198:201], v[80:83]
	v_mfma_f32_16x16x32_bf16 v[84:87], v[186:189], v[198:201], v[84:87]
	v_mfma_f32_16x16x32_bf16 v[88:91], v[190:193], v[198:201], v[88:91]
	v_mfma_f32_16x16x32_bf16 v[92:95], v[194:197], v[198:201], v[92:95]
	v_mfma_f32_16x16x32_bf16 v[96:99], v[182:185], v[152:155], v[96:99]
	v_mfma_f32_16x16x32_bf16 v[100:103], v[186:189], v[152:155], v[100:103]
	v_mfma_f32_16x16x32_bf16 v[104:107], v[190:193], v[152:155], v[104:107]
	v_mfma_f32_16x16x32_bf16 v[108:111], v[194:197], v[152:155], v[108:111]
	v_mfma_f32_16x16x32_bf16 v[112:115], v[182:185], v[156:159], v[112:115]
	v_mfma_f32_16x16x32_bf16 v[116:119], v[186:189], v[156:159], v[116:119]
	v_mfma_f32_16x16x32_bf16 v[120:123], v[190:193], v[156:159], v[120:123]
	v_mfma_f32_16x16x32_bf16 v[124:127], v[194:197], v[156:159], v[124:127]
	s_waitcnt vmcnt(0)
	s_barrier
	s_cmp_eq_u32 s8, 3
	s_cbranch_scc1 .Lp3a_k1last
	s_cmp_lt_u32 s5, 0x4000
	s_cbranch_scc0 .Lp3a_t3
	s_add_u32 m0, s9, 0x0
	s_nop 0
	global_load_lds_dwordx4 v128, s[0:1]
	global_load_lds_dwordx4 v129, s[0:1] offset:1088
	global_load_lds_dwordx4 v130, s[0:1] offset:2176
	global_load_lds_dwordx4 v131, s[0:1] offset:3264
	s_add_u32 m0, s9, 0x1180
	s_nop 0
	global_load_lds_dwordx4 v136, s[0:1]
	global_load_lds_dwordx4 v137, s[0:1] offset:1088
	global_load_lds_dwordx4 v138, s[0:1] offset:2176
	global_load_lds_dwordx4 v139, s[0:1] offset:3264
	s_add_u32 m0, s5, 0x11800
	s_nop 0
	global_load_lds_dwordx4 v132, s[6:7]
	global_load_lds_dwordx4 v133, s[6:7] offset:1024
	global_load_lds_dwordx4 v134, s[6:7] offset:2048
	global_load_lds_dwordx4 v135, s[6:7] offset:3072
	s_add_u32 m0, s5, 0x15800
	s_nop 0
	global_load_lds_dwordx4 v140, s[6:7]
	global_load_lds_dwordx4 v141, s[6:7] offset:1024
	global_load_lds_dwordx4 v142, s[6:7] offset:2048
	global_load_lds_dwordx4 v143, s[6:7] offset:3072

; DEV void phase_p3a(const Params& p, int g, char* smem) {
;     ...
;     {
;       RowLoader al{PHG - 512, 2560};
;       RowLoader bl{WbrT, 1024};
;       gemm_mainloop(acc, al, bl, m0, n0, 512, 1024, smem);
.Lp3a_mid0:
	v_add_u32_e32 v128, s3, v150
	v_mul_u32_u24_e32 v128, 0x1400, v128
	v_add_u32_e32 v128, v128, v151
	v_add_u32_e32 v129, 0x9c00, v128
	v_add_u32_e32 v130, 0x13800, v128
	v_add_u32_e32 v131, 0x1d400, v128
	v_xor_b32_e32 v129, 0x40, v129
	v_xor_b32_e32 v131, 0x40, v131
	v_add_u32_e32 v136, 0xa0000, v128
	v_add_u32_e32 v137, 0xa0000, v129
	v_add_u32_e32 v138, 0xa0000, v130
	v_add_u32_e32 v139, 0xa0000, v131
	s_mov_b64 s[0:1], s[56:57]
	v_readlane_b32 s6, v251, 16
	v_readlane_b32 s7, v251, 17
	s_add_u32 s6, s6, 0x400
	s_addc_u32 s7, s7, 0
	s_cmp_lt_u32 s5, 0x4000
	s_cbranch_scc0 .Lp3a_u1
	s_add_u32 m0, s5, 0x0
	s_nop 0
	global_load_lds_dwordx4 v128, s[0:1]
	global_load_lds_dwordx4 v129, s[0:1] offset:1024
	global_load_lds_dwordx4 v130, s[0:1] offset:2048
	global_load_lds_dwordx4 v131, s[0:1] offset:3072
	s_add_u32 m0, s5, 0x10000
	s_nop 0
	global_load_lds_dwordx4 v132, s[6:7]
	global_load_lds_dwordx4 v133, s[6:7] offset:1024
	global_load_lds_dwordx4 v134, s[6:7] offset:2048
	global_load_lds_dwordx4 v135, s[6:7] offset:3072
	s_add_u32 m0, s5, 0x4000
	s_nop 0
	global_load_lds_dwordx4 v136, s[0:1]
	global_load_lds_dwordx4 v137, s[0:1] offset:1024
	global_load_lds_dwordx4 v138, s[0:1] offset:2048
	global_load_lds_dwordx4 v139, s[0:1] offset:3072
	s_add_u32 m0, s5, 0x14000
	s_nop 0
	global_load_lds_dwordx4 v140, s[6:7]
	global_load_lds_dwordx4 v141, s[6:7] offset:1024
	global_load_lds_dwordx4 v142, s[6:7] offset:2048
	global_load_lds_dwordx4 v143, s[6:7] offset:3072

; DEV void phase_p3a(const Params& p, int g, char* smem) {
;     ...
;       RowLoader al{PHG - 512, 2560};
;       RowLoader bl{WbrT, 1024};
;       gemm_mainloop(acc, al, bl, m0, n0, 512, 1024, smem);
.Lp3a_k2loop:
	s_cmp_lt_u32 s5, 0x4000
	s_cbranch_scc0 .Lp3a_u2
	s_add_u32 m0, s5, 0x8000
	s_nop 0
	global_load_lds_dwordx4 v128, s[0:1]
	global_load_lds_dwordx4 v129, s[0:1] offset:1024
	global_load_lds_dwordx4 v130, s[0:1] offset:2048
	global_load_lds_dwordx4 v131, s[0:1] offset:3072
	s_add_u32 m0, s5, 0x18000
	s_nop 0
	global_load_lds_dwordx4 v132, s[6:7]
	global_load_lds_dwordx4 v133, s[6:7] offset:1024
	global_load_lds_dwordx4 v134, s[6:7] offset:2048
	global_load_lds_dwordx4 v135, s[6:7] offset:3072
	s_add_u32 m0, s5, 0xc000
	s_nop 0
	global_load_lds_dwordx4 v136, s[0:1]
	global_load_lds_dwordx4 v137, s[0:1] offset:1024
	global_load_lds_dwordx4 v138, s[0:1] offset:2048
	global_load_lds_dwordx4 v139, s[0:1] offset:3072
	s_add_u32 m0, s5, 0x1c000
	s_nop 0
	global_load_lds_dwordx4 v140, s[6:7]
	global_load_lds_dwordx4 v141, s[6:7] offset:1024
	global_load_lds_dwordx4 v142, s[6:7] offset:2048
	global_load_lds_dwordx4 v143, s[6:7] offset:3072
; template <class AL, class BL>
; DEV void gemm_ktile(Acc& acc, const char* A, const char* B, int wm, int wn, int lr, int lh, const AL& al, const BL& bl,
;                     int tid, int m0, int n0, int knext, char* nxt, R4& ra, R4& rb) {
;   bf16x8 a[2][4], b[2][2];
;   const char* pa = A + (wm + lr) * LDSROW + lh * 16;
;   const char* pb = B + (wn + lr) * LDSROW + lh * 16;
; #pragma unroll
;   for (int i = 0; i < 4; ++i) a[0][i] = *(const bf16x8*)(pa + 32 * i * LDSROW);
; #pragma unroll
;   for (int j = 0; j < 2; ++j) b[0][j] = *(const bf16x8*)(pb + 32 * j * LDSROW);
; #pragma unroll
;   for (int ks = 0; ks < 4; ++ks) {
;     const int cur = ks & 1, nx = cur ^ 1;
;     if (ks < 3) {
; #pragma unroll
;       for (int i = 0; i < 4; ++i) a[nx][i] = *(const bf16x8*)(pa + 32 * i * LDSROW + (ks + 1) * 32);
; #pragma unroll
;       for (int j = 0; j < 2; ++j) b[nx][j] = *(const bf16x8*)(pb + 32 * j * LDSROW + (ks + 1) * 32);
;     }
;     __builtin_amdgcn_sched_barrier(0);
; #pragma unroll
;     for (int i = 0; i < 4; ++i)
; #pragma unroll
;       for (int j = 0; j < 2; ++j)
;         acc[i][j] = __builtin_amdgcn_mfma_f32_32x32x16_bf16(a[cur][i], b[cur][j], acc[i][j], 0, 0, 0);
;     __builtin_amdgcn_sched_barrier(0);
;     if (ks == 1) {
;       al.store(tid, nxt, ra);
;       bl.store(tid, nxt + TILE_BYTES, rb);
;       __builtin_amdgcn_sched_barrier(0);
;       ra = al.load(tid, m0, knext);
;       rb = bl.load(tid, n0, knext);
;       __builtin_amdgcn_sched_barrier(0);
;     }
.Lp3a_u2:
	s_add_u32 s0, s0, 0x80
	s_addc_u32 s1, s1, 0
	s_add_u32 s6, s6, 0x80
	s_addc_u32 s7, s7, 0
	ds_read_b128 v[166:169], v146
	ds_read_b128 v[170:173], v146 offset:2048
	ds_read_b128 v[174:177], v146 offset:4096
	ds_read_b128 v[178:181], v146 offset:6144
	ds_read_b128 v[222:225], v144
	ds_read_b128 v[226:229], v144 offset:2048
	ds_read_b128 v[230:233], v144 offset:4096
	ds_read_b128 v[234:237], v144 offset:6144
	ds_read_b128 v[238:241], v144 offset:8192
	ds_read_b128 v[198:201], v144 offset:10240
	ds_read_b128 v[152:155], v144 offset:12288
	ds_read_b128 v[156:159], v144 offset:14336
	ds_read_b128 v[182:185], v147
	ds_read_b128 v[186:189], v147 offset:2048
	ds_read_b128 v[190:193], v147 offset:4096
	ds_read_b128 v[194:197], v147 offset:6144
	s_waitcnt lgkmcnt(8)
	v_mfma_f32_16x16x32_bf16 v[0:3], v[166:169], v[222:225], v[0:3]
	v_mfma_f32_16x16x32_bf16 v[4:7], v[170:173], v[222:225], v[4:7]
	v_mfma_f32_16x16x32_bf16 v[8:11], v[174:177], v[222:225], v[8:11]
	v_mfma_f32_16x16x32_bf16 v[12:15], v[178:181], v[222:225], v[12:15]
	v_mfma_f32_16x16x32_bf16 v[16:19], v[166:169], v[226:229], v[16:19]
	v_mfma_f32_16x16x32_bf16 v[20:23], v[170:173], v[226:229], v[20:23]
	v_mfma_f32_16x16x32_bf16 v[24:27], v[174:177], v[226:229], v[24:27]
	v_mfma_f32_16x16x32_bf16 v[28:31], v[178:181], v[226:229], v[28:31]
	v_mfma_f32_16x16x32_bf16 v[32:35], v[166:169], v[230:233], v[32:35]
	v_mfma_f32_16x16x32_bf16 v[36:39], v[170:173], v[230:233], v[36:39]
	v_mfma_f32_16x16x32_bf16 v[40:43], v[174:177], v[230:233], v[40:43]
	v_mfma_f32_16x16x32_bf16 v[44:47], v[178:181], v[230:233], v[44:47]
	v_mfma_f32_16x16x32_bf16 v[48:51], v[166:169], v[234:237], v[48:51]
	v_mfma_f32_16x16x32_bf16 v[52:55], v[170:173], v[234:237], v[52:55]
	v_mfma_f32_16x16x32_bf16 v[56:59], v[174:177], v[234:237], v[56:59]
	v_mfma_f32_16x16x32_bf16 v[60:63], v[178:181], v[234:237], v[60:63]
	ds_read_b128 v[222:225], v145
	ds_read_b128 v[226:229], v145 offset:2048
	ds_read_b128 v[230:233], v145 offset:4096
	ds_read_b128 v[234:237], v145 offset:6144
	s_waitcnt lgkmcnt(8)
	v_mfma_f32_16x16x32_bf16 v[64:67], v[166:169], v[238:241], v[64:67]
	v_mfma_f32_16x16x32_bf16 v[68:71], v[170:173], v[238:241], v[68:71]
	v_mfma_f32_16x16x32_bf16 v[72:75], v[174:177], v[238:241], v[72:75]
	v_mfma_f32_16x16x32_bf16 v[76:79], v[178:181], v[238:241], v[76:79]
	v_mfma_f32_16x16x32_bf16 v[80:83], v[166:169], v[198:201], v[80:83]
	v_mfma_f32_16x16x32_bf16 v[84:87], v[170:173], v[198:201], v[84:87]
	v_mfma_f32_16x16x32_bf16 v[88:91], v[174:177], v[198:201], v[88:91]
	v_mfma_f32_16x16x32_bf16 v[92:95], v[178:181], v[198:201], v[92:95]
	v_mfma_f32_16x16x32_bf16 v[96:99], v[166:169], v[152:155], v[96:99]
	v_mfma_f32_16x16x32_bf16 v[100:103], v[170:173], v[152:155], v[100:103]
	v_mfma_f32_16x16x32_bf16 v[104:107], v[174:177], v[152:155], v[104:107]
	v_mfma_f32_16x16x32_bf16 v[108:111], v[178:181], v[152:155], v[108:111]
	v_mfma_f32_16x16x32_bf16 v[112:115], v[166:169], v[156:159], v[112:115]
	v_mfma_f32_16x16x32_bf16 v[116:119], v[170:173], v[156:159], v[116:119]
	v_mfma_f32_16x16x32_bf16 v[120:123], v[174:177], v[156:159], v[120:123]
	v_mfma_f32_16x16x32_bf16 v[124:127], v[178:181], v[156:159], v[124:127]
	ds_read_b128 v[238:241], v145 offset:8192
	ds_read_b128 v[198:201], v145 offset:10240
	ds_read_b128 v[152:155], v145 offset:12288
	ds_read_b128 v[156:159], v145 offset:14336
	s_waitcnt lgkmcnt(4)
	v_mfma_f32_16x16x32_bf16 v[0:3], v[182:185], v[222:225], v[0:3]
	v_mfma_f32_16x16x32_bf16 v[4:7], v[186:189], v[222:225], v[4:7]
	v_mfma_f32_16x16x32_bf16 v[8:11], v[190:193], v[222:225], v[8:11]
	v_mfma_f32_16x16x32_bf16 v[12:15], v[194:197], v[222:225], v[12:15]
	v_mfma_f32_16x16x32_bf16 v[16:19], v[182:185], v[226:229], v[16:19]
	v_mfma_f32_16x16x32_bf16 v[20:23], v[186:189], v[226:229], v[20:23]
	v_mfma_f32_16x16x32_bf16 v[24:27], v[190:193], v[226:229], v[24:27]
	v_mfma_f32_16x16x32_bf16 v[28:31], v[194:197], v[226:229], v[28:31]
	v_mfma_f32_16x16x32_bf16 v[32:35], v[182:185], v[230:233], v[32:35]
	v_mfma_f32_16x16x32_bf16 v[36:39], v[186:189], v[230:233], v[36:39]
	v_mfma_f32_16x16x32_bf16 v[40:43], v[190:193], v[230:233], v[40:43]
	v_mfma_f32_16x16x32_bf16 v[44:47], v[194:197], v[230:233], v[44:47]
	v_mfma_f32_16x16x32_bf16 v[48:51], v[182:185], v[234:237], v[48:51]
	v_mfma_f32_16x16x32_bf16 v[52:55], v[186:189], v[234:237], v[52:55]
	v_mfma_f32_16x16x32_bf16 v[56:59], v[190:193], v[234:237], v[56:59]
	v_mfma_f32_16x16x32_bf16 v[60:63], v[194:197], v[234:237], v[60:63]
	s_waitcnt lgkmcnt(0)
	v_mfma_f32_16x16x32_bf16 v[64:67], v[182:185], v[238:241], v[64:67]
	v_mfma_f32_16x16x32_bf16 v[68:71], v[186:189], v[238:241], v[68:71]
	v_mfma_f32_16x16x32_bf16 v[72:75], v[190:193], v[238:241], v[72:75]
	v_mfma_f32_16x16x32_bf16 v[76:79], v[194:197], v[238:241], v[76:79]
	v_mfma_f32_16x16x32_bf16 v[80:83], v[182:185], v[198:201], v[80:83]
	v_mfma_f32_16x16x32_bf16 v[84:87], v[186:189], v[198:201], v[84:87]
	v_mfma_f32_16x16x32_bf16 v[88:91], v[190:193], v[198:201], v[88:91]
	v_mfma_f32_16x16x32_bf16 v[92:95], v[194:197], v[198:201], v[92:95]
	v_mfma_f32_16x16x32_bf16 v[96:99], v[182:185], v[152:155], v[96:99]
	v_mfma_f32_16x16x32_bf16 v[100:103], v[186:189], v[152:155], v[100:103]
	v_mfma_f32_16x16x32_bf16 v[104:107], v[190:193], v[152:155], v[104:107]
	v_mfma_f32_16x16x32_bf16 v[108:111], v[194:197], v[152:155], v[108:111]
	v_mfma_f32_16x16x32_bf16 v[112:115], v[182:185], v[156:159], v[112:115]
	v_mfma_f32_16x16x32_bf16 v[116:119], v[186:189], v[156:159], v[116:119]
	v_mfma_f32_16x16x32_bf16 v[120:123], v[190:193], v[156:159], v[120:123]
	v_mfma_f32_16x16x32_bf16 v[124:127], v[194:197], v[156:159], v[124:127]
	s_waitcnt vmcnt(0)
	s_barrier
	s_cmp_eq_u32 s8, 3
	s_cbranch_scc1 .Lp3a_k2last
	s_cmp_lt_u32 s5, 0x4000
	s_cbranch_scc0 .Lp3a_u3
	s_add_u32 m0, s5, 0x0
	s_nop 0
	global_load_lds_dwordx4 v128, s[0:1]
	global_load_lds_dwordx4 v129, s[0:1] offset:1024
	global_load_lds_dwordx4 v130, s[0:1] offset:2048
	global_load_lds_dwordx4 v131, s[0:1] offset:3072
	s_add_u32 m0, s5, 0x10000
	s_nop 0
	global_load_lds_dwordx4 v132, s[6:7]
	global_load_lds_dwordx4 v133, s[6:7] offset:1024
	global_load_lds_dwordx4 v134, s[6:7] offset:2048
	global_load_lds_dwordx4 v135, s[6:7] offset:3072
	s_add_u32 m0, s5, 0x4000
	s_nop 0
	global_load_lds_dwordx4 v136, s[0:1]
	global_load_lds_dwordx4 v137, s[0:1] offset:1024
	global_load_lds_dwordx4 v138, s[0:1] offset:2048
	global_load_lds_dwordx4 v139, s[0:1] offset:3072
	s_add_u32 m0, s5, 0x14000
	s_nop 0
	global_load_lds_dwordx4 v140, s[6:7]
	global_load_lds_dwordx4 v141, s[6:7] offset:1024
	global_load_lds_dwordx4 v142, s[6:7] offset:2048
	global_load_lds_dwordx4 v143, s[6:7] offset:3072

; DEV void phase_p3b(const Params& p, int g, char* smem) {
;     ...
;   for (int iter = 0;; ++iter) {
;     int mt, nt;
;     if (!tile_map(iter, 128, 4, mt, nt)) break;
;     const int m0 = mt * 256, n0 = nt * 256;
;     Acc acc;
;     acc_zero(acc);
;     RowLoader al{PHG + 1024, 2560}, bl{WoutT, 1024};
;     gemm_mainloop(acc, al, bl, m0, n0, 0, 1024, smem);
.LBB0_1001:
	v_readlane_b32 s2, v251, 23
	v_readlane_b32 s3, v251, 24
	v_readlane_b32 s10, v251, 21
	v_readlane_b32 s11, v251, 22
	s_lshl_b32 s5, s7, 8
	s_lshl_b32 s4, s8, 8
	v_lshrrev_b32_e32 v149, 6, v202
	v_and_b32_e32 v148, 63, v202
	s_nop 0
	v_readfirstlane_b32 s9, v149
	v_lshrrev_b32_e32 v150, 3, v148
	v_lshl_add_u32 v150, v149, 5, v150
	v_and_b32_e32 v151, 7, v148
	v_lshrrev_b32_e32 v128, 4, v148
	v_xor_b32_e32 v151, v128, v151
	v_lshlrev_b32_e32 v151, 4, v151
	s_lshl_b32 s9, s9, 12
	v_add_u32_e32 v128, s5, v150
	v_mul_u32_u24_e32 v128, 0x1400, v128
	v_add_u32_e32 v128, v128, v151
	v_add_u32_e32 v129, 0x9c00, v128
	v_add_u32_e32 v130, 0x13800, v128
	v_add_u32_e32 v131, 0x1d400, v128
	v_xor_b32_e32 v129, 0x40, v129
	v_xor_b32_e32 v131, 0x40, v131
	v_add_u32_e32 v136, 0xa0000, v128
	v_add_u32_e32 v137, 0xa0000, v129
	v_add_u32_e32 v138, 0xa0000, v130
	v_add_u32_e32 v139, 0xa0000, v131
	v_add_u32_e32 v132, s4, v150
	v_lshlrev_b32_e32 v132, 11, v132
	v_add_u32_e32 v132, v132, v151
	v_add_u32_e32 v133, 0x3c00, v132
	v_add_u32_e32 v134, 0x7800, v132
	v_add_u32_e32 v135, 0xb400, v132
	v_xor_b32_e32 v133, 0x40, v133
	v_xor_b32_e32 v135, 0x40, v135
	v_add_u32_e32 v140, 0x40000, v132
	v_add_u32_e32 v141, 0x40000, v133
	v_add_u32_e32 v142, 0x40000, v134
	v_add_u32_e32 v143, 0x40000, v135
	v_lshrrev_b32_e32 v161, 6, v202
	v_and_b32_e32 v160, 63, v202
	v_bfe_u32 v164, v160, 1, 3
	v_lshrrev_b32_e32 v199, 4, v160
	v_xor_b32_e32 v164, v164, v199
	v_lshlrev_b32_e32 v164, 4, v164
	v_and_b32_e32 v199, 15, v160
	v_lshlrev_b32_e32 v199, 7, v199
	v_lshrrev_b32_e32 v144, 2, v161
	v_lshl_add_u32 v144, v144, 14, v199
	v_and_b32_e32 v146, 3, v161
	v_lshl_add_u32 v146, v146, 13, v199
	v_add_u32_e32 v146, 0x10000, v146
	v_xor_b32_e32 v145, 0x40, v164
	v_add_u32_e32 v145, v144, v145
	v_add_u32_e32 v144, v144, v164
	v_xor_b32_e32 v147, 0x40, v164
	v_add_u32_e32 v147, v146, v147
	v_add_u32_e32 v146, v146, v164
	s_mov_b64 s[12:13], s[2:3]
	s_mov_b64 s[14:15], s[10:11]
	s_cmp_lt_u32 s9, 0x4000
	s_cbranch_scc0 .Lp3b_d1
	s_add_u32 m0, s9, 0x0
	s_nop 0
	global_load_lds_dwordx4 v128, s[12:13]
	global_load_lds_dwordx4 v129, s[12:13] offset:1024
	global_load_lds_dwordx4 v130, s[12:13] offset:2048
	global_load_lds_dwordx4 v131, s[12:13] offset:3072
	s_add_u32 m0, s9, 0x10000
	s_nop 0
	global_load_lds_dwordx4 v132, s[14:15]
	global_load_lds_dwordx4 v133, s[14:15] offset:1024
	global_load_lds_dwordx4 v134, s[14:15] offset:2048
	global_load_lds_dwordx4 v135, s[14:15] offset:3072
	s_add_u32 m0, s9, 0x4000
	s_nop 0
	global_load_lds_dwordx4 v136, s[12:13]
	global_load_lds_dwordx4 v137, s[12:13] offset:1024
	global_load_lds_dwordx4 v138, s[12:13] offset:2048
	global_load_lds_dwordx4 v139, s[12:13] offset:3072
	s_add_u32 m0, s9, 0x14000
	s_nop 0
	global_load_lds_dwordx4 v140, s[14:15]
	global_load_lds_dwordx4 v141, s[14:15] offset:1024
	global_load_lds_dwordx4 v142, s[14:15] offset:2048
	global_load_lds_dwordx4 v143, s[14:15] offset:3072

; template <class AL, class BL>
; DEV void gemm_mainloop(Acc& acc, const AL& al, const BL& bl, int m0, int n0, int kbeg, int kend, char* lds) {
;     ...
;   for (int kt = 0; kt < nk; ++kt) {
;     const char* cur = lds + (kt & 1) * 2 * TILE_BYTES;
;     char* nxt = lds + ((kt + 1) & 1) * 2 * TILE_BYTES;
;     const int t2 = (kt + 2 < nk) ? kt + 2 : nk - 1;
;     __builtin_amdgcn_sched_barrier(0);
;     gemm_ktile(acc, cur, cur + TILE_BYTES, wm, wn, lr, lh, al, bl, tid, m0, n0, kbeg + t2 * BK, nxt, a0, b0);
; DEV void phase_p3b(const Params& p, int g, char* smem) {
;     ...
;     RowLoader al{PHG + 1024, 2560}, bl{WoutT, 1024};
;     gemm_mainloop(acc, al, bl, m0, n0, 0, 1024, smem);
.Lp3b_kloop:
	s_cmp_lt_u32 s9, 0x4000
	s_cbranch_scc0 .Lp3b_d2
	s_add_u32 m0, s9, 0x8000
	s_nop 0
	global_load_lds_dwordx4 v128, s[12:13]
	global_load_lds_dwordx4 v129, s[12:13] offset:1024
	global_load_lds_dwordx4 v130, s[12:13] offset:2048
	global_load_lds_dwordx4 v131, s[12:13] offset:3072
	s_add_u32 m0, s9, 0x18000
	s_nop 0
	global_load_lds_dwordx4 v132, s[14:15]
	global_load_lds_dwordx4 v133, s[14:15] offset:1024
	global_load_lds_dwordx4 v134, s[14:15] offset:2048
	global_load_lds_dwordx4 v135, s[14:15] offset:3072
	s_add_u32 m0, s9, 0xc000
	s_nop 0
	global_load_lds_dwordx4 v136, s[12:13]
	global_load_lds_dwordx4 v137, s[12:13] offset:1024
	global_load_lds_dwordx4 v138, s[12:13] offset:2048
	global_load_lds_dwordx4 v139, s[12:13] offset:3072
	s_add_u32 m0, s9, 0x1c000
	s_nop 0
	global_load_lds_dwordx4 v140, s[14:15]
	global_load_lds_dwordx4 v141, s[14:15] offset:1024
	global_load_lds_dwordx4 v142, s[14:15] offset:2048
	global_load_lds_dwordx4 v143, s[14:15] offset:3072
; template <class AL, class BL>
; DEV void gemm_ktile(Acc& acc, const char* A, const char* B, int wm, int wn, int lr, int lh, const AL& al, const BL& bl,
;                     int tid, int m0, int n0, int knext, char* nxt, R4& ra, R4& rb) {
;   bf16x8 a[2][4], b[2][2];
;   const char* pa = A + (wm + lr) * LDSROW + lh * 16;
;   const char* pb = B + (wn + lr) * LDSROW + lh * 16;
; #pragma unroll
;   for (int i = 0; i < 4; ++i) a[0][i] = *(const bf16x8*)(pa + 32 * i * LDSROW);
; #pragma unroll
;   for (int j = 0; j < 2; ++j) b[0][j] = *(const bf16x8*)(pb + 32 * j * LDSROW);
; #pragma unroll
;   for (int ks = 0; ks < 4; ++ks) {
;     const int cur = ks & 1, nx = cur ^ 1;
;     if (ks < 3) {
; #pragma unroll
;       for (int i = 0; i < 4; ++i) a[nx][i] = *(const bf16x8*)(pa + 32 * i * LDSROW + (ks + 1) * 32);
; #pragma unroll
;       for (int j = 0; j < 2; ++j) b[nx][j] = *(const bf16x8*)(pb + 32 * j * LDSROW + (ks + 1) * 32);
;     }
;     __builtin_amdgcn_sched_barrier(0);
; #pragma unroll
;     for (int i = 0; i < 4; ++i)
; #pragma unroll
;       for (int j = 0; j < 2; ++j)
;         acc[i][j] = __builtin_amdgcn_mfma_f32_32x32x16_bf16(a[cur][i], b[cur][j], acc[i][j], 0, 0, 0);
;     __builtin_amdgcn_sched_barrier(0);
;     if (ks == 1) {
;       al.store(tid, nxt, ra);
;       bl.store(tid, nxt + TILE_BYTES, rb);
;       __builtin_amdgcn_sched_barrier(0);
;       ra = al.load(tid, m0, knext);
;       rb = bl.load(tid, n0, knext);
;       __builtin_amdgcn_sched_barrier(0);
;     }
.Lp3b_d2:
	s_add_u32 s12, s12, 0x80
	s_addc_u32 s13, s13, 0
	s_add_u32 s14, s14, 0x80
	s_addc_u32 s15, s15, 0
	ds_read_b128 v[166:169], v146
	ds_read_b128 v[170:173], v146 offset:2048
	ds_read_b128 v[174:177], v146 offset:4096
	ds_read_b128 v[178:181], v146 offset:6144
	ds_read_b128 v[222:225], v144
	ds_read_b128 v[226:229], v144 offset:2048
	ds_read_b128 v[230:233], v144 offset:4096
	ds_read_b128 v[234:237], v144 offset:6144
	ds_read_b128 v[238:241], v144 offset:8192
	ds_read_b128 v[198:201], v144 offset:10240
	ds_read_b128 v[152:155], v144 offset:12288
	ds_read_b128 v[156:159], v144 offset:14336
	ds_read_b128 v[182:185], v147
	ds_read_b128 v[186:189], v147 offset:2048
	ds_read_b128 v[190:193], v147 offset:4096
	ds_read_b128 v[194:197], v147 offset:6144
	s_waitcnt lgkmcnt(8)
	v_mfma_f32_16x16x32_bf16 v[0:3], v[166:169], v[222:225], v[0:3]
	v_mfma_f32_16x16x32_bf16 v[4:7], v[170:173], v[222:225], v[4:7]
	v_mfma_f32_16x16x32_bf16 v[8:11], v[174:177], v[222:225], v[8:11]
	v_mfma_f32_16x16x32_bf16 v[12:15], v[178:181], v[222:225], v[12:15]
	v_mfma_f32_16x16x32_bf16 v[16:19], v[166:169], v[226:229], v[16:19]
	v_mfma_f32_16x16x32_bf16 v[20:23], v[170:173], v[226:229], v[20:23]
	v_mfma_f32_16x16x32_bf16 v[24:27], v[174:177], v[226:229], v[24:27]
	v_mfma_f32_16x16x32_bf16 v[28:31], v[178:181], v[226:229], v[28:31]
	v_mfma_f32_16x16x32_bf16 v[32:35], v[166:169], v[230:233], v[32:35]
	v_mfma_f32_16x16x32_bf16 v[36:39], v[170:173], v[230:233], v[36:39]
	v_mfma_f32_16x16x32_bf16 v[40:43], v[174:177], v[230:233], v[40:43]
	v_mfma_f32_16x16x32_bf16 v[44:47], v[178:181], v[230:233], v[44:47]
	v_mfma_f32_16x16x32_bf16 v[48:51], v[166:169], v[234:237], v[48:51]
	v_mfma_f32_16x16x32_bf16 v[52:55], v[170:173], v[234:237], v[52:55]
	v_mfma_f32_16x16x32_bf16 v[56:59], v[174:177], v[234:237], v[56:59]
	v_mfma_f32_16x16x32_bf16 v[60:63], v[178:181], v[234:237], v[60:63]
	ds_read_b128 v[222:225], v145
	ds_read_b128 v[226:229], v145 offset:2048
	ds_read_b128 v[230:233], v145 offset:4096
	ds_read_b128 v[234:237], v145 offset:6144
	s_waitcnt lgkmcnt(8)
	v_mfma_f32_16x16x32_bf16 v[64:67], v[166:169], v[238:241], v[64:67]
	v_mfma_f32_16x16x32_bf16 v[68:71], v[170:173], v[238:241], v[68:71]
	v_mfma_f32_16x16x32_bf16 v[72:75], v[174:177], v[238:241], v[72:75]
	v_mfma_f32_16x16x32_bf16 v[76:79], v[178:181], v[238:241], v[76:79]
	v_mfma_f32_16x16x32_bf16 v[80:83], v[166:169], v[198:201], v[80:83]
	v_mfma_f32_16x16x32_bf16 v[84:87], v[170:173], v[198:201], v[84:87]
	v_mfma_f32_16x16x32_bf16 v[88:91], v[174:177], v[198:201], v[88:91]
	v_mfma_f32_16x16x32_bf16 v[92:95], v[178:181], v[198:201], v[92:95]
	v_mfma_f32_16x16x32_bf16 v[96:99], v[166:169], v[152:155], v[96:99]
	v_mfma_f32_16x16x32_bf16 v[100:103], v[170:173], v[152:155], v[100:103]
	v_mfma_f32_16x16x32_bf16 v[104:107], v[174:177], v[152:155], v[104:107]
	v_mfma_f32_16x16x32_bf16 v[108:111], v[178:181], v[152:155], v[108:111]
	v_mfma_f32_16x16x32_bf16 v[112:115], v[166:169], v[156:159], v[112:115]
	v_mfma_f32_16x16x32_bf16 v[116:119], v[170:173], v[156:159], v[116:119]
	v_mfma_f32_16x16x32_bf16 v[120:123], v[174:177], v[156:159], v[120:123]
	v_mfma_f32_16x16x32_bf16 v[124:127], v[178:181], v[156:159], v[124:127]
	ds_read_b128 v[238:241], v145 offset:8192
	ds_read_b128 v[198:201], v145 offset:10240
	ds_read_b128 v[152:155], v145 offset:12288
	ds_read_b128 v[156:159], v145 offset:14336
	s_waitcnt lgkmcnt(4)
	v_mfma_f32_16x16x32_bf16 v[0:3], v[182:185], v[222:225], v[0:3]
	v_mfma_f32_16x16x32_bf16 v[4:7], v[186:189], v[222:225], v[4:7]
	v_mfma_f32_16x16x32_bf16 v[8:11], v[190:193], v[222:225], v[8:11]
	v_mfma_f32_16x16x32_bf16 v[12:15], v[194:197], v[222:225], v[12:15]
	v_mfma_f32_16x16x32_bf16 v[16:19], v[182:185], v[226:229], v[16:19]
	v_mfma_f32_16x16x32_bf16 v[20:23], v[186:189], v[226:229], v[20:23]
	v_mfma_f32_16x16x32_bf16 v[24:27], v[190:193], v[226:229], v[24:27]
	v_mfma_f32_16x16x32_bf16 v[28:31], v[194:197], v[226:229], v[28:31]
	v_mfma_f32_16x16x32_bf16 v[32:35], v[182:185], v[230:233], v[32:35]
	v_mfma_f32_16x16x32_bf16 v[36:39], v[186:189], v[230:233], v[36:39]
	v_mfma_f32_16x16x32_bf16 v[40:43], v[190:193], v[230:233], v[40:43]
	v_mfma_f32_16x16x32_bf16 v[44:47], v[194:197], v[230:233], v[44:47]
	v_mfma_f32_16x16x32_bf16 v[48:51], v[182:185], v[234:237], v[48:51]
	v_mfma_f32_16x16x32_bf16 v[52:55], v[186:189], v[234:237], v[52:55]
	v_mfma_f32_16x16x32_bf16 v[56:59], v[190:193], v[234:237], v[56:59]
	v_mfma_f32_16x16x32_bf16 v[60:63], v[194:197], v[234:237], v[60:63]
	s_waitcnt lgkmcnt(0)
	v_mfma_f32_16x16x32_bf16 v[64:67], v[182:185], v[238:241], v[64:67]
	v_mfma_f32_16x16x32_bf16 v[68:71], v[186:189], v[238:241], v[68:71]
	v_mfma_f32_16x16x32_bf16 v[72:75], v[190:193], v[238:241], v[72:75]
	v_mfma_f32_16x16x32_bf16 v[76:79], v[194:197], v[238:241], v[76:79]
	v_mfma_f32_16x16x32_bf16 v[80:83], v[182:185], v[198:201], v[80:83]
	v_mfma_f32_16x16x32_bf16 v[84:87], v[186:189], v[198:201], v[84:87]
	v_mfma_f32_16x16x32_bf16 v[88:91], v[190:193], v[198:201], v[88:91]
	v_mfma_f32_16x16x32_bf16 v[92:95], v[194:197], v[198:201], v[92:95]
	v_mfma_f32_16x16x32_bf16 v[96:99], v[182:185], v[152:155], v[96:99]
	v_mfma_f32_16x16x32_bf16 v[100:103], v[186:189], v[152:155], v[100:103]
	v_mfma_f32_16x16x32_bf16 v[104:107], v[190:193], v[152:155], v[104:107]
	v_mfma_f32_16x16x32_bf16 v[108:111], v[194:197], v[152:155], v[108:111]
	v_mfma_f32_16x16x32_bf16 v[112:115], v[182:185], v[156:159], v[112:115]
	v_mfma_f32_16x16x32_bf16 v[116:119], v[186:189], v[156:159], v[116:119]
	v_mfma_f32_16x16x32_bf16 v[120:123], v[190:193], v[156:159], v[120:123]
	v_mfma_f32_16x16x32_bf16 v[124:127], v[194:197], v[156:159], v[124:127]
	s_waitcnt vmcnt(0)
	s_barrier
	s_cmp_eq_u32 s7, 7
	s_cbranch_scc1 .Lp3b_last
	s_cmp_lt_u32 s9, 0x4000
	s_cbranch_scc0 .Lp3b_d3
	s_add_u32 m0, s9, 0x0
	s_nop 0
	global_load_lds_dwordx4 v128, s[12:13]
	global_load_lds_dwordx4 v129, s[12:13] offset:1024
	global_load_lds_dwordx4 v130, s[12:13] offset:2048
	global_load_lds_dwordx4 v131, s[12:13] offset:3072
	s_add_u32 m0, s9, 0x10000
	s_nop 0
	global_load_lds_dwordx4 v132, s[14:15]
	global_load_lds_dwordx4 v133, s[14:15] offset:1024
	global_load_lds_dwordx4 v134, s[14:15] offset:2048
	global_load_lds_dwordx4 v135, s[14:15] offset:3072
	s_add_u32 m0, s9, 0x4000
	s_nop 0
	global_load_lds_dwordx4 v136, s[12:13]
	global_load_lds_dwordx4 v137, s[12:13] offset:1024
	global_load_lds_dwordx4 v138, s[12:13] offset:2048
	global_load_lds_dwordx4 v139, s[12:13] offset:3072
	s_add_u32 m0, s9, 0x14000
	s_nop 0
	global_load_lds_dwordx4 v140, s[14:15]
	global_load_lds_dwordx4 v141, s[14:15] offset:1024
	global_load_lds_dwordx4 v142, s[14:15] offset:2048
	global_load_lds_dwordx4 v143, s[14:15] offset:3072

; template <class AL, class BL>
; DEV void gemm_mainloop_p(Acc& acc, const AL& al, const BL& bl, int m0, int n0, int m0n, int n0n, int K, char* lds,
;                          GemmPipe& gp) {
;     ...
;   if (!gp.primed) {
;     gp.ra = al.load(tid, m0, 0);
;     gp.rb = bl.load(tid, n0, 0);
;     __syncthreads();
;     al.store(tid, lds, gp.ra);
;     bl.store(tid, lds + TILE_BYTES, gp.rb);
;     gp.ra = al.load(tid, m0, BK);
;     gp.rb = bl.load(tid, n0, BK);
.LBB0_1126:
	v_readlane_b32 s18, v249, 48
	v_readlane_b32 s19, v249, 49
	v_readlane_b32 s20, v251, 25
	v_readlane_b32 s21, v251, 26
	s_and_b64 vcc, exec, s[2:3]
	s_lshl_b32 s5, s9, 8
	s_lshl_b32 s4, s10, 8
	v_lshrrev_b32_e32 v149, 6, v202
	v_and_b32_e32 v148, 63, v202
	s_nop 0
	v_readfirstlane_b32 s13, v149
	v_lshrrev_b32_e32 v150, 3, v148
	v_lshl_add_u32 v150, v149, 5, v150
	v_and_b32_e32 v151, 7, v148
	v_lshrrev_b32_e32 v128, 4, v148
	v_xor_b32_e32 v151, v128, v151
	v_lshlrev_b32_e32 v151, 4, v151
	s_lshl_b32 s13, s13, 12
	v_add_u32_e32 v128, s5, v150
	v_lshlrev_b32_e32 v128, 11, v128
	v_add_u32_e32 v128, v128, v151
	v_add_u32_e32 v129, 0x3c00, v128
	v_add_u32_e32 v130, 0x7800, v128
	v_add_u32_e32 v131, 0xb400, v128
	v_xor_b32_e32 v129, 0x40, v129
	v_xor_b32_e32 v131, 0x40, v131
	v_add_u32_e32 v132, s4, v150
	v_lshlrev_b32_e32 v132, 11, v132
	v_add_u32_e32 v132, v132, v151
	v_add_u32_e32 v133, 0x3c00, v132
	v_add_u32_e32 v134, 0x7800, v132
	v_add_u32_e32 v135, 0xb400, v132
	v_xor_b32_e32 v133, 0x40, v133
	v_xor_b32_e32 v135, 0x40, v135
	v_add_u32_e32 v136, 0x40000, v128
	v_add_u32_e32 v137, 0x40000, v129
	v_add_u32_e32 v138, 0x40000, v130
	v_add_u32_e32 v139, 0x40000, v131
	v_add_u32_e32 v140, 0x40000, v132
	v_add_u32_e32 v141, 0x40000, v133
	v_add_u32_e32 v142, 0x40000, v134
	v_add_u32_e32 v143, 0x40000, v135
	v_lshrrev_b32_e32 v161, 6, v202
	v_and_b32_e32 v160, 63, v202
	v_bfe_u32 v242, v160, 1, 3
	v_lshrrev_b32_e32 v243, 4, v160
	v_xor_b32_e32 v242, v242, v243
	v_lshlrev_b32_e32 v242, 4, v242
	v_and_b32_e32 v243, 15, v160
	v_lshlrev_b32_e32 v243, 7, v243
	v_lshrrev_b32_e32 v144, 2, v161
	v_lshl_add_u32 v144, v144, 14, v243
	v_and_b32_e32 v146, 3, v161
	v_lshl_add_u32 v146, v146, 13, v243
	v_add_u32_e32 v146, 0x10000, v146
	v_xor_b32_e32 v145, 0x40, v242
	v_add_u32_e32 v145, v144, v145
	v_add_u32_e32 v144, v144, v242
	v_xor_b32_e32 v147, 0x40, v242
	v_add_u32_e32 v147, v146, v147
	v_add_u32_e32 v146, v146, v242
	s_mov_b64 s[22:23], s[18:19]
	s_mov_b64 s[14:15], s[20:21]
	s_cbranch_vccnz .Lff1_primed
	s_cmp_lt_u32 s13, 0x4000
	s_cbranch_scc0 .Lff1_d1
	s_add_u32 m0, s13, 0x0
	s_nop 0
	global_load_lds_dwordx4 v128, s[22:23]
	global_load_lds_dwordx4 v129, s[22:23] offset:1024
	global_load_lds_dwordx4 v130, s[22:23] offset:2048
	global_load_lds_dwordx4 v131, s[22:23] offset:3072
	s_add_u32 m0, s13, 0x10000
	s_nop 0
	global_load_lds_dwordx4 v132, s[14:15]
	global_load_lds_dwordx4 v133, s[14:15] offset:1024
	global_load_lds_dwordx4 v134, s[14:15] offset:2048
	global_load_lds_dwordx4 v135, s[14:15] offset:3072
	s_add_u32 m0, s13, 0x4000
	s_nop 0
	global_load_lds_dwordx4 v136, s[22:23]
	global_load_lds_dwordx4 v137, s[22:23] offset:1024
	global_load_lds_dwordx4 v138, s[22:23] offset:2048
	global_load_lds_dwordx4 v139, s[22:23] offset:3072
	s_add_u32 m0, s13, 0x14000
	s_nop 0
	global_load_lds_dwordx4 v140, s[14:15]
	global_load_lds_dwordx4 v141, s[14:15] offset:1024
	global_load_lds_dwordx4 v142, s[14:15] offset:2048
	global_load_lds_dwordx4 v143, s[14:15] offset:3072

; template <class AL, class BL>
; DEV void gemm_mainloop_p(Acc& acc, const AL& al, const BL& bl, int m0, int n0, int m0n, int n0n, int K, char* lds,
;                          GemmPipe& gp) {
;     ...
;   for (int kt = 0; kt < nk; ++kt) {
;     const char* cur = lds + (kt & 1) * 2 * TILE_BYTES;
;     char* nxt = lds + ((kt + 1) & 1) * 2 * TILE_BYTES;
;     const bool wrap = (kt + 2 >= nk);
;     const int kk = (wrap ? kt + 2 - nk : kt + 2) * BK;
;     const int mr = wrap ? m0n : m0, nr = wrap ? n0n : n0;
;     __builtin_amdgcn_sched_barrier(0);
;     gemm_ktile(acc, cur, cur + TILE_BYTES, wm, wn, lr, lh, al, bl, tid, mr, nr, kk, nxt, gp.ra, gp.rb);
; DEV void acc_zero(Acc& acc) {
; #pragma unroll
;   for (int i = 0; i < 4; ++i)
; #pragma unroll
;     for (int j = 0; j < 2; ++j)
; #pragma unroll
;       for (int r = 0; r < 16; ++r) acc[i][j][r] = 0.f;
; }
.Lff1_primed:
	s_add_u32 s22, s22, 0x80
	s_addc_u32 s23, s23, 0
	s_add_u32 s14, s14, 0x80
	s_addc_u32 s15, s15, 0
	v_mov_b32_e32 v0, 0
	v_mov_b32_e32 v1, 0
	v_mov_b64_e32 v[2:3], v[0:1]
	v_mov_b64_e32 v[4:5], v[0:1]
	v_mov_b64_e32 v[6:7], v[0:1]
	v_mov_b64_e32 v[8:9], v[0:1]
	v_mov_b64_e32 v[10:11], v[0:1]
	v_mov_b64_e32 v[12:13], v[0:1]
	v_mov_b64_e32 v[14:15], v[0:1]
	v_mov_b64_e32 v[16:17], v[0:1]
	v_mov_b64_e32 v[18:19], v[0:1]
	v_mov_b64_e32 v[20:21], v[0:1]
	v_mov_b64_e32 v[22:23], v[0:1]
	v_mov_b64_e32 v[24:25], v[0:1]
	v_mov_b64_e32 v[26:27], v[0:1]
	v_mov_b64_e32 v[28:29], v[0:1]
	v_mov_b64_e32 v[30:31], v[0:1]
	v_mov_b64_e32 v[32:33], v[0:1]
	v_mov_b64_e32 v[34:35], v[0:1]
	v_mov_b64_e32 v[36:37], v[0:1]
	v_mov_b64_e32 v[38:39], v[0:1]
	v_mov_b64_e32 v[40:41], v[0:1]
	v_mov_b64_e32 v[42:43], v[0:1]
	v_mov_b64_e32 v[44:45], v[0:1]
	v_mov_b64_e32 v[46:47], v[0:1]
	v_mov_b64_e32 v[48:49], v[0:1]
	v_mov_b64_e32 v[50:51], v[0:1]
	v_mov_b64_e32 v[52:53], v[0:1]
	v_mov_b64_e32 v[54:55], v[0:1]
	v_mov_b64_e32 v[56:57], v[0:1]
	v_mov_b64_e32 v[58:59], v[0:1]
	v_mov_b64_e32 v[60:61], v[0:1]
	v_mov_b64_e32 v[62:63], v[0:1]
	v_mov_b64_e32 v[64:65], v[0:1]
	v_mov_b64_e32 v[66:67], v[0:1]
	v_mov_b64_e32 v[68:69], v[0:1]
	v_mov_b64_e32 v[70:71], v[0:1]
	v_mov_b64_e32 v[72:73], v[0:1]
	v_mov_b64_e32 v[74:75], v[0:1]
	v_mov_b64_e32 v[76:77], v[0:1]
	v_mov_b64_e32 v[78:79], v[0:1]
	v_mov_b64_e32 v[80:81], v[0:1]
	v_mov_b64_e32 v[82:83], v[0:1]
	v_mov_b64_e32 v[84:85], v[0:1]
	v_mov_b64_e32 v[86:87], v[0:1]
	v_mov_b64_e32 v[88:89], v[0:1]
	v_mov_b64_e32 v[90:91], v[0:1]
	v_mov_b64_e32 v[92:93], v[0:1]
	v_mov_b64_e32 v[94:95], v[0:1]
	v_mov_b64_e32 v[96:97], v[0:1]
	v_mov_b64_e32 v[98:99], v[0:1]
	v_mov_b64_e32 v[100:101], v[0:1]
	v_mov_b64_e32 v[102:103], v[0:1]
	v_mov_b64_e32 v[104:105], v[0:1]
	v_mov_b64_e32 v[106:107], v[0:1]
	v_mov_b64_e32 v[108:109], v[0:1]
	v_mov_b64_e32 v[110:111], v[0:1]
	v_mov_b64_e32 v[112:113], v[0:1]
	v_mov_b64_e32 v[114:115], v[0:1]
	v_mov_b64_e32 v[116:117], v[0:1]
	v_mov_b64_e32 v[118:119], v[0:1]
	v_mov_b64_e32 v[120:121], v[0:1]
	v_mov_b64_e32 v[122:123], v[0:1]
	v_mov_b64_e32 v[124:125], v[0:1]
	v_mov_b64_e32 v[126:127], v[0:1]
	s_mov_b32 s17, 0
	s_waitcnt vmcnt(16)
	s_barrier
.Lff1_kloop:
	s_cmp_lt_u32 s13, 0x4000
	s_cbranch_scc0 .Lff1_d2
	s_add_u32 m0, s13, 0x8000
	s_nop 0
	global_load_lds_dwordx4 v128, s[22:23]
	global_load_lds_dwordx4 v129, s[22:23] offset:1024
	global_load_lds_dwordx4 v130, s[22:23] offset:2048
	global_load_lds_dwordx4 v131, s[22:23] offset:3072
	s_add_u32 m0, s13, 0x18000
	s_nop 0
	global_load_lds_dwordx4 v132, s[14:15]
	global_load_lds_dwordx4 v133, s[14:15] offset:1024
	global_load_lds_dwordx4 v134, s[14:15] offset:2048
	global_load_lds_dwordx4 v135, s[14:15] offset:3072
	s_add_u32 m0, s13, 0xc000
	s_nop 0
	global_load_lds_dwordx4 v136, s[22:23]
	global_load_lds_dwordx4 v137, s[22:23] offset:1024
	global_load_lds_dwordx4 v138, s[22:23] offset:2048
	global_load_lds_dwordx4 v139, s[22:23] offset:3072
	s_add_u32 m0, s13, 0x1c000
	s_nop 0
	global_load_lds_dwordx4 v140, s[14:15]
	global_load_lds_dwordx4 v141, s[14:15] offset:1024
	global_load_lds_dwordx4 v142, s[14:15] offset:2048
	global_load_lds_dwordx4 v143, s[14:15] offset:3072
; template <class AL, class BL>
; DEV void gemm_ktile(Acc& acc, const char* A, const char* B, int wm, int wn, int lr, int lh, const AL& al, const BL& bl,
;                     int tid, int m0, int n0, int knext, char* nxt, R4& ra, R4& rb) {
;   bf16x8 a[2][4], b[2][2];
;   const char* pa = A + (wm + lr) * LDSROW + lh * 16;
;   const char* pb = B + (wn + lr) * LDSROW + lh * 16;
; #pragma unroll
;   for (int i = 0; i < 4; ++i) a[0][i] = *(const bf16x8*)(pa + 32 * i * LDSROW);
; #pragma unroll
;   for (int j = 0; j < 2; ++j) b[0][j] = *(const bf16x8*)(pb + 32 * j * LDSROW);
; #pragma unroll
;   for (int ks = 0; ks < 4; ++ks) {
;     const int cur = ks & 1, nx = cur ^ 1;
;     if (ks < 3) {
; #pragma unroll
;       for (int i = 0; i < 4; ++i) a[nx][i] = *(const bf16x8*)(pa + 32 * i * LDSROW + (ks + 1) * 32);
; #pragma unroll
;       for (int j = 0; j < 2; ++j) b[nx][j] = *(const bf16x8*)(pb + 32 * j * LDSROW + (ks + 1) * 32);
;     }
;     __builtin_amdgcn_sched_barrier(0);
; #pragma unroll
;     for (int i = 0; i < 4; ++i)
; #pragma unroll
;       for (int j = 0; j < 2; ++j)
;         acc[i][j] = __builtin_amdgcn_mfma_f32_32x32x16_bf16(a[cur][i], b[cur][j], acc[i][j], 0, 0, 0);
;     __builtin_amdgcn_sched_barrier(0);
;     if (ks == 1) {
;       al.store(tid, nxt, ra);
;       bl.store(tid, nxt + TILE_BYTES, rb);
;       __builtin_amdgcn_sched_barrier(0);
;       ra = al.load(tid, m0, knext);
;       rb = bl.load(tid, n0, knext);
;       __builtin_amdgcn_sched_barrier(0);
;     }
;   }
; }
.Lff1_d2:
	s_add_u32 s22, s22, 0x80
	s_addc_u32 s23, s23, 0
	s_add_u32 s14, s14, 0x80
	s_addc_u32 s15, s15, 0
	ds_read_b128 v[166:169], v146
	ds_read_b128 v[170:173], v146 offset:2048
	ds_read_b128 v[174:177], v146 offset:4096
	ds_read_b128 v[178:181], v146 offset:6144
	ds_read_b128 v[222:225], v144
	ds_read_b128 v[226:229], v144 offset:2048
	ds_read_b128 v[230:233], v144 offset:4096
	ds_read_b128 v[234:237], v144 offset:6144
	ds_read_b128 v[238:241], v144 offset:8192
	ds_read_b128 v[198:201], v144 offset:10240
	ds_read_b128 v[152:155], v144 offset:12288
	ds_read_b128 v[156:159], v144 offset:14336
	ds_read_b128 v[182:185], v147
	ds_read_b128 v[186:189], v147 offset:2048
	ds_read_b128 v[190:193], v147 offset:4096
	ds_read_b128 v[194:197], v147 offset:6144
	s_waitcnt lgkmcnt(8)
	v_mfma_f32_16x16x32_bf16 v[0:3], v[166:169], v[222:225], v[0:3]
	v_mfma_f32_16x16x32_bf16 v[4:7], v[170:173], v[222:225], v[4:7]
	v_mfma_f32_16x16x32_bf16 v[8:11], v[174:177], v[222:225], v[8:11]
	v_mfma_f32_16x16x32_bf16 v[12:15], v[178:181], v[222:225], v[12:15]
	v_mfma_f32_16x16x32_bf16 v[16:19], v[166:169], v[226:229], v[16:19]
	v_mfma_f32_16x16x32_bf16 v[20:23], v[170:173], v[226:229], v[20:23]
	v_mfma_f32_16x16x32_bf16 v[24:27], v[174:177], v[226:229], v[24:27]
	v_mfma_f32_16x16x32_bf16 v[28:31], v[178:181], v[226:229], v[28:31]
	v_mfma_f32_16x16x32_bf16 v[32:35], v[166:169], v[230:233], v[32:35]
	v_mfma_f32_16x16x32_bf16 v[36:39], v[170:173], v[230:233], v[36:39]
	v_mfma_f32_16x16x32_bf16 v[40:43], v[174:177], v[230:233], v[40:43]
	v_mfma_f32_16x16x32_bf16 v[44:47], v[178:181], v[230:233], v[44:47]
	v_mfma_f32_16x16x32_bf16 v[48:51], v[166:169], v[234:237], v[48:51]
	v_mfma_f32_16x16x32_bf16 v[52:55], v[170:173], v[234:237], v[52:55]
	v_mfma_f32_16x16x32_bf16 v[56:59], v[174:177], v[234:237], v[56:59]
	v_mfma_f32_16x16x32_bf16 v[60:63], v[178:181], v[234:237], v[60:63]
	ds_read_b128 v[222:225], v145
	ds_read_b128 v[226:229], v145 offset:2048
	ds_read_b128 v[230:233], v145 offset:4096
	ds_read_b128 v[234:237], v145 offset:6144
	s_waitcnt lgkmcnt(8)
	v_mfma_f32_16x16x32_bf16 v[64:67], v[166:169], v[238:241], v[64:67]
	v_mfma_f32_16x16x32_bf16 v[68:71], v[170:173], v[238:241], v[68:71]
	v_mfma_f32_16x16x32_bf16 v[72:75], v[174:177], v[238:241], v[72:75]
	v_mfma_f32_16x16x32_bf16 v[76:79], v[178:181], v[238:241], v[76:79]
	v_mfma_f32_16x16x32_bf16 v[80:83], v[166:169], v[198:201], v[80:83]
	v_mfma_f32_16x16x32_bf16 v[84:87], v[170:173], v[198:201], v[84:87]
	v_mfma_f32_16x16x32_bf16 v[88:91], v[174:177], v[198:201], v[88:91]
	v_mfma_f32_16x16x32_bf16 v[92:95], v[178:181], v[198:201], v[92:95]
	v_mfma_f32_16x16x32_bf16 v[96:99], v[166:169], v[152:155], v[96:99]
	v_mfma_f32_16x16x32_bf16 v[100:103], v[170:173], v[152:155], v[100:103]
	v_mfma_f32_16x16x32_bf16 v[104:107], v[174:177], v[152:155], v[104:107]
	v_mfma_f32_16x16x32_bf16 v[108:111], v[178:181], v[152:155], v[108:111]
	v_mfma_f32_16x16x32_bf16 v[112:115], v[166:169], v[156:159], v[112:115]
	v_mfma_f32_16x16x32_bf16 v[116:119], v[170:173], v[156:159], v[116:119]
	v_mfma_f32_16x16x32_bf16 v[120:123], v[174:177], v[156:159], v[120:123]
	v_mfma_f32_16x16x32_bf16 v[124:127], v[178:181], v[156:159], v[124:127]
	ds_read_b128 v[238:241], v145 offset:8192
	ds_read_b128 v[198:201], v145 offset:10240
	ds_read_b128 v[152:155], v145 offset:12288
	ds_read_b128 v[156:159], v145 offset:14336
	s_waitcnt lgkmcnt(4)
	v_mfma_f32_16x16x32_bf16 v[0:3], v[182:185], v[222:225], v[0:3]
	v_mfma_f32_16x16x32_bf16 v[4:7], v[186:189], v[222:225], v[4:7]
	v_mfma_f32_16x16x32_bf16 v[8:11], v[190:193], v[222:225], v[8:11]
	v_mfma_f32_16x16x32_bf16 v[12:15], v[194:197], v[222:225], v[12:15]
	v_mfma_f32_16x16x32_bf16 v[16:19], v[182:185], v[226:229], v[16:19]
	v_mfma_f32_16x16x32_bf16 v[20:23], v[186:189], v[226:229], v[20:23]
	v_mfma_f32_16x16x32_bf16 v[24:27], v[190:193], v[226:229], v[24:27]
	v_mfma_f32_16x16x32_bf16 v[28:31], v[194:197], v[226:229], v[28:31]
	v_mfma_f32_16x16x32_bf16 v[32:35], v[182:185], v[230:233], v[32:35]
	v_mfma_f32_16x16x32_bf16 v[36:39], v[186:189], v[230:233], v[36:39]
	v_mfma_f32_16x16x32_bf16 v[40:43], v[190:193], v[230:233], v[40:43]
	v_mfma_f32_16x16x32_bf16 v[44:47], v[194:197], v[230:233], v[44:47]
	v_mfma_f32_16x16x32_bf16 v[48:51], v[182:185], v[234:237], v[48:51]
	v_mfma_f32_16x16x32_bf16 v[52:55], v[186:189], v[234:237], v[52:55]
	v_mfma_f32_16x16x32_bf16 v[56:59], v[190:193], v[234:237], v[56:59]
	v_mfma_f32_16x16x32_bf16 v[60:63], v[194:197], v[234:237], v[60:63]
	s_waitcnt lgkmcnt(0)
	v_mfma_f32_16x16x32_bf16 v[64:67], v[182:185], v[238:241], v[64:67]
	v_mfma_f32_16x16x32_bf16 v[68:71], v[186:189], v[238:241], v[68:71]
	v_mfma_f32_16x16x32_bf16 v[72:75], v[190:193], v[238:241], v[72:75]
	v_mfma_f32_16x16x32_bf16 v[76:79], v[194:197], v[238:241], v[76:79]
	v_mfma_f32_16x16x32_bf16 v[80:83], v[182:185], v[198:201], v[80:83]
	v_mfma_f32_16x16x32_bf16 v[84:87], v[186:189], v[198:201], v[84:87]
	v_mfma_f32_16x16x32_bf16 v[88:91], v[190:193], v[198:201], v[88:91]
	v_mfma_f32_16x16x32_bf16 v[92:95], v[194:197], v[198:201], v[92:95]
	v_mfma_f32_16x16x32_bf16 v[96:99], v[182:185], v[152:155], v[96:99]
	v_mfma_f32_16x16x32_bf16 v[100:103], v[186:189], v[152:155], v[100:103]
	v_mfma_f32_16x16x32_bf16 v[104:107], v[190:193], v[152:155], v[104:107]
	v_mfma_f32_16x16x32_bf16 v[108:111], v[194:197], v[152:155], v[108:111]
	v_mfma_f32_16x16x32_bf16 v[112:115], v[182:185], v[156:159], v[112:115]
	v_mfma_f32_16x16x32_bf16 v[116:119], v[186:189], v[156:159], v[116:119]
	v_mfma_f32_16x16x32_bf16 v[120:123], v[190:193], v[156:159], v[120:123]
	v_mfma_f32_16x16x32_bf16 v[124:127], v[194:197], v[156:159], v[124:127]
	s_waitcnt vmcnt(0)
	s_barrier
	s_cmp_eq_u32 s17, 7
	s_cbranch_scc1 .Lff1_last
	s_cmp_lt_u32 s13, 0x4000
	s_cbranch_scc0 .Lff1_d3
	s_add_u32 m0, s13, 0x0
	s_nop 0
	global_load_lds_dwordx4 v128, s[22:23]
	global_load_lds_dwordx4 v129, s[22:23] offset:1024
	global_load_lds_dwordx4 v130, s[22:23] offset:2048
	global_load_lds_dwordx4 v131, s[22:23] offset:3072
	s_add_u32 m0, s13, 0x10000
	s_nop 0
	global_load_lds_dwordx4 v132, s[14:15]
	global_load_lds_dwordx4 v133, s[14:15] offset:1024
	global_load_lds_dwordx4 v134, s[14:15] offset:2048
	global_load_lds_dwordx4 v135, s[14:15] offset:3072
	s_add_u32 m0, s13, 0x4000
	s_nop 0
	global_load_lds_dwordx4 v136, s[22:23]
	global_load_lds_dwordx4 v137, s[22:23] offset:1024
	global_load_lds_dwordx4 v138, s[22:23] offset:2048
	global_load_lds_dwordx4 v139, s[22:23] offset:3072
	s_add_u32 m0, s13, 0x14000
	s_nop 0
	global_load_lds_dwordx4 v140, s[14:15]
	global_load_lds_dwordx4 v141, s[14:15] offset:1024
	global_load_lds_dwordx4 v142, s[14:15] offset:2048
	global_load_lds_dwordx4 v143, s[14:15] offset:3072

; template <class AL, class BL>
; DEV void gemm_ktile(Acc& acc, const char* A, const char* B, int wm, int wn, int lr, int lh, const AL& al, const BL& bl,
;                     int tid, int m0, int n0, int knext, char* nxt, R4& ra, R4& rb) {
;   bf16x8 a[2][4], b[2][2];
;   const char* pa = A + (wm + lr) * LDSROW + lh * 16;
;   const char* pb = B + (wn + lr) * LDSROW + lh * 16;
; #pragma unroll
;   for (int i = 0; i < 4; ++i) a[0][i] = *(const bf16x8*)(pa + 32 * i * LDSROW);
; #pragma unroll
;   for (int j = 0; j < 2; ++j) b[0][j] = *(const bf16x8*)(pb + 32 * j * LDSROW);
; #pragma unroll
;   for (int ks = 0; ks < 4; ++ks) {
;     const int cur = ks & 1, nx = cur ^ 1;
;     if (ks < 3) {
; #pragma unroll
;       for (int i = 0; i < 4; ++i) a[nx][i] = *(const bf16x8*)(pa + 32 * i * LDSROW + (ks + 1) * 32);
; #pragma unroll
;       for (int j = 0; j < 2; ++j) b[nx][j] = *(const bf16x8*)(pb + 32 * j * LDSROW + (ks + 1) * 32);
;     }
;     __builtin_amdgcn_sched_barrier(0);
; #pragma unroll
;     for (int i = 0; i < 4; ++i)
; #pragma unroll
;       for (int j = 0; j < 2; ++j)
;         acc[i][j] = __builtin_amdgcn_mfma_f32_32x32x16_bf16(a[cur][i], b[cur][j], acc[i][j], 0, 0, 0);
.Lff1_last:
	ds_read_b128 v[166:169], v146 offset:32768
	ds_read_b128 v[170:173], v146 offset:34816
	ds_read_b128 v[174:177], v146 offset:36864
	ds_read_b128 v[178:181], v146 offset:38912
	ds_read_b128 v[222:225], v144 offset:32768
	ds_read_b128 v[226:229], v144 offset:34816
	ds_read_b128 v[230:233], v144 offset:36864
	ds_read_b128 v[234:237], v144 offset:38912
	ds_read_b128 v[238:241], v144 offset:40960
	ds_read_b128 v[198:201], v144 offset:43008
	ds_read_b128 v[152:155], v144 offset:45056
	ds_read_b128 v[156:159], v144 offset:47104
	ds_read_b128 v[182:185], v147 offset:32768
	ds_read_b128 v[186:189], v147 offset:34816
	ds_read_b128 v[190:193], v147 offset:36864
	ds_read_b128 v[194:197], v147 offset:38912
	s_waitcnt lgkmcnt(8)
	v_mfma_f32_16x16x32_bf16 v[0:3], v[166:169], v[222:225], v[0:3]
	v_mfma_f32_16x16x32_bf16 v[4:7], v[170:173], v[222:225], v[4:7]
	v_mfma_f32_16x16x32_bf16 v[8:11], v[174:177], v[222:225], v[8:11]
	v_mfma_f32_16x16x32_bf16 v[12:15], v[178:181], v[222:225], v[12:15]
	v_mfma_f32_16x16x32_bf16 v[16:19], v[166:169], v[226:229], v[16:19]
	v_mfma_f32_16x16x32_bf16 v[20:23], v[170:173], v[226:229], v[20:23]
	v_mfma_f32_16x16x32_bf16 v[24:27], v[174:177], v[226:229], v[24:27]
	v_mfma_f32_16x16x32_bf16 v[28:31], v[178:181], v[226:229], v[28:31]
	v_mfma_f32_16x16x32_bf16 v[32:35], v[166:169], v[230:233], v[32:35]
	v_mfma_f32_16x16x32_bf16 v[36:39], v[170:173], v[230:233], v[36:39]
	v_mfma_f32_16x16x32_bf16 v[40:43], v[174:177], v[230:233], v[40:43]
	v_mfma_f32_16x16x32_bf16 v[44:47], v[178:181], v[230:233], v[44:47]
	v_mfma_f32_16x16x32_bf16 v[48:51], v[166:169], v[234:237], v[48:51]
	v_mfma_f32_16x16x32_bf16 v[52:55], v[170:173], v[234:237], v[52:55]
	v_mfma_f32_16x16x32_bf16 v[56:59], v[174:177], v[234:237], v[56:59]
	v_mfma_f32_16x16x32_bf16 v[60:63], v[178:181], v[234:237], v[60:63]
	ds_read_b128 v[222:225], v145 offset:32768
	ds_read_b128 v[226:229], v145 offset:34816
	ds_read_b128 v[230:233], v145 offset:36864
	ds_read_b128 v[234:237], v145 offset:38912
	s_waitcnt lgkmcnt(8)
	v_mfma_f32_16x16x32_bf16 v[64:67], v[166:169], v[238:241], v[64:67]
	v_mfma_f32_16x16x32_bf16 v[68:71], v[170:173], v[238:241], v[68:71]
	v_mfma_f32_16x16x32_bf16 v[72:75], v[174:177], v[238:241], v[72:75]
	v_mfma_f32_16x16x32_bf16 v[76:79], v[178:181], v[238:241], v[76:79]
	v_mfma_f32_16x16x32_bf16 v[80:83], v[166:169], v[198:201], v[80:83]
	v_mfma_f32_16x16x32_bf16 v[84:87], v[170:173], v[198:201], v[84:87]
	v_mfma_f32_16x16x32_bf16 v[88:91], v[174:177], v[198:201], v[88:91]
	v_mfma_f32_16x16x32_bf16 v[92:95], v[178:181], v[198:201], v[92:95]
	v_mfma_f32_16x16x32_bf16 v[96:99], v[166:169], v[152:155], v[96:99]
	v_mfma_f32_16x16x32_bf16 v[100:103], v[170:173], v[152:155], v[100:103]
	v_mfma_f32_16x16x32_bf16 v[104:107], v[174:177], v[152:155], v[104:107]
	v_mfma_f32_16x16x32_bf16 v[108:111], v[178:181], v[152:155], v[108:111]
	v_mfma_f32_16x16x32_bf16 v[112:115], v[166:169], v[156:159], v[112:115]
	v_mfma_f32_16x16x32_bf16 v[116:119], v[170:173], v[156:159], v[116:119]
	v_mfma_f32_16x16x32_bf16 v[120:123], v[174:177], v[156:159], v[120:123]
	v_mfma_f32_16x16x32_bf16 v[124:127], v[178:181], v[156:159], v[124:127]
	ds_read_b128 v[238:241], v145 offset:40960
	ds_read_b128 v[198:201], v145 offset:43008
	ds_read_b128 v[152:155], v145 offset:45056
	ds_read_b128 v[156:159], v145 offset:47104
	s_waitcnt lgkmcnt(4)
	v_mfma_f32_16x16x32_bf16 v[0:3], v[182:185], v[222:225], v[0:3]
	v_mfma_f32_16x16x32_bf16 v[4:7], v[186:189], v[222:225], v[4:7]
	v_mfma_f32_16x16x32_bf16 v[8:11], v[190:193], v[222:225], v[8:11]
	v_mfma_f32_16x16x32_bf16 v[12:15], v[194:197], v[222:225], v[12:15]
	v_mfma_f32_16x16x32_bf16 v[16:19], v[182:185], v[226:229], v[16:19]
	v_mfma_f32_16x16x32_bf16 v[20:23], v[186:189], v[226:229], v[20:23]
	v_mfma_f32_16x16x32_bf16 v[24:27], v[190:193], v[226:229], v[24:27]
	v_mfma_f32_16x16x32_bf16 v[28:31], v[194:197], v[226:229], v[28:31]
	v_mfma_f32_16x16x32_bf16 v[32:35], v[182:185], v[230:233], v[32:35]
	v_mfma_f32_16x16x32_bf16 v[36:39], v[186:189], v[230:233], v[36:39]
	v_mfma_f32_16x16x32_bf16 v[40:43], v[190:193], v[230:233], v[40:43]
	v_mfma_f32_16x16x32_bf16 v[44:47], v[194:197], v[230:233], v[44:47]
	v_mfma_f32_16x16x32_bf16 v[48:51], v[182:185], v[234:237], v[48:51]
	v_mfma_f32_16x16x32_bf16 v[52:55], v[186:189], v[234:237], v[52:55]
	v_mfma_f32_16x16x32_bf16 v[56:59], v[190:193], v[234:237], v[56:59]
	v_mfma_f32_16x16x32_bf16 v[60:63], v[194:197], v[234:237], v[60:63]
	s_waitcnt lgkmcnt(0)
	v_mfma_f32_16x16x32_bf16 v[64:67], v[182:185], v[238:241], v[64:67]
	v_mfma_f32_16x16x32_bf16 v[68:71], v[186:189], v[238:241], v[68:71]
	v_mfma_f32_16x16x32_bf16 v[72:75], v[190:193], v[238:241], v[72:75]
	v_mfma_f32_16x16x32_bf16 v[76:79], v[194:197], v[238:241], v[76:79]
	v_mfma_f32_16x16x32_bf16 v[80:83], v[182:185], v[198:201], v[80:83]
	v_mfma_f32_16x16x32_bf16 v[84:87], v[186:189], v[198:201], v[84:87]
	v_mfma_f32_16x16x32_bf16 v[88:91], v[190:193], v[198:201], v[88:91]
	v_mfma_f32_16x16x32_bf16 v[92:95], v[194:197], v[198:201], v[92:95]
	v_mfma_f32_16x16x32_bf16 v[96:99], v[182:185], v[152:155], v[96:99]
	v_mfma_f32_16x16x32_bf16 v[100:103], v[186:189], v[152:155], v[100:103]
	v_mfma_f32_16x16x32_bf16 v[104:107], v[190:193], v[152:155], v[104:107]
	v_mfma_f32_16x16x32_bf16 v[108:111], v[194:197], v[152:155], v[108:111]
	v_mfma_f32_16x16x32_bf16 v[112:115], v[182:185], v[156:159], v[112:115]
	v_mfma_f32_16x16x32_bf16 v[116:119], v[186:189], v[156:159], v[116:119]
	v_mfma_f32_16x16x32_bf16 v[120:123], v[190:193], v[156:159], v[120:123]
	v_mfma_f32_16x16x32_bf16 v[124:127], v[194:197], v[156:159], v[124:127]
	s_barrier
; DEV void phase_ff1(const Params& p, int g, char* smem) {
;     ...
;     const bool more = tile_map(iter + 1, 128, 16, mtn, ntn);
;     if (!more) { mtn = mt; ntn = nt; }
;     const int m0 = mt * 256, n0 = nt * 256;
;     Acc acc;
;     acc_zero(acc);
;     RowLoader al{H2, 1024}, bl{W, 1024};
;     gemm_mainloop_p(acc, al, bl, m0, n0, mtn * 256, ntn * 256, 1024, smem, gp);
;     gp.primed = more;
	s_and_b64 vcc, exec, s[0:1]
	s_cbranch_vccz .Lff1_nomore
	s_lshl_b32 s7, s11, 8
	s_lshl_b32 s8, s12, 8
	v_add_u32_e32 v128, s7, v150
	v_lshlrev_b32_e32 v128, 11, v128
	v_add_u32_e32 v128, v128, v151
	v_add_u32_e32 v129, 0x3c00, v128
	v_add_u32_e32 v130, 0x7800, v128
	v_add_u32_e32 v131, 0xb400, v128
	v_xor_b32_e32 v129, 0x40, v129
	v_xor_b32_e32 v131, 0x40, v131
	v_add_u32_e32 v132, s8, v150
	v_lshlrev_b32_e32 v132, 11, v132
	v_add_u32_e32 v132, v132, v151
	v_add_u32_e32 v133, 0x3c00, v132
	v_add_u32_e32 v134, 0x7800, v132
	v_add_u32_e32 v135, 0xb400, v132
	v_xor_b32_e32 v133, 0x40, v133
	v_xor_b32_e32 v135, 0x40, v135
	v_add_u32_e32 v136, 0x40000, v128
	v_add_u32_e32 v137, 0x40000, v129
	v_add_u32_e32 v138, 0x40000, v130
	v_add_u32_e32 v139, 0x40000, v131
	v_add_u32_e32 v140, 0x40000, v132
	v_add_u32_e32 v141, 0x40000, v133
	v_add_u32_e32 v142, 0x40000, v134
	v_add_u32_e32 v143, 0x40000, v135
	s_mov_b64 s[22:23], s[18:19]
	s_mov_b64 s[14:15], s[20:21]
	s_cmp_lt_u32 s13, 0x4000
	s_cbranch_scc0 .Lff1_d4
	s_add_u32 m0, s13, 0x0
	s_nop 0
	global_load_lds_dwordx4 v128, s[22:23]
	global_load_lds_dwordx4 v129, s[22:23] offset:1024
	global_load_lds_dwordx4 v130, s[22:23] offset:2048
	global_load_lds_dwordx4 v131, s[22:23] offset:3072
	s_add_u32 m0, s13, 0x10000
	s_nop 0
	global_load_lds_dwordx4 v132, s[14:15]
	global_load_lds_dwordx4 v133, s[14:15] offset:1024
	global_load_lds_dwordx4 v134, s[14:15] offset:2048
	global_load_lds_dwordx4 v135, s[14:15] offset:3072
	s_add_u32 m0, s13, 0x4000
	s_nop 0
	global_load_lds_dwordx4 v136, s[22:23]
	global_load_lds_dwordx4 v137, s[22:23] offset:1024
	global_load_lds_dwordx4 v138, s[22:23] offset:2048
	global_load_lds_dwordx4 v139, s[22:23] offset:3072
	s_add_u32 m0, s13, 0x14000
	s_nop 0
	global_load_lds_dwordx4 v140, s[14:15]
	global_load_lds_dwordx4 v141, s[14:15] offset:1024
	global_load_lds_dwordx4 v142, s[14:15] offset:2048
	global_load_lds_dwordx4 v143, s[14:15] offset:3072

; template <class AL, class BL>
; DEV void gemm_mainloop(Acc& acc, const AL& al, const BL& bl, int m0, int n0, int kbeg, int kend, char* lds) {
;   const int tid = tidx_full();
;   const int wave = tid >> 6, lane = tid & 63;
;   const int wm = (wave >> 2) * 128, wn = (wave & 3) * 64;
;   const int lr = lane & 31, lh = lane >> 5;
;   const int nk = (kend - kbeg) / BK;
;   R4 a0 = al.load(tid, m0, kbeg);
;   R4 b0 = bl.load(tid, n0, kbeg);
;   __syncthreads();
;   al.store(tid, lds, a0);
;   bl.store(tid, lds + TILE_BYTES, b0);
;   a0 = al.load(tid, m0, kbeg + BK);
;   b0 = bl.load(tid, n0, kbeg + BK);
;   __syncthreads();
; DEV void phase_ff2(const Params& p, int g, char* smem) {
;     ...
;   for (int iter = 0;; ++iter) {
;     int mt, nt;
;     if (!tile_map(iter, 128, 4, mt, nt)) break;
;     const int m0 = mt * 256, n0 = nt * 256;
;     Acc acc;
;     acc_zero(acc);
;     RowLoader al{AB, 4096}, bl{W, 4096};
;     gemm_mainloop(acc, al, bl, m0, n0, 0, 4096, smem);
.LBB0_1192:
	s_lshl_b32 s3, s5, 8
	s_lshl_b32 s2, s6, 8
	v_readlane_b32 s0, v251, 30
	v_readlane_b32 s1, v251, 31
	s_mov_b64 s[6:7], s[74:75]
	v_lshrrev_b32_e32 v149, 6, v202
	v_and_b32_e32 v148, 63, v202
	s_nop 0
	v_readfirstlane_b32 s8, v149
	v_lshrrev_b32_e32 v150, 3, v148
	v_lshl_add_u32 v150, v149, 5, v150
	v_and_b32_e32 v151, 7, v148
	v_lshrrev_b32_e32 v128, 4, v148
	v_xor_b32_e32 v151, v128, v151
	v_lshlrev_b32_e32 v151, 4, v151
	s_lshl_b32 s8, s8, 12
	v_add_u32_e32 v128, s3, v150
	v_lshlrev_b32_e32 v128, 13, v128
	v_add_u32_e32 v128, v128, v151
	v_add_u32_e32 v129, 0xfc00, v128
	v_add_u32_e32 v130, 0x1f800, v128
	v_add_u32_e32 v131, 0x2f400, v128
	v_xor_b32_e32 v129, 0x40, v129
	v_xor_b32_e32 v131, 0x40, v131
	v_add_u32_e32 v132, s2, v150
	v_lshlrev_b32_e32 v132, 13, v132
	v_add_u32_e32 v132, v132, v151
	v_add_u32_e32 v133, 0xfc00, v132
	v_add_u32_e32 v134, 0x1f800, v132
	v_add_u32_e32 v135, 0x2f400, v132
	v_xor_b32_e32 v133, 0x40, v133
	v_xor_b32_e32 v135, 0x40, v135
	v_lshrrev_b32_e32 v150, 1, v148
	v_and_b32_e32 v150, 7, v150
	v_lshrrev_b32_e32 v151, 5, v148
	v_xor_b32_e32 v150, v150, v151
	v_lshlrev_b32_e32 v150, 4, v150
	v_and_b32_e32 v151, 31, v148
	v_lshlrev_b32_e32 v151, 7, v151
	v_lshrrev_b32_e32 v156, 2, v149
	v_lshl_add_u32 v156, v156, 14, v151
	v_and_b32_e32 v207, 3, v149
	v_lshl_add_u32 v207, v207, 13, v151
	v_add_u32_e32 v207, 0x10000, v207
	v_xor_b32_e32 v159, 0x60, v150
	v_add_u32_e32 v159, v156, v159
	v_xor_b32_e32 v158, 0x40, v150
	v_add_u32_e32 v158, v156, v158
	v_xor_b32_e32 v157, 0x20, v150
	v_add_u32_e32 v157, v156, v157
	v_add_u32_e32 v156, v156, v150
	v_xor_b32_e32 v210, 0x60, v150
	v_add_u32_e32 v210, v207, v210
	v_xor_b32_e32 v209, 0x40, v150
	v_add_u32_e32 v209, v207, v209
	v_xor_b32_e32 v208, 0x20, v150
	v_add_u32_e32 v208, v207, v208
	v_add_u32_e32 v207, v207, v150
	v_add_u32_e32 v136, 0x100000, v128
	v_add_u32_e32 v137, 0x100000, v129
	v_add_u32_e32 v138, 0x100000, v130
	v_add_u32_e32 v139, 0x100000, v131
	v_add_u32_e32 v140, 0x100000, v132
	v_add_u32_e32 v141, 0x100000, v133
	v_add_u32_e32 v142, 0x100000, v134
	v_add_u32_e32 v143, 0x100000, v135
	v_lshrrev_b32_e32 v149, 6, v202
	v_and_b32_e32 v148, 63, v202
	v_bfe_u32 v150, v148, 1, 3
	v_lshrrev_b32_e32 v151, 4, v148
	v_xor_b32_e32 v150, v150, v151
	v_lshlrev_b32_e32 v150, 4, v150
	v_and_b32_e32 v151, 15, v148
	v_lshlrev_b32_e32 v151, 7, v151
	v_lshrrev_b32_e32 v144, 2, v149
	v_lshl_add_u32 v144, v144, 14, v151
	v_and_b32_e32 v146, 3, v149
	v_lshl_add_u32 v146, v146, 13, v151
	v_add_u32_e32 v146, 0x10000, v146
	v_xor_b32_e32 v145, 0x40, v150
	v_add_u32_e32 v145, v144, v145
	v_add_u32_e32 v144, v144, v150
	v_xor_b32_e32 v147, 0x40, v150
	v_add_u32_e32 v147, v146, v147
	v_add_u32_e32 v146, v146, v150
	v_mov_b32_e32 v0, 0
	v_mov_b32_e32 v1, 0
	v_mov_b64_e32 v[2:3], v[0:1]
	v_mov_b64_e32 v[4:5], v[0:1]
	v_mov_b64_e32 v[6:7], v[0:1]
	v_mov_b64_e32 v[8:9], v[0:1]
	v_mov_b64_e32 v[10:11], v[0:1]
	v_mov_b64_e32 v[12:13], v[0:1]
	v_mov_b64_e32 v[14:15], v[0:1]
	v_mov_b64_e32 v[16:17], v[0:1]
	v_mov_b64_e32 v[18:19], v[0:1]
	v_mov_b64_e32 v[20:21], v[0:1]
	v_mov_b64_e32 v[22:23], v[0:1]
	v_mov_b64_e32 v[24:25], v[0:1]
	v_mov_b64_e32 v[26:27], v[0:1]
	v_mov_b64_e32 v[28:29], v[0:1]
	v_mov_b64_e32 v[30:31], v[0:1]
	v_mov_b64_e32 v[32:33], v[0:1]
	v_mov_b64_e32 v[34:35], v[0:1]
	v_mov_b64_e32 v[36:37], v[0:1]
	v_mov_b64_e32 v[38:39], v[0:1]
	v_mov_b64_e32 v[40:41], v[0:1]
	v_mov_b64_e32 v[42:43], v[0:1]
	v_mov_b64_e32 v[44:45], v[0:1]
	v_mov_b64_e32 v[46:47], v[0:1]
	v_mov_b64_e32 v[48:49], v[0:1]
	v_mov_b64_e32 v[50:51], v[0:1]
	v_mov_b64_e32 v[52:53], v[0:1]
	v_mov_b64_e32 v[54:55], v[0:1]
	v_mov_b64_e32 v[56:57], v[0:1]
	v_mov_b64_e32 v[58:59], v[0:1]
	v_mov_b64_e32 v[60:61], v[0:1]
	v_mov_b64_e32 v[62:63], v[0:1]
	v_mov_b64_e32 v[64:65], v[0:1]
	v_mov_b64_e32 v[66:67], v[0:1]
	v_mov_b64_e32 v[68:69], v[0:1]
	v_mov_b64_e32 v[70:71], v[0:1]
	v_mov_b64_e32 v[72:73], v[0:1]
	v_mov_b64_e32 v[74:75], v[0:1]
	v_mov_b64_e32 v[76:77], v[0:1]
	v_mov_b64_e32 v[78:79], v[0:1]
	v_mov_b64_e32 v[80:81], v[0:1]
	v_mov_b64_e32 v[82:83], v[0:1]
	v_mov_b64_e32 v[84:85], v[0:1]
	v_mov_b64_e32 v[86:87], v[0:1]
	v_mov_b64_e32 v[88:89], v[0:1]
	v_mov_b64_e32 v[90:91], v[0:1]
	v_mov_b64_e32 v[92:93], v[0:1]
	v_mov_b64_e32 v[94:95], v[0:1]
	v_mov_b64_e32 v[96:97], v[0:1]
	v_mov_b64_e32 v[98:99], v[0:1]
	v_mov_b64_e32 v[100:101], v[0:1]
	v_mov_b64_e32 v[102:103], v[0:1]
	v_mov_b64_e32 v[104:105], v[0:1]
	v_mov_b64_e32 v[106:107], v[0:1]
	v_mov_b64_e32 v[108:109], v[0:1]
	v_mov_b64_e32 v[110:111], v[0:1]
	v_mov_b64_e32 v[112:113], v[0:1]
	v_mov_b64_e32 v[114:115], v[0:1]
	v_mov_b64_e32 v[116:117], v[0:1]
	v_mov_b64_e32 v[118:119], v[0:1]
	v_mov_b64_e32 v[120:121], v[0:1]
	v_mov_b64_e32 v[122:123], v[0:1]
	v_mov_b64_e32 v[124:125], v[0:1]
	v_mov_b64_e32 v[126:127], v[0:1]
	s_cmp_lt_u32 s8, 0x4000
	s_cbranch_scc0 .Lff2_d1
	s_add_u32 m0, s8, 0x0
	s_nop 0
	global_load_lds_dwordx4 v128, s[6:7]
	global_load_lds_dwordx4 v129, s[6:7] offset:1024
	global_load_lds_dwordx4 v130, s[6:7] offset:2048
	global_load_lds_dwordx4 v131, s[6:7] offset:3072
	s_add_u32 m0, s8, 0x10000
	s_nop 0
	global_load_lds_dwordx4 v132, s[0:1]
	global_load_lds_dwordx4 v133, s[0:1] offset:1024
	global_load_lds_dwordx4 v134, s[0:1] offset:2048
	global_load_lds_dwordx4 v135, s[0:1] offset:3072
	s_add_u32 m0, s8, 0x4000
	s_nop 0
	global_load_lds_dwordx4 v136, s[6:7]
	global_load_lds_dwordx4 v137, s[6:7] offset:1024
	global_load_lds_dwordx4 v138, s[6:7] offset:2048
	global_load_lds_dwordx4 v139, s[6:7] offset:3072
	s_add_u32 m0, s8, 0x14000
	s_nop 0
	global_load_lds_dwordx4 v140, s[0:1]
	global_load_lds_dwordx4 v141, s[0:1] offset:1024
	global_load_lds_dwordx4 v142, s[0:1] offset:2048
	global_load_lds_dwordx4 v143, s[0:1] offset:3072

; template <class AL, class BL>
; DEV void gemm_mainloop(Acc& acc, const AL& al, const BL& bl, int m0, int n0, int kbeg, int kend, char* lds) {
;     ...
;   for (int kt = 0; kt < nk; ++kt) {
;     const char* cur = lds + (kt & 1) * 2 * TILE_BYTES;
;     char* nxt = lds + ((kt + 1) & 1) * 2 * TILE_BYTES;
;     const int t2 = (kt + 2 < nk) ? kt + 2 : nk - 1;
;     __builtin_amdgcn_sched_barrier(0);
;     gemm_ktile(acc, cur, cur + TILE_BYTES, wm, wn, lr, lh, al, bl, tid, m0, n0, kbeg + t2 * BK, nxt, a0, b0);
.Lff2_kloop:
	s_cmp_lt_u32 s8, 0x4000
	s_cbranch_scc0 .Lff2_d2
	s_add_u32 m0, s8, 0x8000
	s_nop 0
	global_load_lds_dwordx4 v128, s[6:7]
	global_load_lds_dwordx4 v129, s[6:7] offset:1024
	global_load_lds_dwordx4 v130, s[6:7] offset:2048
	global_load_lds_dwordx4 v131, s[6:7] offset:3072
	s_add_u32 m0, s8, 0x18000
	s_nop 0
	global_load_lds_dwordx4 v132, s[0:1]
	global_load_lds_dwordx4 v133, s[0:1] offset:1024
	global_load_lds_dwordx4 v134, s[0:1] offset:2048
	global_load_lds_dwordx4 v135, s[0:1] offset:3072
	s_add_u32 m0, s8, 0xc000
	s_nop 0
	global_load_lds_dwordx4 v136, s[6:7]
	global_load_lds_dwordx4 v137, s[6:7] offset:1024
	global_load_lds_dwordx4 v138, s[6:7] offset:2048
	global_load_lds_dwordx4 v139, s[6:7] offset:3072
	s_add_u32 m0, s8, 0x1c000
	s_nop 0
	global_load_lds_dwordx4 v140, s[0:1]
	global_load_lds_dwordx4 v141, s[0:1] offset:1024
	global_load_lds_dwordx4 v142, s[0:1] offset:2048
	global_load_lds_dwordx4 v143, s[0:1] offset:3072
; template <class AL, class BL>
; DEV void gemm_ktile(Acc& acc, const char* A, const char* B, int wm, int wn, int lr, int lh, const AL& al, const BL& bl,
;                     int tid, int m0, int n0, int knext, char* nxt, R4& ra, R4& rb) {
;   bf16x8 a[2][4], b[2][2];
;   const char* pa = A + (wm + lr) * LDSROW + lh * 16;
;   const char* pb = B + (wn + lr) * LDSROW + lh * 16;
; #pragma unroll
;   for (int i = 0; i < 4; ++i) a[0][i] = *(const bf16x8*)(pa + 32 * i * LDSROW);
; #pragma unroll
;   for (int j = 0; j < 2; ++j) b[0][j] = *(const bf16x8*)(pb + 32 * j * LDSROW);
; #pragma unroll
;   for (int ks = 0; ks < 4; ++ks) {
;     const int cur = ks & 1, nx = cur ^ 1;
;     if (ks < 3) {
; #pragma unroll
;       for (int i = 0; i < 4; ++i) a[nx][i] = *(const bf16x8*)(pa + 32 * i * LDSROW + (ks + 1) * 32);
; #pragma unroll
;       for (int j = 0; j < 2; ++j) b[nx][j] = *(const bf16x8*)(pb + 32 * j * LDSROW + (ks + 1) * 32);
;     }
;     __builtin_amdgcn_sched_barrier(0);
; #pragma unroll
;     for (int i = 0; i < 4; ++i)
; #pragma unroll
;       for (int j = 0; j < 2; ++j)
;         acc[i][j] = __builtin_amdgcn_mfma_f32_32x32x16_bf16(a[cur][i], b[cur][j], acc[i][j], 0, 0, 0);
;     __builtin_amdgcn_sched_barrier(0);
;     if (ks == 1) {
;       al.store(tid, nxt, ra);
;       bl.store(tid, nxt + TILE_BYTES, rb);
;       __builtin_amdgcn_sched_barrier(0);
;       ra = al.load(tid, m0, knext);
;       rb = bl.load(tid, n0, knext);
;       __builtin_amdgcn_sched_barrier(0);
;     }
;   }
; }
.Lff2_d2:
	s_add_u32 s6, s6, 0x80
	s_addc_u32 s7, s7, 0
	s_add_u32 s0, s0, 0x80
	s_addc_u32 s1, s1, 0
	ds_read_b128 v[166:169], v146
	ds_read_b128 v[170:173], v146 offset:2048
	ds_read_b128 v[174:177], v146 offset:4096
	ds_read_b128 v[178:181], v146 offset:6144
	ds_read_b128 v[222:225], v144
	ds_read_b128 v[226:229], v144 offset:2048
	ds_read_b128 v[230:233], v144 offset:4096
	ds_read_b128 v[234:237], v144 offset:6144
	ds_read_b128 v[238:241], v144 offset:8192
	ds_read_b128 v[242:245], v144 offset:10240
	ds_read_b128 v[198:201], v144 offset:12288
	ds_read_b128 v[152:155], v144 offset:14336
	ds_read_b128 v[182:185], v147
	ds_read_b128 v[186:189], v147 offset:2048
	ds_read_b128 v[190:193], v147 offset:4096
	ds_read_b128 v[194:197], v147 offset:6144
	s_waitcnt lgkmcnt(8)
	v_mfma_f32_16x16x32_bf16 v[0:3], v[166:169], v[222:225], v[0:3]
	v_mfma_f32_16x16x32_bf16 v[4:7], v[170:173], v[222:225], v[4:7]
	v_mfma_f32_16x16x32_bf16 v[8:11], v[174:177], v[222:225], v[8:11]
	v_mfma_f32_16x16x32_bf16 v[12:15], v[178:181], v[222:225], v[12:15]
	v_mfma_f32_16x16x32_bf16 v[16:19], v[166:169], v[226:229], v[16:19]
	v_mfma_f32_16x16x32_bf16 v[20:23], v[170:173], v[226:229], v[20:23]
	v_mfma_f32_16x16x32_bf16 v[24:27], v[174:177], v[226:229], v[24:27]
	v_mfma_f32_16x16x32_bf16 v[28:31], v[178:181], v[226:229], v[28:31]
	v_mfma_f32_16x16x32_bf16 v[32:35], v[166:169], v[230:233], v[32:35]
	v_mfma_f32_16x16x32_bf16 v[36:39], v[170:173], v[230:233], v[36:39]
	v_mfma_f32_16x16x32_bf16 v[40:43], v[174:177], v[230:233], v[40:43]
	v_mfma_f32_16x16x32_bf16 v[44:47], v[178:181], v[230:233], v[44:47]
	v_mfma_f32_16x16x32_bf16 v[48:51], v[166:169], v[234:237], v[48:51]
	v_mfma_f32_16x16x32_bf16 v[52:55], v[170:173], v[234:237], v[52:55]
	v_mfma_f32_16x16x32_bf16 v[56:59], v[174:177], v[234:237], v[56:59]
	v_mfma_f32_16x16x32_bf16 v[60:63], v[178:181], v[234:237], v[60:63]
	ds_read_b128 v[222:225], v145
	ds_read_b128 v[226:229], v145 offset:2048
	ds_read_b128 v[230:233], v145 offset:4096
	ds_read_b128 v[234:237], v145 offset:6144
	s_waitcnt lgkmcnt(8)
	v_mfma_f32_16x16x32_bf16 v[64:67], v[166:169], v[238:241], v[64:67]
	v_mfma_f32_16x16x32_bf16 v[68:71], v[170:173], v[238:241], v[68:71]
	v_mfma_f32_16x16x32_bf16 v[72:75], v[174:177], v[238:241], v[72:75]
	v_mfma_f32_16x16x32_bf16 v[76:79], v[178:181], v[238:241], v[76:79]
	v_mfma_f32_16x16x32_bf16 v[80:83], v[166:169], v[242:245], v[80:83]
	v_mfma_f32_16x16x32_bf16 v[84:87], v[170:173], v[242:245], v[84:87]
	v_mfma_f32_16x16x32_bf16 v[88:91], v[174:177], v[242:245], v[88:91]
	v_mfma_f32_16x16x32_bf16 v[92:95], v[178:181], v[242:245], v[92:95]
	v_mfma_f32_16x16x32_bf16 v[96:99], v[166:169], v[198:201], v[96:99]
	v_mfma_f32_16x16x32_bf16 v[100:103], v[170:173], v[198:201], v[100:103]
	v_mfma_f32_16x16x32_bf16 v[104:107], v[174:177], v[198:201], v[104:107]
	v_mfma_f32_16x16x32_bf16 v[108:111], v[178:181], v[198:201], v[108:111]
	v_mfma_f32_16x16x32_bf16 v[112:115], v[166:169], v[152:155], v[112:115]
	v_mfma_f32_16x16x32_bf16 v[116:119], v[170:173], v[152:155], v[116:119]
	v_mfma_f32_16x16x32_bf16 v[120:123], v[174:177], v[152:155], v[120:123]
	v_mfma_f32_16x16x32_bf16 v[124:127], v[178:181], v[152:155], v[124:127]
	ds_read_b128 v[238:241], v145 offset:8192
	ds_read_b128 v[242:245], v145 offset:10240
	ds_read_b128 v[198:201], v145 offset:12288
	ds_read_b128 v[152:155], v145 offset:14336
	s_waitcnt lgkmcnt(4)
	v_mfma_f32_16x16x32_bf16 v[0:3], v[182:185], v[222:225], v[0:3]
	v_mfma_f32_16x16x32_bf16 v[4:7], v[186:189], v[222:225], v[4:7]
	v_mfma_f32_16x16x32_bf16 v[8:11], v[190:193], v[222:225], v[8:11]
	v_mfma_f32_16x16x32_bf16 v[12:15], v[194:197], v[222:225], v[12:15]
	v_mfma_f32_16x16x32_bf16 v[16:19], v[182:185], v[226:229], v[16:19]
	v_mfma_f32_16x16x32_bf16 v[20:23], v[186:189], v[226:229], v[20:23]
	v_mfma_f32_16x16x32_bf16 v[24:27], v[190:193], v[226:229], v[24:27]
	v_mfma_f32_16x16x32_bf16 v[28:31], v[194:197], v[226:229], v[28:31]
	v_mfma_f32_16x16x32_bf16 v[32:35], v[182:185], v[230:233], v[32:35]
	v_mfma_f32_16x16x32_bf16 v[36:39], v[186:189], v[230:233], v[36:39]
	v_mfma_f32_16x16x32_bf16 v[40:43], v[190:193], v[230:233], v[40:43]
	v_mfma_f32_16x16x32_bf16 v[44:47], v[194:197], v[230:233], v[44:47]
	v_mfma_f32_16x16x32_bf16 v[48:51], v[182:185], v[234:237], v[48:51]
	v_mfma_f32_16x16x32_bf16 v[52:55], v[186:189], v[234:237], v[52:55]
	v_mfma_f32_16x16x32_bf16 v[56:59], v[190:193], v[234:237], v[56:59]
	v_mfma_f32_16x16x32_bf16 v[60:63], v[194:197], v[234:237], v[60:63]
	s_waitcnt lgkmcnt(0)
	v_mfma_f32_16x16x32_bf16 v[64:67], v[182:185], v[238:241], v[64:67]
	v_mfma_f32_16x16x32_bf16 v[68:71], v[186:189], v[238:241], v[68:71]
	v_mfma_f32_16x16x32_bf16 v[72:75], v[190:193], v[238:241], v[72:75]
	v_mfma_f32_16x16x32_bf16 v[76:79], v[194:197], v[238:241], v[76:79]
	v_mfma_f32_16x16x32_bf16 v[80:83], v[182:185], v[242:245], v[80:83]
	v_mfma_f32_16x16x32_bf16 v[84:87], v[186:189], v[242:245], v[84:87]
	v_mfma_f32_16x16x32_bf16 v[88:91], v[190:193], v[242:245], v[88:91]
	v_mfma_f32_16x16x32_bf16 v[92:95], v[194:197], v[242:245], v[92:95]
	v_mfma_f32_16x16x32_bf16 v[96:99], v[182:185], v[198:201], v[96:99]
	v_mfma_f32_16x16x32_bf16 v[100:103], v[186:189], v[198:201], v[100:103]
	v_mfma_f32_16x16x32_bf16 v[104:107], v[190:193], v[198:201], v[104:107]
	v_mfma_f32_16x16x32_bf16 v[108:111], v[194:197], v[198:201], v[108:111]
	v_mfma_f32_16x16x32_bf16 v[112:115], v[182:185], v[152:155], v[112:115]
	v_mfma_f32_16x16x32_bf16 v[116:119], v[186:189], v[152:155], v[116:119]
	v_mfma_f32_16x16x32_bf16 v[120:123], v[190:193], v[152:155], v[120:123]
	v_mfma_f32_16x16x32_bf16 v[124:127], v[194:197], v[152:155], v[124:127]
	s_waitcnt vmcnt(0)
	s_barrier
	s_cmp_eq_u32 s5, 31
	s_cbranch_scc1 .Lff2_last
	s_cmp_lt_u32 s8, 0x4000
	s_cbranch_scc0 .Lff2_d3
	s_add_u32 m0, s8, 0x0
	s_nop 0
	global_load_lds_dwordx4 v128, s[6:7]
	global_load_lds_dwordx4 v129, s[6:7] offset:1024
	global_load_lds_dwordx4 v130, s[6:7] offset:2048
	global_load_lds_dwordx4 v131, s[6:7] offset:3072
	s_add_u32 m0, s8, 0x10000
	s_nop 0
	global_load_lds_dwordx4 v132, s[0:1]
	global_load_lds_dwordx4 v133, s[0:1] offset:1024
	global_load_lds_dwordx4 v134, s[0:1] offset:2048
	global_load_lds_dwordx4 v135, s[0:1] offset:3072
	s_add_u32 m0, s8, 0x4000
	s_nop 0
	global_load_lds_dwordx4 v136, s[6:7]
	global_load_lds_dwordx4 v137, s[6:7] offset:1024
	global_load_lds_dwordx4 v138, s[6:7] offset:2048
	global_load_lds_dwordx4 v139, s[6:7] offset:3072
	s_add_u32 m0, s8, 0x14000
	s_nop 0
	global_load_lds_dwordx4 v140, s[0:1]
	global_load_lds_dwordx4 v141, s[0:1] offset:1024
	global_load_lds_dwordx4 v142, s[0:1] offset:2048
	global_load_lds_dwordx4 v143, s[0:1] offset:3072
